# coalesced LDS-transposed epilogue stores in P1/P4/P5, batched P5 residual loads, P4 gate scratch loads hoisted, P1/P5 MFMA chains with double-buffered fragments and interleaved loads/ds_writes
# speedup vs baseline: 1.0691x; 1.0691x over previous
; DI unsigned pk2(float a, float b) { f2_t v = {a, b}; bf2_t r = __builtin_convertvector(v, bf2_t); return __builtin_bit_cast(unsigned, r); }
; DI void phase1(const Params& p, int l, char* lds) {
;     ...
;   for (int tile = blockIdx.x; tile < 128 * 51; tile += gridDim.x) {
;     const int grp = tile / (32 * 51), rem = tile % (32 * 51);
;     const int nt = rem >> 5, mt = grp * 32 + (rem & 31);
;     f32x16 acc[2][2];
;     zero_acc(acc);
;     gemm_mainloop(p.xn + (size_t)mt * 128 * 1024, 1024, WINT(l) + (size_t)nt * 128 * 1024, 1024, 1024, lds, acc);
;     ...
; #pragma unroll
;     for (int mi = 0; mi < 2; ++mi) {
;       const size_t row = (size_t)mt * 128 + wm * 64 + mi * 32 + r;
; #pragma unroll
;       for (int ni = 0; ni < 2; ++ni) {
; #pragma unroll
;         for (int a = 0; a < 4; ++a) {
;           const int col = nt * 128 + wn * 64 + ni * 32 + 8 * a + 4 * h;
;           uint2 o;
;           o.x = pk2(acc[mi][ni][4 * a], acc[mi][ni][4 * a + 1]);
;           o.y = pk2(acc[mi][ni][4 * a + 2], acc[mi][ni][4 * a + 3]);
;           *(uint2*)(p.z + row * ZS + col) = o;
;         }
;       }
;     }
.LBB0_216:
	s_or_b64 exec, exec, s[0:1]
	v_readlane_b32 s0, v252, 59
	v_readlane_b32 s1, v252, 60
	s_lshl_b32 s2, s78, 6
	v_mov_b32_e32 v0, v209
	s_and_b64 vcc, exec, s[0:1]
	s_waitcnt lgkmcnt(0)
	s_barrier
	s_cbranch_vccz .LBB0_233
	v_readlane_b32 s0, v253, 1
	v_readlane_b32 s1, v253, 2
	v_lshlrev_b32_e32 v66, 4, v209
	s_nop 4
	global_store_dwordx4 v66, v[168:171], s[0:1]
	v_add_u32_e32 v66, 0x1000, v66
	global_store_dwordx4 v66, v[172:175], s[0:1]
	v_add_u32_e32 v66, 0x1000, v66
	global_store_dwordx4 v66, v[176:179], s[0:1]
	v_add_u32_e32 v66, 0x1000, v66
	global_store_dwordx4 v66, v[180:183], s[0:1]
	v_add_u32_e32 v66, 0x1000, v66
	global_store_dwordx4 v66, v[184:187], s[0:1]
	v_add_u32_e32 v66, 0x1000, v66
	s_mul_i32 s18, s78, 0x660000
	v_readlane_b32 s80, v253, 12
	s_lshl_b64 s[0:1], s[18:19], 1
	v_readlane_b32 s90, v253, 22
	s_mov_b32 s3, s19
	v_readlane_b32 s91, v253, 23
	s_add_u32 s20, s90, s0
	s_addc_u32 s21, s91, s1
	s_lshl_b64 s[0:1], s[2:3], 2
	s_add_u32 s4, s72, s0
	s_addc_u32 s5, s73, s1
	s_add_u32 s6, s70, s0
	v_readlane_b32 s36, v251, 2
	s_addc_u32 s7, s71, s1
	v_readlane_b32 s46, v251, 12
	v_readlane_b32 s47, v251, 13
	s_add_u32 s8, s46, s0
	v_readlane_b32 s44, v251, 10
	s_addc_u32 s9, s47, s1
	s_add_u32 s10, s44, s0
	v_lshlrev_b32_e32 v2, 2, v0
	s_movk_i32 s0, 0x80
	v_bfrev_b32_e32 v3, 0.5
	v_bitop3_b32 v154, v2, s0, v3 bitop3:0x6c
	v_lshrrev_b32_e32 v2, 3, v0
	v_readlane_b32 s45, v251, 11
	v_and_b32_e32 v130, 4, v2
	v_ashrrev_i32_e32 v2, 1, v0
	s_addc_u32 s11, s45, s1
	v_and_b32_e32 v2, 0xffffffc0, v2
	v_readlane_b32 s0, v253, 36
	s_mov_b32 s25, s19
	v_readlane_b32 s88, v253, 20
	v_readlane_b32 s89, v253, 21
	v_and_b32_e32 v131, 64, v0
	v_ashrrev_i32_e32 v133, 31, v2
	v_and_or_b32 v132, v0, 31, v2
	s_mov_b32 s3, s0
	v_readlane_b32 s81, v253, 13
	v_readlane_b32 s82, v253, 14
	v_readlane_b32 s83, v253, 15
	v_readlane_b32 s84, v253, 16
	v_readlane_b32 s85, v253, 17
	v_readlane_b32 s86, v253, 18
	v_readlane_b32 s87, v253, 19
	v_readlane_b32 s92, v253, 24
	v_readlane_b32 s93, v253, 25
	v_readlane_b32 s94, v253, 26
	v_readlane_b32 s95, v253, 27
	v_readlane_b32 s37, v251, 3
	v_readlane_b32 s38, v251, 4
	v_readlane_b32 s39, v251, 5
	v_readlane_b32 s40, v251, 6
	v_readlane_b32 s41, v251, 7
	v_readlane_b32 s42, v251, 8
	v_readlane_b32 s43, v251, 9
	v_readlane_b32 s48, v251, 14
	v_readlane_b32 s49, v251, 15
	v_readlane_b32 s50, v251, 16
	v_readlane_b32 s51, v251, 17
	v_readlane_b32 s1, v253, 37
	s_branch .LBB0_219
.LBB0_218:
	s_or_b64 exec, exec, s[14:15]
	s_lshl_b32 s0, s12, 7
	v_readlane_b32 s80, v253, 12
	v_readlane_b32 s86, v253, 18
	v_readlane_b32 s87, v253, 19
	v_readlane_b32 s88, v253, 20
	v_readlane_b32 s89, v253, 21
	v_readlane_b32 s81, v253, 13
	v_readlane_b32 s82, v253, 14
	v_readlane_b32 s83, v253, 15
	v_readlane_b32 s84, v253, 16
	v_readlane_b32 s85, v253, 17
	v_readlane_b32 s90, v253, 22
	v_readlane_b32 s91, v253, 23
	v_readlane_b32 s92, v253, 24
	v_readlane_b32 s93, v253, 25
	v_readlane_b32 s94, v253, 26
	v_readlane_b32 s95, v253, 27
	v_and_b32_e32 v66, 63, v209
	v_lshrrev_b32_e32 v67, 3, v66
	v_and_b32_e32 v68, 7, v66
	v_lshrrev_b32_e32 v69, 7, v209
	v_lshl_add_u32 v69, v69, 6, v67
	v_add_u32_e32 v70, s0, v69
	v_mul_lo_u32 v70, v70, s75
	v_lshlrev_b32_e32 v71, 1, v83
	v_lshl_add_u32 v71, v68, 4, v71
	v_add_u32_e32 v70, v70, v71
	v_lshrrev_b32_e32 v72, 6, v209
	v_mul_u32_u24_e32 v73, 0x2400, v72
	v_lshrrev_b32_e32 v74, 1, v72
	v_mul_u32_u24_e32 v74, 0x4800, v74
	v_add_u32_e32 v73, v73, v74
	v_add_u32_e32 v73, 0x4800, v73
	v_and_b32_e32 v75, 31, v66
	v_lshrrev_b32_e32 v76, 5, v66
	v_mul_u32_u24_e32 v75, 0x90, v75
	v_lshl_add_u32 v75, v76, 3, v75
	v_add_u32_e32 v75, v75, v73
	v_mul_u32_u24_e32 v77, 0x90, v67
	v_lshl_add_u32 v77, v68, 4, v77
	v_add_u32_e32 v77, v77, v73
	v_cvt_pk_f16_f32 v50, v50, v51
	v_cvt_pk_f16_f32 v51, v52, v53
	v_cvt_pk_f16_f32 v52, v54, v55
	v_cvt_pk_f16_f32 v53, v56, v57
	v_cvt_pk_f16_f32 v54, v58, v59
	v_cvt_pk_f16_f32 v55, v60, v61
	v_cvt_pk_f16_f32 v56, v62, v63
	v_cvt_pk_f16_f32 v57, v64, v65
	v_cvt_pk_f16_f32 v34, v34, v35
	v_cvt_pk_f16_f32 v35, v36, v37
	v_cvt_pk_f16_f32 v36, v38, v39
	v_cvt_pk_f16_f32 v37, v40, v41
	v_cvt_pk_f16_f32 v38, v42, v43
	v_cvt_pk_f16_f32 v39, v44, v45
	v_cvt_pk_f16_f32 v40, v46, v47
	v_cvt_pk_f16_f32 v41, v48, v49
	v_cvt_pk_f16_f32 v18, v18, v19
	v_cvt_pk_f16_f32 v19, v20, v21
	v_cvt_pk_f16_f32 v20, v22, v23
	v_cvt_pk_f16_f32 v21, v24, v25
	v_cvt_pk_f16_f32 v22, v26, v27
	v_cvt_pk_f16_f32 v23, v28, v29
	v_cvt_pk_f16_f32 v24, v30, v31
	v_cvt_pk_f16_f32 v25, v32, v33
	v_cvt_pk_f16_f32 v2, v2, v3
	v_cvt_pk_f16_f32 v3, v4, v5
	v_cvt_pk_f16_f32 v4, v6, v7
	v_cvt_pk_f16_f32 v5, v8, v9
	v_cvt_pk_f16_f32 v6, v10, v11
	v_cvt_pk_f16_f32 v7, v12, v13
	v_cvt_pk_f16_f32 v8, v14, v15
	v_cvt_pk_f16_f32 v9, v16, v17
	ds_write_b64 v75, v[50:51]
	ds_write_b64 v75, v[52:53] offset:16
	ds_write_b64 v75, v[54:55] offset:32
	ds_write_b64 v75, v[56:57] offset:48
	ds_write_b64 v75, v[34:35] offset:64
	ds_write_b64 v75, v[36:37] offset:80
	ds_write_b64 v75, v[38:39] offset:96
	ds_write_b64 v75, v[40:41] offset:112
	ds_write_b64 v75, v[18:19] offset:4608
	ds_write_b64 v75, v[20:21] offset:4624
	ds_write_b64 v75, v[22:23] offset:4640
	ds_write_b64 v75, v[24:25] offset:4656
	ds_write_b64 v75, v[2:3] offset:4672
	ds_write_b64 v75, v[4:5] offset:4688
	ds_write_b64 v75, v[6:7] offset:4704
	ds_write_b64 v75, v[8:9] offset:4720
	s_waitcnt lgkmcnt(0)
	ds_read_b128 v[84:87], v77
	ds_read_b128 v[88:91], v77 offset:1152
	ds_read_b128 v[92:95], v77 offset:2304
	ds_read_b128 v[96:99], v77 offset:3456
	ds_read_b128 v[100:103], v77 offset:4608
	ds_read_b128 v[104:107], v77 offset:5760
	ds_read_b128 v[108:111], v77 offset:6912
	ds_read_b128 v[112:115], v77 offset:8064
	s_add_i32 s3, s3, s30
	s_waitcnt lgkmcnt(7)
	global_store_dwordx4 v70, v[84:87], s[86:87]
	v_add_u32_e32 v70, 0x19800, v70
	s_waitcnt lgkmcnt(6)
	global_store_dwordx4 v70, v[88:91], s[86:87]
	v_add_u32_e32 v70, 0x19800, v70
	s_waitcnt lgkmcnt(5)
	global_store_dwordx4 v70, v[92:95], s[86:87]
	v_add_u32_e32 v70, 0x19800, v70
	s_waitcnt lgkmcnt(4)
	global_store_dwordx4 v70, v[96:99], s[86:87]
	v_add_u32_e32 v70, 0x19800, v70
	s_waitcnt lgkmcnt(3)
	global_store_dwordx4 v70, v[100:103], s[86:87]
	v_add_u32_e32 v70, 0x19800, v70
	s_waitcnt lgkmcnt(2)
	global_store_dwordx4 v70, v[104:107], s[86:87]
	v_add_u32_e32 v70, 0x19800, v70
	s_waitcnt lgkmcnt(1)
	global_store_dwordx4 v70, v[108:111], s[86:87]
	v_add_u32_e32 v70, 0x19800, v70
	s_waitcnt lgkmcnt(0)
	global_store_dwordx4 v70, v[112:115], s[86:87]
	s_cmpk_lt_i32 s3, 0x1980
	s_cbranch_scc0 .LBB0_232
; DI int TID() { int t = threadIdx.x; asm volatile("" : "+v"(t)); return t; }
; #define GEMM_GLOAD(P, kt_) { GEMM_GL1(P, 0, kt_) GEMM_GL1(P, 1, kt_) GEMM_GL1(P, 2, kt_) GEMM_GL1(P, 3, kt_) }
; #define GEMM_LSTORE(P, buf_) { GEMM_LS1(P, 0, buf_) GEMM_LS1(P, 1, buf_) GEMM_LS1(P, 2, buf_) GEMM_LS1(P, 3, buf_) }
; template <bool DEEP>
; DI void gemm_mainloop_t(const u16* __restrict__ Ag, int lda, const u16* __restrict__ Bg, int ldb, int K, char* ldsraw,
;                         f32x16 (&acc)[2][2], int akstep) {
;   const int tid = TID(), lane = tid & 63, w = tid >> 6, wm = w >> 1, wn = w & 1, r = lane & 31, h = lane >> 5;
;   u16* As = (u16*)ldsraw;
;   u16* Bs = As + 2 * 128 * LDT;
;   uint4 xa0, xa1, xa2, xa3, xb0, xb1, xb2, xb3;
;   const int nk = K >> 6;
;   const int row0 = tid >> 3, cc = tid & 7;
;   if (DEEP) {
;     uint4 ya0, ya1, ya2, ya3, yb0, yb1, yb2, yb3;
;     GEMM_GLOAD(x, 0);
;     GEMM_GLOAD(y, 1);
;     GEMM_LSTORE(x, 0);
;     __syncthreads();
;     for (int kt = 0; kt < nk; kt += 2) {
;       if (kt + 2 < nk) GEMM_GLOAD(x, kt + 2);
;       GEMM_COMPUTE(0);
;       GEMM_LSTORE(y, 1);
;       __syncthreads();
;       if (kt + 3 < nk) GEMM_GLOAD(y, kt + 3);
;       GEMM_COMPUTE(1);
; DI void phase1(const Params& p, int l, char* lds) {
;     ...
;   for (int tile = blockIdx.x; tile < 128 * 51; tile += gridDim.x) {
;     const int grp = tile / (32 * 51), rem = tile % (32 * 51);
;     const int nt = rem >> 5, mt = grp * 32 + (rem & 31);
;     f32x16 acc[2][2];
;     zero_acc(acc);
;     gemm_mainloop(p.xn + (size_t)mt * 128 * 1024, 1024, WINT(l) + (size_t)nt * 128 * 1024, 1024, 1024, lds, acc);
.LBB0_219:
	s_mul_hi_i32 s0, s3, 0xa0a0a0a1
	s_add_i32 s0, s0, s3
	s_lshr_b32 s1, s0, 31
	s_ashr_i32 s0, s0, 10
	s_add_i32 s1, s0, s1
	s_mul_i32 s0, s1, 0xfffff9a0
	s_add_i32 s18, s3, s0
	s_lshl_b32 s1, s1, 5
	s_and_b32 s12, s18, 31
	s_or_b32 s12, s1, s12
	s_ashr_i32 s13, s12, 31
	s_ashr_i32 s0, s18, 5
	s_lshl_b64 s[14:15], s[12:13], 18
	s_waitcnt vmcnt(31)
	v_mov_b32_e32 v36, v209
	s_add_u32 s14, s88, s14
	s_addc_u32 s15, s89, s15
	v_ashrrev_i32_e32 v34, 3, v36
	s_ashr_i32 s1, s0, 31
	v_ashrrev_i32_e32 v35, 31, v34
	s_lshl_b64 s[16:17], s[0:1], 18
	v_lshlrev_b64 v[26:27], 11, v[34:35]
	s_add_u32 s16, s20, s16
	v_lshlrev_b32_e32 v0, 4, v36
	v_lshl_add_u64 v[14:15], v[26:27], 0, s[52:53]
	s_addc_u32 s17, s21, s17
	v_lshl_add_u64 v[2:3], s[14:15], 0, v[26:27]
	v_and_b32_e32 v0, 0x70, v0
	v_lshl_add_u64 v[10:11], s[14:15], 0, v[14:15]
	s_mov_b64 s[22:23], 0x20000
	v_lshl_add_u64 v[138:139], v[2:3], 0, v[0:1]
	v_lshl_add_u64 v[6:7], s[16:17], 0, v[26:27]
	v_lshl_add_u64 v[142:143], v[10:11], 0, v[0:1]
	v_lshl_add_u64 v[14:15], s[16:17], 0, v[14:15]
	v_lshl_add_u64 v[22:23], v[26:27], 0, s[22:23]
	global_load_dwordx4 v[2:5], v[138:139], off
	v_lshl_add_u64 v[140:141], v[6:7], 0, v[0:1]
	global_load_dwordx4 v[10:13], v[142:143], off
	v_lshl_add_u64 v[144:145], v[14:15], 0, v[0:1]
	v_lshl_add_u64 v[18:19], s[14:15], 0, v[22:23]
	s_mov_b64 s[22:23], 0x30000
	global_load_dwordx4 v[6:9], v[140:141], off
	global_load_dwordx4 v[14:17], v[144:145], off
	v_lshl_add_u64 v[146:147], v[18:19], 0, v[0:1]
	v_lshl_add_u64 v[22:23], s[16:17], 0, v[22:23]
	v_lshl_add_u64 v[30:31], v[26:27], 0, s[22:23]
	global_load_dwordx4 v[18:21], v[146:147], off
	v_lshl_add_u64 v[148:149], v[22:23], 0, v[0:1]
	v_lshl_add_u64 v[26:27], s[14:15], 0, v[30:31]
	global_load_dwordx4 v[22:25], v[148:149], off
	v_lshl_add_u64 v[150:151], v[26:27], 0, v[0:1]
	global_load_dwordx4 v[26:29], v[150:151], off
	v_lshl_add_u64 v[30:31], s[16:17], 0, v[30:31]
	v_lshl_add_u64 v[152:153], v[30:31], 0, v[0:1]
	global_load_dwordx4 v[30:33], v[152:153], off
	global_load_dwordx4 v[98:101], v[138:139], off offset:128
	global_load_dwordx4 v[102:105], v[140:141], off offset:128
	global_load_dwordx4 v[106:109], v[142:143], off offset:128
	global_load_dwordx4 v[110:113], v[144:145], off offset:128
	global_load_dwordx4 v[114:117], v[146:147], off offset:128
	global_load_dwordx4 v[118:121], v[148:149], off offset:128
	global_load_dwordx4 v[122:125], v[150:151], off offset:128
	global_load_dwordx4 v[126:129], v[152:153], off offset:128
	v_mad_u64_u32 v[136:137], s[14:15], v34, s76, v[0:1]
	v_and_b32_e32 v0, 31, v36
	v_add_u32_e32 v137, 0x1200, v136
	s_waitcnt vmcnt(15)
	ds_write_b128 v136, v[2:5]
	s_waitcnt vmcnt(13)
	ds_write_b128 v136, v[6:9] offset:36864
	ds_write_b128 v136, v[10:13] offset:4608
	s_waitcnt vmcnt(12)
	ds_write_b128 v136, v[14:17] offset:41472
	s_waitcnt vmcnt(11)
	ds_write_b128 v136, v[18:21] offset:9216
	s_waitcnt vmcnt(10)
	ds_write_b128 v136, v[22:25] offset:46080
	s_waitcnt vmcnt(9)
	ds_write_b128 v136, v[26:29] offset:13824
	s_waitcnt vmcnt(8)
	ds_write_b128 v136, v[30:33] offset:50688
	s_waitcnt lgkmcnt(0)
	s_barrier
	v_lshrrev_b32_e32 v2, 1, v36
	v_and_or_b32 v3, v2, s74, v0
	v_and_b32_e32 v0, 16, v2
	v_and_b32_e32 v2, 0x5f, v36
	v_mad_u64_u32 v[134:135], s[14:15], v3, s76, v[0:1]
	v_mul_u32_u24_e32 v2, 0x48, v2
	v_lshl_add_u32 v0, v2, 1, v0
	s_setprio 1
	ds_read_b128 v[156:159], v0 offset:36864
	ds_read_b128 v[160:163], v134
	ds_read_b128 v[164:167], v0 offset:41472
	ds_read_b128 v[168:171], v134 offset:4608
	ds_read_b128 v[172:175], v0 offset:36896
	ds_read_b128 v[176:179], v134 offset:32
	ds_read_b128 v[180:183], v0 offset:41504
	ds_read_b128 v[184:187], v134 offset:4640
	s_waitcnt lgkmcnt(6)
	v_mfma_f32_32x32x16_f16 v[50:65], v[156:159], v[160:163], 0
	global_load_dwordx4 v[66:69], v[138:139], off offset:256
	s_waitcnt lgkmcnt(5)
	v_mfma_f32_32x32x16_f16 v[34:49], v[164:167], v[160:163], 0
	s_waitcnt vmcnt(8)
	ds_write_b128 v136, v[98:101] offset:18432
	s_waitcnt lgkmcnt(5)
	v_mfma_f32_32x32x16_f16 v[18:33], v[156:159], v[168:171], 0
	global_load_dwordx4 v[70:73], v[140:141], off offset:256
	v_mfma_f32_32x32x16_f16 v[2:17], v[164:167], v[168:171], 0
	s_waitcnt vmcnt(8)
	ds_write_b128 v136, v[102:105] offset:55296
	ds_read_b128 v[156:159], v0 offset:36928
	ds_read_b128 v[160:163], v134 offset:64
	ds_read_b128 v[164:167], v0 offset:41536
	ds_read_b128 v[168:171], v134 offset:4672
	s_waitcnt lgkmcnt(8)
	v_mfma_f32_32x32x16_f16 v[50:65], v[172:175], v[176:179], v[50:65]
	global_load_dwordx4 v[74:77], v[142:143], off offset:256
	s_waitcnt lgkmcnt(7)
	v_mfma_f32_32x32x16_f16 v[34:49], v[180:183], v[176:179], v[34:49]
	s_waitcnt vmcnt(8)
	ds_write_b128 v136, v[106:109] offset:23040
	s_waitcnt lgkmcnt(7)
	v_mfma_f32_32x32x16_f16 v[18:33], v[172:175], v[184:187], v[18:33]
	global_load_dwordx4 v[78:81], v[144:145], off offset:256
	v_mfma_f32_32x32x16_f16 v[2:17], v[180:183], v[184:187], v[2:17]
	s_waitcnt vmcnt(8)
	ds_write_b128 v136, v[110:113] offset:59904
	ds_read_b128 v[172:175], v0 offset:36960
	ds_read_b128 v[176:179], v134 offset:96
	ds_read_b128 v[180:183], v0 offset:41568
	ds_read_b128 v[184:187], v134 offset:4704
	s_waitcnt lgkmcnt(8)
	v_mfma_f32_32x32x16_f16 v[50:65], v[156:159], v[160:163], v[50:65]
	global_load_dwordx4 v[82:85], v[146:147], off offset:256
	s_waitcnt lgkmcnt(7)
	v_mfma_f32_32x32x16_f16 v[34:49], v[164:167], v[160:163], v[34:49]
	s_waitcnt vmcnt(8)
	ds_write_b128 v136, v[114:117] offset:27648
	s_waitcnt lgkmcnt(7)
	v_mfma_f32_32x32x16_f16 v[18:33], v[156:159], v[168:171], v[18:33]
	global_load_dwordx4 v[86:89], v[148:149], off offset:256
	v_mfma_f32_32x32x16_f16 v[2:17], v[164:167], v[168:171], v[2:17]
	s_waitcnt vmcnt(8)
	ds_write_b128 v136, v[118:121] offset:64512
	s_waitcnt lgkmcnt(4)
	v_mfma_f32_32x32x16_f16 v[50:65], v[172:175], v[176:179], v[50:65]
	global_load_dwordx4 v[90:93], v[150:151], off offset:256
	s_waitcnt lgkmcnt(3)
	v_mfma_f32_32x32x16_f16 v[34:49], v[180:183], v[176:179], v[34:49]
	s_waitcnt vmcnt(8)
	ds_write_b128 v136, v[122:125] offset:32256
	s_waitcnt lgkmcnt(3)
	v_mfma_f32_32x32x16_f16 v[18:33], v[172:175], v[184:187], v[18:33]
	global_load_dwordx4 v[94:97], v[152:153], off offset:256
	v_mfma_f32_32x32x16_f16 v[2:17], v[180:183], v[184:187], v[2:17]
	s_waitcnt vmcnt(8)
	ds_write_b128 v137, v[126:129] offset:64512
	s_setprio 0
	s_waitcnt lgkmcnt(0)
	s_barrier
; #define GEMM_GLOAD(P, kt_) { GEMM_GL1(P, 0, kt_) GEMM_GL1(P, 1, kt_) GEMM_GL1(P, 2, kt_) GEMM_GL1(P, 3, kt_) }
; #define GEMM_LSTORE(P, buf_) { GEMM_LS1(P, 0, buf_) GEMM_LS1(P, 1, buf_) GEMM_LS1(P, 2, buf_) GEMM_LS1(P, 3, buf_) }
; template <bool DEEP>
; DI void gemm_mainloop_t(const u16* __restrict__ Ag, int lda, const u16* __restrict__ Bg, int ldb, int K, char* ldsraw,
;                         f32x16 (&acc)[2][2], int akstep) {
;     ...
;     for (int kt = 0; kt < nk; kt += 2) {
;       if (kt + 2 < nk) GEMM_GLOAD(x, kt + 2);
;       GEMM_COMPUTE(0);
;       GEMM_LSTORE(y, 1);
;       __syncthreads();
;       if (kt + 3 < nk) GEMM_GLOAD(y, kt + 3);
;       GEMM_COMPUTE(1);
;       if (kt + 2 < nk) GEMM_LSTORE(x, 0);
	s_setprio 1
	ds_read_b128 v[156:159], v0 offset:55296
	ds_read_b128 v[160:163], v134 offset:18432
	ds_read_b128 v[164:167], v0 offset:59904
	ds_read_b128 v[168:171], v134 offset:23040
	ds_read_b128 v[172:175], v0 offset:55328
	ds_read_b128 v[176:179], v134 offset:18464
	ds_read_b128 v[180:183], v0 offset:59936
	ds_read_b128 v[184:187], v134 offset:23072
	s_waitcnt lgkmcnt(6)
	v_mfma_f32_32x32x16_f16 v[50:65], v[156:159], v[160:163], v[50:65]
	global_load_dwordx4 v[98:101], v[138:139], off offset:384
	s_waitcnt lgkmcnt(5)
	v_mfma_f32_32x32x16_f16 v[34:49], v[164:167], v[160:163], v[34:49]
	s_waitcnt vmcnt(8)
	ds_write_b128 v136, v[66:69]
	s_waitcnt lgkmcnt(5)
	v_mfma_f32_32x32x16_f16 v[18:33], v[156:159], v[168:171], v[18:33]
	global_load_dwordx4 v[102:105], v[140:141], off offset:384
	v_mfma_f32_32x32x16_f16 v[2:17], v[164:167], v[168:171], v[2:17]
	s_waitcnt vmcnt(8)
	ds_write_b128 v136, v[70:73] offset:36864
	ds_read_b128 v[156:159], v0 offset:55360
	ds_read_b128 v[160:163], v134 offset:18496
	ds_read_b128 v[164:167], v0 offset:59968
	ds_read_b128 v[168:171], v134 offset:23104
	s_waitcnt lgkmcnt(8)
	v_mfma_f32_32x32x16_f16 v[50:65], v[172:175], v[176:179], v[50:65]
	global_load_dwordx4 v[106:109], v[142:143], off offset:384
	s_waitcnt lgkmcnt(7)
	v_mfma_f32_32x32x16_f16 v[34:49], v[180:183], v[176:179], v[34:49]
	s_waitcnt vmcnt(8)
	ds_write_b128 v136, v[74:77] offset:4608
	s_waitcnt lgkmcnt(7)
	v_mfma_f32_32x32x16_f16 v[18:33], v[172:175], v[184:187], v[18:33]
	global_load_dwordx4 v[110:113], v[144:145], off offset:384
	v_mfma_f32_32x32x16_f16 v[2:17], v[180:183], v[184:187], v[2:17]
	s_waitcnt vmcnt(8)
	ds_write_b128 v136, v[78:81] offset:41472
	ds_read_b128 v[172:175], v0 offset:55392
	ds_read_b128 v[176:179], v134 offset:18528
	ds_read_b128 v[180:183], v0 offset:60000
	ds_read_b128 v[184:187], v134 offset:23136
	s_waitcnt lgkmcnt(8)
	v_mfma_f32_32x32x16_f16 v[50:65], v[156:159], v[160:163], v[50:65]
	global_load_dwordx4 v[114:117], v[146:147], off offset:384
	s_waitcnt lgkmcnt(7)
	v_mfma_f32_32x32x16_f16 v[34:49], v[164:167], v[160:163], v[34:49]
	s_waitcnt vmcnt(8)
	ds_write_b128 v136, v[82:85] offset:9216
	s_waitcnt lgkmcnt(7)
	v_mfma_f32_32x32x16_f16 v[18:33], v[156:159], v[168:171], v[18:33]
	global_load_dwordx4 v[118:121], v[148:149], off offset:384
	v_mfma_f32_32x32x16_f16 v[2:17], v[164:167], v[168:171], v[2:17]
	s_waitcnt vmcnt(8)
	ds_write_b128 v136, v[86:89] offset:46080
	s_waitcnt lgkmcnt(4)
	v_mfma_f32_32x32x16_f16 v[50:65], v[172:175], v[176:179], v[50:65]
	global_load_dwordx4 v[122:125], v[150:151], off offset:384
	s_waitcnt lgkmcnt(3)
	v_mfma_f32_32x32x16_f16 v[34:49], v[180:183], v[176:179], v[34:49]
	s_waitcnt vmcnt(8)
	ds_write_b128 v136, v[90:93] offset:13824
	s_waitcnt lgkmcnt(3)
	v_mfma_f32_32x32x16_f16 v[18:33], v[172:175], v[184:187], v[18:33]
	global_load_dwordx4 v[126:129], v[152:153], off offset:384
	v_mfma_f32_32x32x16_f16 v[2:17], v[180:183], v[184:187], v[2:17]
	s_waitcnt vmcnt(8)
	ds_write_b128 v136, v[94:97] offset:50688
	s_setprio 0
	s_waitcnt lgkmcnt(0)
	s_barrier
	s_setprio 1
	ds_read_b128 v[156:159], v0 offset:36864
	ds_read_b128 v[160:163], v134
	ds_read_b128 v[164:167], v0 offset:41472
	ds_read_b128 v[168:171], v134 offset:4608
	ds_read_b128 v[172:175], v0 offset:36896
	ds_read_b128 v[176:179], v134 offset:32
	ds_read_b128 v[180:183], v0 offset:41504
	ds_read_b128 v[184:187], v134 offset:4640
	s_waitcnt lgkmcnt(6)
	v_mfma_f32_32x32x16_f16 v[50:65], v[156:159], v[160:163], v[50:65]
	global_load_dwordx4 v[66:69], v[138:139], off offset:512
	s_waitcnt lgkmcnt(5)
	v_mfma_f32_32x32x16_f16 v[34:49], v[164:167], v[160:163], v[34:49]
	s_waitcnt vmcnt(8)
	ds_write_b128 v136, v[98:101] offset:18432
	s_waitcnt lgkmcnt(5)
	v_mfma_f32_32x32x16_f16 v[18:33], v[156:159], v[168:171], v[18:33]
	global_load_dwordx4 v[70:73], v[140:141], off offset:512
	v_mfma_f32_32x32x16_f16 v[2:17], v[164:167], v[168:171], v[2:17]
	s_waitcnt vmcnt(8)
	ds_write_b128 v136, v[102:105] offset:55296
	ds_read_b128 v[156:159], v0 offset:36928
	ds_read_b128 v[160:163], v134 offset:64
	ds_read_b128 v[164:167], v0 offset:41536
	ds_read_b128 v[168:171], v134 offset:4672
	s_waitcnt lgkmcnt(8)
	v_mfma_f32_32x32x16_f16 v[50:65], v[172:175], v[176:179], v[50:65]
	global_load_dwordx4 v[74:77], v[142:143], off offset:512
	s_waitcnt lgkmcnt(7)
	v_mfma_f32_32x32x16_f16 v[34:49], v[180:183], v[176:179], v[34:49]
	s_waitcnt vmcnt(8)
	ds_write_b128 v136, v[106:109] offset:23040
	s_waitcnt lgkmcnt(7)
	v_mfma_f32_32x32x16_f16 v[18:33], v[172:175], v[184:187], v[18:33]
	global_load_dwordx4 v[78:81], v[144:145], off offset:512
	v_mfma_f32_32x32x16_f16 v[2:17], v[180:183], v[184:187], v[2:17]
	s_waitcnt vmcnt(8)
	ds_write_b128 v136, v[110:113] offset:59904
	ds_read_b128 v[172:175], v0 offset:36960
	ds_read_b128 v[176:179], v134 offset:96
	ds_read_b128 v[180:183], v0 offset:41568
	ds_read_b128 v[184:187], v134 offset:4704
	s_waitcnt lgkmcnt(8)
	v_mfma_f32_32x32x16_f16 v[50:65], v[156:159], v[160:163], v[50:65]
	global_load_dwordx4 v[82:85], v[146:147], off offset:512
	s_waitcnt lgkmcnt(7)
	v_mfma_f32_32x32x16_f16 v[34:49], v[164:167], v[160:163], v[34:49]
	s_waitcnt vmcnt(8)
	ds_write_b128 v136, v[114:117] offset:27648
	s_waitcnt lgkmcnt(7)
	v_mfma_f32_32x32x16_f16 v[18:33], v[156:159], v[168:171], v[18:33]
	global_load_dwordx4 v[86:89], v[148:149], off offset:512
	v_mfma_f32_32x32x16_f16 v[2:17], v[164:167], v[168:171], v[2:17]
	s_waitcnt vmcnt(8)
	ds_write_b128 v136, v[118:121] offset:64512
	s_waitcnt lgkmcnt(4)
	v_mfma_f32_32x32x16_f16 v[50:65], v[172:175], v[176:179], v[50:65]
	global_load_dwordx4 v[90:93], v[150:151], off offset:512
	s_waitcnt lgkmcnt(3)
	v_mfma_f32_32x32x16_f16 v[34:49], v[180:183], v[176:179], v[34:49]
	s_waitcnt vmcnt(8)
	ds_write_b128 v136, v[122:125] offset:32256
	s_waitcnt lgkmcnt(3)
	v_mfma_f32_32x32x16_f16 v[18:33], v[172:175], v[184:187], v[18:33]
	global_load_dwordx4 v[94:97], v[152:153], off offset:512
	v_mfma_f32_32x32x16_f16 v[2:17], v[180:183], v[184:187], v[2:17]
	s_waitcnt vmcnt(8)
	ds_write_b128 v137, v[126:129] offset:64512
	s_setprio 0
	s_waitcnt lgkmcnt(0)
	s_barrier
; #define GEMM_GLOAD(P, kt_) { GEMM_GL1(P, 0, kt_) GEMM_GL1(P, 1, kt_) GEMM_GL1(P, 2, kt_) GEMM_GL1(P, 3, kt_) }
; #define GEMM_LSTORE(P, buf_) { GEMM_LS1(P, 0, buf_) GEMM_LS1(P, 1, buf_) GEMM_LS1(P, 2, buf_) GEMM_LS1(P, 3, buf_) }
; template <bool DEEP>
; DI void gemm_mainloop_t(const u16* __restrict__ Ag, int lda, const u16* __restrict__ Bg, int ldb, int K, char* ldsraw,
;                         f32x16 (&acc)[2][2], int akstep) {
;     ...
;     for (int kt = 0; kt < nk; kt += 2) {
;       if (kt + 2 < nk) GEMM_GLOAD(x, kt + 2);
;       GEMM_COMPUTE(0);
;       GEMM_LSTORE(y, 1);
;       __syncthreads();
;       if (kt + 3 < nk) GEMM_GLOAD(y, kt + 3);
;       GEMM_COMPUTE(1);
;       if (kt + 2 < nk) GEMM_LSTORE(x, 0);
	s_setprio 1
	ds_read_b128 v[156:159], v0 offset:55296
	ds_read_b128 v[160:163], v134 offset:18432
	ds_read_b128 v[164:167], v0 offset:59904
	ds_read_b128 v[168:171], v134 offset:23040
	ds_read_b128 v[172:175], v0 offset:55328
	ds_read_b128 v[176:179], v134 offset:18464
	ds_read_b128 v[180:183], v0 offset:59936
	ds_read_b128 v[184:187], v134 offset:23072
	s_waitcnt lgkmcnt(6)
	v_mfma_f32_32x32x16_f16 v[50:65], v[156:159], v[160:163], v[50:65]
	global_load_dwordx4 v[98:101], v[138:139], off offset:640
	s_waitcnt lgkmcnt(5)
	v_mfma_f32_32x32x16_f16 v[34:49], v[164:167], v[160:163], v[34:49]
	s_waitcnt vmcnt(8)
	ds_write_b128 v136, v[66:69]
	s_waitcnt lgkmcnt(5)
	v_mfma_f32_32x32x16_f16 v[18:33], v[156:159], v[168:171], v[18:33]
	global_load_dwordx4 v[102:105], v[140:141], off offset:640
	v_mfma_f32_32x32x16_f16 v[2:17], v[164:167], v[168:171], v[2:17]
	s_waitcnt vmcnt(8)
	ds_write_b128 v136, v[70:73] offset:36864
	ds_read_b128 v[156:159], v0 offset:55360
	ds_read_b128 v[160:163], v134 offset:18496
	ds_read_b128 v[164:167], v0 offset:59968
	ds_read_b128 v[168:171], v134 offset:23104
	s_waitcnt lgkmcnt(8)
	v_mfma_f32_32x32x16_f16 v[50:65], v[172:175], v[176:179], v[50:65]
	global_load_dwordx4 v[106:109], v[142:143], off offset:640
	s_waitcnt lgkmcnt(7)
	v_mfma_f32_32x32x16_f16 v[34:49], v[180:183], v[176:179], v[34:49]
	s_waitcnt vmcnt(8)
	ds_write_b128 v136, v[74:77] offset:4608
	s_waitcnt lgkmcnt(7)
	v_mfma_f32_32x32x16_f16 v[18:33], v[172:175], v[184:187], v[18:33]
	global_load_dwordx4 v[110:113], v[144:145], off offset:640
	v_mfma_f32_32x32x16_f16 v[2:17], v[180:183], v[184:187], v[2:17]
	s_waitcnt vmcnt(8)
	ds_write_b128 v136, v[78:81] offset:41472
	ds_read_b128 v[172:175], v0 offset:55392
	ds_read_b128 v[176:179], v134 offset:18528
	ds_read_b128 v[180:183], v0 offset:60000
	ds_read_b128 v[184:187], v134 offset:23136
	s_waitcnt lgkmcnt(8)
	v_mfma_f32_32x32x16_f16 v[50:65], v[156:159], v[160:163], v[50:65]
	global_load_dwordx4 v[114:117], v[146:147], off offset:640
	s_waitcnt lgkmcnt(7)
	v_mfma_f32_32x32x16_f16 v[34:49], v[164:167], v[160:163], v[34:49]
	s_waitcnt vmcnt(8)
	ds_write_b128 v136, v[82:85] offset:9216
	s_waitcnt lgkmcnt(7)
	v_mfma_f32_32x32x16_f16 v[18:33], v[156:159], v[168:171], v[18:33]
	global_load_dwordx4 v[118:121], v[148:149], off offset:640
	v_mfma_f32_32x32x16_f16 v[2:17], v[164:167], v[168:171], v[2:17]
	s_waitcnt vmcnt(8)
	ds_write_b128 v136, v[86:89] offset:46080
	s_waitcnt lgkmcnt(4)
	v_mfma_f32_32x32x16_f16 v[50:65], v[172:175], v[176:179], v[50:65]
	global_load_dwordx4 v[122:125], v[150:151], off offset:640
	s_waitcnt lgkmcnt(3)
	v_mfma_f32_32x32x16_f16 v[34:49], v[180:183], v[176:179], v[34:49]
	s_waitcnt vmcnt(8)
	ds_write_b128 v136, v[90:93] offset:13824
	s_waitcnt lgkmcnt(3)
	v_mfma_f32_32x32x16_f16 v[18:33], v[172:175], v[184:187], v[18:33]
	global_load_dwordx4 v[126:129], v[152:153], off offset:640
	v_mfma_f32_32x32x16_f16 v[2:17], v[180:183], v[184:187], v[2:17]
	s_waitcnt vmcnt(8)
	ds_write_b128 v136, v[94:97] offset:50688
	s_setprio 0
	s_waitcnt lgkmcnt(0)
	s_barrier
	s_setprio 1
	ds_read_b128 v[156:159], v0 offset:36864
	ds_read_b128 v[160:163], v134
	ds_read_b128 v[164:167], v0 offset:41472
	ds_read_b128 v[168:171], v134 offset:4608
	ds_read_b128 v[172:175], v0 offset:36896
	ds_read_b128 v[176:179], v134 offset:32
	ds_read_b128 v[180:183], v0 offset:41504
	ds_read_b128 v[184:187], v134 offset:4640
	s_waitcnt lgkmcnt(6)
	v_mfma_f32_32x32x16_f16 v[50:65], v[156:159], v[160:163], v[50:65]
	global_load_dwordx4 v[66:69], v[138:139], off offset:768
	s_waitcnt lgkmcnt(5)
	v_mfma_f32_32x32x16_f16 v[34:49], v[164:167], v[160:163], v[34:49]
	s_waitcnt vmcnt(8)
	ds_write_b128 v136, v[98:101] offset:18432
	s_waitcnt lgkmcnt(5)
	v_mfma_f32_32x32x16_f16 v[18:33], v[156:159], v[168:171], v[18:33]
	global_load_dwordx4 v[70:73], v[140:141], off offset:768
	v_mfma_f32_32x32x16_f16 v[2:17], v[164:167], v[168:171], v[2:17]
	s_waitcnt vmcnt(8)
	ds_write_b128 v136, v[102:105] offset:55296
	ds_read_b128 v[156:159], v0 offset:36928
	ds_read_b128 v[160:163], v134 offset:64
	ds_read_b128 v[164:167], v0 offset:41536
	ds_read_b128 v[168:171], v134 offset:4672
	s_waitcnt lgkmcnt(8)
	v_mfma_f32_32x32x16_f16 v[50:65], v[172:175], v[176:179], v[50:65]
	global_load_dwordx4 v[74:77], v[142:143], off offset:768
	s_waitcnt lgkmcnt(7)
	v_mfma_f32_32x32x16_f16 v[34:49], v[180:183], v[176:179], v[34:49]
	s_waitcnt vmcnt(8)
	ds_write_b128 v136, v[106:109] offset:23040
	s_waitcnt lgkmcnt(7)
	v_mfma_f32_32x32x16_f16 v[18:33], v[172:175], v[184:187], v[18:33]
	global_load_dwordx4 v[78:81], v[144:145], off offset:768
	v_mfma_f32_32x32x16_f16 v[2:17], v[180:183], v[184:187], v[2:17]
	s_waitcnt vmcnt(8)
	ds_write_b128 v136, v[110:113] offset:59904
	ds_read_b128 v[172:175], v0 offset:36960
	ds_read_b128 v[176:179], v134 offset:96
	ds_read_b128 v[180:183], v0 offset:41568
	ds_read_b128 v[184:187], v134 offset:4704
	s_waitcnt lgkmcnt(8)
	v_mfma_f32_32x32x16_f16 v[50:65], v[156:159], v[160:163], v[50:65]
	global_load_dwordx4 v[82:85], v[146:147], off offset:768
	s_waitcnt lgkmcnt(7)
	v_mfma_f32_32x32x16_f16 v[34:49], v[164:167], v[160:163], v[34:49]
	s_waitcnt vmcnt(8)
	ds_write_b128 v136, v[114:117] offset:27648
	s_waitcnt lgkmcnt(7)
	v_mfma_f32_32x32x16_f16 v[18:33], v[156:159], v[168:171], v[18:33]
	global_load_dwordx4 v[86:89], v[148:149], off offset:768
	v_mfma_f32_32x32x16_f16 v[2:17], v[164:167], v[168:171], v[2:17]
	s_waitcnt vmcnt(8)
	ds_write_b128 v136, v[118:121] offset:64512
	s_waitcnt lgkmcnt(4)
	v_mfma_f32_32x32x16_f16 v[50:65], v[172:175], v[176:179], v[50:65]
	global_load_dwordx4 v[90:93], v[150:151], off offset:768
	s_waitcnt lgkmcnt(3)
	v_mfma_f32_32x32x16_f16 v[34:49], v[180:183], v[176:179], v[34:49]
	s_waitcnt vmcnt(8)
	ds_write_b128 v136, v[122:125] offset:32256
	s_waitcnt lgkmcnt(3)
	v_mfma_f32_32x32x16_f16 v[18:33], v[172:175], v[184:187], v[18:33]
	global_load_dwordx4 v[94:97], v[152:153], off offset:768
	v_mfma_f32_32x32x16_f16 v[2:17], v[180:183], v[184:187], v[2:17]
	s_waitcnt vmcnt(8)
	ds_write_b128 v137, v[126:129] offset:64512
	s_setprio 0
	s_waitcnt lgkmcnt(0)
	s_barrier
; #define GEMM_GLOAD(P, kt_) { GEMM_GL1(P, 0, kt_) GEMM_GL1(P, 1, kt_) GEMM_GL1(P, 2, kt_) GEMM_GL1(P, 3, kt_) }
; #define GEMM_LSTORE(P, buf_) { GEMM_LS1(P, 0, buf_) GEMM_LS1(P, 1, buf_) GEMM_LS1(P, 2, buf_) GEMM_LS1(P, 3, buf_) }
; template <bool DEEP>
; DI void gemm_mainloop_t(const u16* __restrict__ Ag, int lda, const u16* __restrict__ Bg, int ldb, int K, char* ldsraw,
;                         f32x16 (&acc)[2][2], int akstep) {
;     ...
;     for (int kt = 0; kt < nk; kt += 2) {
;       if (kt + 2 < nk) GEMM_GLOAD(x, kt + 2);
;       GEMM_COMPUTE(0);
;       GEMM_LSTORE(y, 1);
;       __syncthreads();
;       if (kt + 3 < nk) GEMM_GLOAD(y, kt + 3);
;       GEMM_COMPUTE(1);
;       if (kt + 2 < nk) GEMM_LSTORE(x, 0);
	s_setprio 1
	ds_read_b128 v[156:159], v0 offset:55296
	ds_read_b128 v[160:163], v134 offset:18432
	ds_read_b128 v[164:167], v0 offset:59904
	ds_read_b128 v[168:171], v134 offset:23040
	ds_read_b128 v[172:175], v0 offset:55328
	ds_read_b128 v[176:179], v134 offset:18464
	ds_read_b128 v[180:183], v0 offset:59936
	ds_read_b128 v[184:187], v134 offset:23072
	s_waitcnt lgkmcnt(6)
	v_mfma_f32_32x32x16_f16 v[50:65], v[156:159], v[160:163], v[50:65]
	global_load_dwordx4 v[98:101], v[138:139], off offset:896
	s_waitcnt lgkmcnt(5)
	v_mfma_f32_32x32x16_f16 v[34:49], v[164:167], v[160:163], v[34:49]
	s_waitcnt vmcnt(8)
	ds_write_b128 v136, v[66:69]
	s_waitcnt lgkmcnt(5)
	v_mfma_f32_32x32x16_f16 v[18:33], v[156:159], v[168:171], v[18:33]
	global_load_dwordx4 v[102:105], v[140:141], off offset:896
	v_mfma_f32_32x32x16_f16 v[2:17], v[164:167], v[168:171], v[2:17]
	s_waitcnt vmcnt(8)
	ds_write_b128 v136, v[70:73] offset:36864
	ds_read_b128 v[156:159], v0 offset:55360
	ds_read_b128 v[160:163], v134 offset:18496
	ds_read_b128 v[164:167], v0 offset:59968
	ds_read_b128 v[168:171], v134 offset:23104
	s_waitcnt lgkmcnt(8)
	v_mfma_f32_32x32x16_f16 v[50:65], v[172:175], v[176:179], v[50:65]
	global_load_dwordx4 v[106:109], v[142:143], off offset:896
	s_waitcnt lgkmcnt(7)
	v_mfma_f32_32x32x16_f16 v[34:49], v[180:183], v[176:179], v[34:49]
	s_waitcnt vmcnt(8)
	ds_write_b128 v136, v[74:77] offset:4608
	s_waitcnt lgkmcnt(7)
	v_mfma_f32_32x32x16_f16 v[18:33], v[172:175], v[184:187], v[18:33]
	global_load_dwordx4 v[110:113], v[144:145], off offset:896
	v_mfma_f32_32x32x16_f16 v[2:17], v[180:183], v[184:187], v[2:17]
	s_waitcnt vmcnt(8)
	ds_write_b128 v136, v[78:81] offset:41472
	ds_read_b128 v[172:175], v0 offset:55392
	ds_read_b128 v[176:179], v134 offset:18528
	ds_read_b128 v[180:183], v0 offset:60000
	ds_read_b128 v[184:187], v134 offset:23136
	s_waitcnt lgkmcnt(8)
	v_mfma_f32_32x32x16_f16 v[50:65], v[156:159], v[160:163], v[50:65]
	global_load_dwordx4 v[114:117], v[146:147], off offset:896
	s_waitcnt lgkmcnt(7)
	v_mfma_f32_32x32x16_f16 v[34:49], v[164:167], v[160:163], v[34:49]
	s_waitcnt vmcnt(8)
	ds_write_b128 v136, v[82:85] offset:9216
	s_waitcnt lgkmcnt(7)
	v_mfma_f32_32x32x16_f16 v[18:33], v[156:159], v[168:171], v[18:33]
	global_load_dwordx4 v[118:121], v[148:149], off offset:896
	v_mfma_f32_32x32x16_f16 v[2:17], v[164:167], v[168:171], v[2:17]
	s_waitcnt vmcnt(8)
	ds_write_b128 v136, v[86:89] offset:46080
	s_waitcnt lgkmcnt(4)
	v_mfma_f32_32x32x16_f16 v[50:65], v[172:175], v[176:179], v[50:65]
	global_load_dwordx4 v[122:125], v[150:151], off offset:896
	s_waitcnt lgkmcnt(3)
	v_mfma_f32_32x32x16_f16 v[34:49], v[180:183], v[176:179], v[34:49]
	s_waitcnt vmcnt(8)
	ds_write_b128 v136, v[90:93] offset:13824
	s_waitcnt lgkmcnt(3)
	v_mfma_f32_32x32x16_f16 v[18:33], v[172:175], v[184:187], v[18:33]
	global_load_dwordx4 v[126:129], v[152:153], off offset:896
	v_mfma_f32_32x32x16_f16 v[2:17], v[180:183], v[184:187], v[2:17]
	s_waitcnt vmcnt(8)
	ds_write_b128 v136, v[94:97] offset:50688
	s_setprio 0
	s_waitcnt lgkmcnt(0)
	s_barrier
	s_setprio 1
	ds_read_b128 v[156:159], v0 offset:36864
	ds_read_b128 v[160:163], v134
	ds_read_b128 v[164:167], v0 offset:41472
	ds_read_b128 v[168:171], v134 offset:4608
	ds_read_b128 v[172:175], v0 offset:36896
	ds_read_b128 v[176:179], v134 offset:32
	ds_read_b128 v[180:183], v0 offset:41504
	ds_read_b128 v[184:187], v134 offset:4640
	s_waitcnt lgkmcnt(6)
	v_mfma_f32_32x32x16_f16 v[50:65], v[156:159], v[160:163], v[50:65]
	global_load_dwordx4 v[66:69], v[138:139], off offset:1024
	s_waitcnt lgkmcnt(5)
	v_mfma_f32_32x32x16_f16 v[34:49], v[164:167], v[160:163], v[34:49]
	s_waitcnt vmcnt(8)
	ds_write_b128 v136, v[98:101] offset:18432
	s_waitcnt lgkmcnt(5)
	v_mfma_f32_32x32x16_f16 v[18:33], v[156:159], v[168:171], v[18:33]
	global_load_dwordx4 v[70:73], v[140:141], off offset:1024
	v_mfma_f32_32x32x16_f16 v[2:17], v[164:167], v[168:171], v[2:17]
	s_waitcnt vmcnt(8)
	ds_write_b128 v136, v[102:105] offset:55296
	ds_read_b128 v[156:159], v0 offset:36928
	ds_read_b128 v[160:163], v134 offset:64
	ds_read_b128 v[164:167], v0 offset:41536
	ds_read_b128 v[168:171], v134 offset:4672
	s_waitcnt lgkmcnt(8)
	v_mfma_f32_32x32x16_f16 v[50:65], v[172:175], v[176:179], v[50:65]
	global_load_dwordx4 v[74:77], v[142:143], off offset:1024
	s_waitcnt lgkmcnt(7)
	v_mfma_f32_32x32x16_f16 v[34:49], v[180:183], v[176:179], v[34:49]
	s_waitcnt vmcnt(8)
	ds_write_b128 v136, v[106:109] offset:23040
	s_waitcnt lgkmcnt(7)
	v_mfma_f32_32x32x16_f16 v[18:33], v[172:175], v[184:187], v[18:33]
	global_load_dwordx4 v[78:81], v[144:145], off offset:1024
	v_mfma_f32_32x32x16_f16 v[2:17], v[180:183], v[184:187], v[2:17]
	s_waitcnt vmcnt(8)
	ds_write_b128 v136, v[110:113] offset:59904
	ds_read_b128 v[172:175], v0 offset:36960
	ds_read_b128 v[176:179], v134 offset:96
	ds_read_b128 v[180:183], v0 offset:41568
	ds_read_b128 v[184:187], v134 offset:4704
	s_waitcnt lgkmcnt(8)
	v_mfma_f32_32x32x16_f16 v[50:65], v[156:159], v[160:163], v[50:65]
	global_load_dwordx4 v[82:85], v[146:147], off offset:1024
	s_waitcnt lgkmcnt(7)
	v_mfma_f32_32x32x16_f16 v[34:49], v[164:167], v[160:163], v[34:49]
	s_waitcnt vmcnt(8)
	ds_write_b128 v136, v[114:117] offset:27648
	s_waitcnt lgkmcnt(7)
	v_mfma_f32_32x32x16_f16 v[18:33], v[156:159], v[168:171], v[18:33]
	global_load_dwordx4 v[86:89], v[148:149], off offset:1024
	v_mfma_f32_32x32x16_f16 v[2:17], v[164:167], v[168:171], v[2:17]
	s_waitcnt vmcnt(8)
	ds_write_b128 v136, v[118:121] offset:64512
	s_waitcnt lgkmcnt(4)
	v_mfma_f32_32x32x16_f16 v[50:65], v[172:175], v[176:179], v[50:65]
	global_load_dwordx4 v[90:93], v[150:151], off offset:1024
	s_waitcnt lgkmcnt(3)
	v_mfma_f32_32x32x16_f16 v[34:49], v[180:183], v[176:179], v[34:49]
	s_waitcnt vmcnt(8)
	ds_write_b128 v136, v[122:125] offset:32256
	s_waitcnt lgkmcnt(3)
	v_mfma_f32_32x32x16_f16 v[18:33], v[172:175], v[184:187], v[18:33]
	global_load_dwordx4 v[94:97], v[152:153], off offset:1024
	v_mfma_f32_32x32x16_f16 v[2:17], v[180:183], v[184:187], v[2:17]
	s_waitcnt vmcnt(8)
	ds_write_b128 v137, v[126:129] offset:64512
	s_setprio 0
	s_waitcnt lgkmcnt(0)
	s_barrier
; #define GEMM_GLOAD(P, kt_) { GEMM_GL1(P, 0, kt_) GEMM_GL1(P, 1, kt_) GEMM_GL1(P, 2, kt_) GEMM_GL1(P, 3, kt_) }
; #define GEMM_LSTORE(P, buf_) { GEMM_LS1(P, 0, buf_) GEMM_LS1(P, 1, buf_) GEMM_LS1(P, 2, buf_) GEMM_LS1(P, 3, buf_) }
; template <bool DEEP>
; DI void gemm_mainloop_t(const u16* __restrict__ Ag, int lda, const u16* __restrict__ Bg, int ldb, int K, char* ldsraw,
;                         f32x16 (&acc)[2][2], int akstep) {
;     ...
;     for (int kt = 0; kt < nk; kt += 2) {
;       if (kt + 2 < nk) GEMM_GLOAD(x, kt + 2);
;       GEMM_COMPUTE(0);
;       GEMM_LSTORE(y, 1);
;       __syncthreads();
;       if (kt + 3 < nk) GEMM_GLOAD(y, kt + 3);
;       GEMM_COMPUTE(1);
;       if (kt + 2 < nk) GEMM_LSTORE(x, 0);
	s_setprio 1
	ds_read_b128 v[156:159], v0 offset:55296
	ds_read_b128 v[160:163], v134 offset:18432
	ds_read_b128 v[164:167], v0 offset:59904
	ds_read_b128 v[168:171], v134 offset:23040
	ds_read_b128 v[172:175], v0 offset:55328
	ds_read_b128 v[176:179], v134 offset:18464
	ds_read_b128 v[180:183], v0 offset:59936
	ds_read_b128 v[184:187], v134 offset:23072
	s_waitcnt lgkmcnt(6)
	v_mfma_f32_32x32x16_f16 v[50:65], v[156:159], v[160:163], v[50:65]
	global_load_dwordx4 v[98:101], v[138:139], off offset:1152
	s_waitcnt lgkmcnt(5)
	v_mfma_f32_32x32x16_f16 v[34:49], v[164:167], v[160:163], v[34:49]
	s_waitcnt vmcnt(8)
	ds_write_b128 v136, v[66:69]
	s_waitcnt lgkmcnt(5)
	v_mfma_f32_32x32x16_f16 v[18:33], v[156:159], v[168:171], v[18:33]
	global_load_dwordx4 v[102:105], v[140:141], off offset:1152
	v_mfma_f32_32x32x16_f16 v[2:17], v[164:167], v[168:171], v[2:17]
	s_waitcnt vmcnt(8)
	ds_write_b128 v136, v[70:73] offset:36864
	ds_read_b128 v[156:159], v0 offset:55360
	ds_read_b128 v[160:163], v134 offset:18496
	ds_read_b128 v[164:167], v0 offset:59968
	ds_read_b128 v[168:171], v134 offset:23104
	s_waitcnt lgkmcnt(8)
	v_mfma_f32_32x32x16_f16 v[50:65], v[172:175], v[176:179], v[50:65]
	global_load_dwordx4 v[106:109], v[142:143], off offset:1152
	s_waitcnt lgkmcnt(7)
	v_mfma_f32_32x32x16_f16 v[34:49], v[180:183], v[176:179], v[34:49]
	s_waitcnt vmcnt(8)
	ds_write_b128 v136, v[74:77] offset:4608
	s_waitcnt lgkmcnt(7)
	v_mfma_f32_32x32x16_f16 v[18:33], v[172:175], v[184:187], v[18:33]
	global_load_dwordx4 v[110:113], v[144:145], off offset:1152
	v_mfma_f32_32x32x16_f16 v[2:17], v[180:183], v[184:187], v[2:17]
	s_waitcnt vmcnt(8)
	ds_write_b128 v136, v[78:81] offset:41472
	ds_read_b128 v[172:175], v0 offset:55392
	ds_read_b128 v[176:179], v134 offset:18528
	ds_read_b128 v[180:183], v0 offset:60000
	ds_read_b128 v[184:187], v134 offset:23136
	s_waitcnt lgkmcnt(8)
	v_mfma_f32_32x32x16_f16 v[50:65], v[156:159], v[160:163], v[50:65]
	global_load_dwordx4 v[114:117], v[146:147], off offset:1152
	s_waitcnt lgkmcnt(7)
	v_mfma_f32_32x32x16_f16 v[34:49], v[164:167], v[160:163], v[34:49]
	s_waitcnt vmcnt(8)
	ds_write_b128 v136, v[82:85] offset:9216
	s_waitcnt lgkmcnt(7)
	v_mfma_f32_32x32x16_f16 v[18:33], v[156:159], v[168:171], v[18:33]
	global_load_dwordx4 v[118:121], v[148:149], off offset:1152
	v_mfma_f32_32x32x16_f16 v[2:17], v[164:167], v[168:171], v[2:17]
	s_waitcnt vmcnt(8)
	ds_write_b128 v136, v[86:89] offset:46080
	s_waitcnt lgkmcnt(4)
	v_mfma_f32_32x32x16_f16 v[50:65], v[172:175], v[176:179], v[50:65]
	global_load_dwordx4 v[122:125], v[150:151], off offset:1152
	s_waitcnt lgkmcnt(3)
	v_mfma_f32_32x32x16_f16 v[34:49], v[180:183], v[176:179], v[34:49]
	s_waitcnt vmcnt(8)
	ds_write_b128 v136, v[90:93] offset:13824
	s_waitcnt lgkmcnt(3)
	v_mfma_f32_32x32x16_f16 v[18:33], v[172:175], v[184:187], v[18:33]
	global_load_dwordx4 v[126:129], v[152:153], off offset:1152
	v_mfma_f32_32x32x16_f16 v[2:17], v[180:183], v[184:187], v[2:17]
	s_waitcnt vmcnt(8)
	ds_write_b128 v136, v[94:97] offset:50688
	s_setprio 0
	s_waitcnt lgkmcnt(0)
	s_barrier
	s_setprio 1
	ds_read_b128 v[156:159], v0 offset:36864
	ds_read_b128 v[160:163], v134
	ds_read_b128 v[164:167], v0 offset:41472
	ds_read_b128 v[168:171], v134 offset:4608
	ds_read_b128 v[172:175], v0 offset:36896
	ds_read_b128 v[176:179], v134 offset:32
	ds_read_b128 v[180:183], v0 offset:41504
	ds_read_b128 v[184:187], v134 offset:4640
	s_waitcnt lgkmcnt(6)
	v_mfma_f32_32x32x16_f16 v[50:65], v[156:159], v[160:163], v[50:65]
	global_load_dwordx4 v[66:69], v[138:139], off offset:1280
	s_waitcnt lgkmcnt(5)
	v_mfma_f32_32x32x16_f16 v[34:49], v[164:167], v[160:163], v[34:49]
	s_waitcnt vmcnt(8)
	ds_write_b128 v136, v[98:101] offset:18432
	s_waitcnt lgkmcnt(5)
	v_mfma_f32_32x32x16_f16 v[18:33], v[156:159], v[168:171], v[18:33]
	global_load_dwordx4 v[70:73], v[140:141], off offset:1280
	v_mfma_f32_32x32x16_f16 v[2:17], v[164:167], v[168:171], v[2:17]
	s_waitcnt vmcnt(8)
	ds_write_b128 v136, v[102:105] offset:55296
	ds_read_b128 v[156:159], v0 offset:36928
	ds_read_b128 v[160:163], v134 offset:64
	ds_read_b128 v[164:167], v0 offset:41536
	ds_read_b128 v[168:171], v134 offset:4672
	s_waitcnt lgkmcnt(8)
	v_mfma_f32_32x32x16_f16 v[50:65], v[172:175], v[176:179], v[50:65]
	global_load_dwordx4 v[74:77], v[142:143], off offset:1280
	s_waitcnt lgkmcnt(7)
	v_mfma_f32_32x32x16_f16 v[34:49], v[180:183], v[176:179], v[34:49]
	s_waitcnt vmcnt(8)
	ds_write_b128 v136, v[106:109] offset:23040
	s_waitcnt lgkmcnt(7)
	v_mfma_f32_32x32x16_f16 v[18:33], v[172:175], v[184:187], v[18:33]
	global_load_dwordx4 v[78:81], v[144:145], off offset:1280
	v_mfma_f32_32x32x16_f16 v[2:17], v[180:183], v[184:187], v[2:17]
	s_waitcnt vmcnt(8)
	ds_write_b128 v136, v[110:113] offset:59904
	ds_read_b128 v[172:175], v0 offset:36960
	ds_read_b128 v[176:179], v134 offset:96
	ds_read_b128 v[180:183], v0 offset:41568
	ds_read_b128 v[184:187], v134 offset:4704
	s_waitcnt lgkmcnt(8)
	v_mfma_f32_32x32x16_f16 v[50:65], v[156:159], v[160:163], v[50:65]
	global_load_dwordx4 v[82:85], v[146:147], off offset:1280
	s_waitcnt lgkmcnt(7)
	v_mfma_f32_32x32x16_f16 v[34:49], v[164:167], v[160:163], v[34:49]
	s_waitcnt vmcnt(8)
	ds_write_b128 v136, v[114:117] offset:27648
	s_waitcnt lgkmcnt(7)
	v_mfma_f32_32x32x16_f16 v[18:33], v[156:159], v[168:171], v[18:33]
	global_load_dwordx4 v[86:89], v[148:149], off offset:1280
	v_mfma_f32_32x32x16_f16 v[2:17], v[164:167], v[168:171], v[2:17]
	s_waitcnt vmcnt(8)
	ds_write_b128 v136, v[118:121] offset:64512
	s_waitcnt lgkmcnt(4)
	v_mfma_f32_32x32x16_f16 v[50:65], v[172:175], v[176:179], v[50:65]
	global_load_dwordx4 v[90:93], v[150:151], off offset:1280
	s_waitcnt lgkmcnt(3)
	v_mfma_f32_32x32x16_f16 v[34:49], v[180:183], v[176:179], v[34:49]
	s_waitcnt vmcnt(8)
	ds_write_b128 v136, v[122:125] offset:32256
	s_waitcnt lgkmcnt(3)
	v_mfma_f32_32x32x16_f16 v[18:33], v[172:175], v[184:187], v[18:33]
	global_load_dwordx4 v[94:97], v[152:153], off offset:1280
	v_mfma_f32_32x32x16_f16 v[2:17], v[180:183], v[184:187], v[2:17]
	s_waitcnt vmcnt(8)
	ds_write_b128 v137, v[126:129] offset:64512
	s_setprio 0
	s_waitcnt lgkmcnt(0)
	s_barrier
; #define GEMM_GLOAD(P, kt_) { GEMM_GL1(P, 0, kt_) GEMM_GL1(P, 1, kt_) GEMM_GL1(P, 2, kt_) GEMM_GL1(P, 3, kt_) }
; #define GEMM_LSTORE(P, buf_) { GEMM_LS1(P, 0, buf_) GEMM_LS1(P, 1, buf_) GEMM_LS1(P, 2, buf_) GEMM_LS1(P, 3, buf_) }
; template <bool DEEP>
; DI void gemm_mainloop_t(const u16* __restrict__ Ag, int lda, const u16* __restrict__ Bg, int ldb, int K, char* ldsraw,
;                         f32x16 (&acc)[2][2], int akstep) {
;     ...
;     for (int kt = 0; kt < nk; kt += 2) {
;       if (kt + 2 < nk) GEMM_GLOAD(x, kt + 2);
;       GEMM_COMPUTE(0);
;       GEMM_LSTORE(y, 1);
;       __syncthreads();
;       if (kt + 3 < nk) GEMM_GLOAD(y, kt + 3);
;       GEMM_COMPUTE(1);
;       if (kt + 2 < nk) GEMM_LSTORE(x, 0);
	s_setprio 1
	ds_read_b128 v[156:159], v0 offset:55296
	ds_read_b128 v[160:163], v134 offset:18432
	ds_read_b128 v[164:167], v0 offset:59904
	ds_read_b128 v[168:171], v134 offset:23040
	ds_read_b128 v[172:175], v0 offset:55328
	ds_read_b128 v[176:179], v134 offset:18464
	ds_read_b128 v[180:183], v0 offset:59936
	ds_read_b128 v[184:187], v134 offset:23072
	s_waitcnt lgkmcnt(6)
	v_mfma_f32_32x32x16_f16 v[50:65], v[156:159], v[160:163], v[50:65]
	global_load_dwordx4 v[98:101], v[138:139], off offset:1408
	s_waitcnt lgkmcnt(5)
	v_mfma_f32_32x32x16_f16 v[34:49], v[164:167], v[160:163], v[34:49]
	s_waitcnt vmcnt(8)
	ds_write_b128 v136, v[66:69]
	s_waitcnt lgkmcnt(5)
	v_mfma_f32_32x32x16_f16 v[18:33], v[156:159], v[168:171], v[18:33]
	global_load_dwordx4 v[102:105], v[140:141], off offset:1408
	v_mfma_f32_32x32x16_f16 v[2:17], v[164:167], v[168:171], v[2:17]
	s_waitcnt vmcnt(8)
	ds_write_b128 v136, v[70:73] offset:36864
	ds_read_b128 v[156:159], v0 offset:55360
	ds_read_b128 v[160:163], v134 offset:18496
	ds_read_b128 v[164:167], v0 offset:59968
	ds_read_b128 v[168:171], v134 offset:23104
	s_waitcnt lgkmcnt(8)
	v_mfma_f32_32x32x16_f16 v[50:65], v[172:175], v[176:179], v[50:65]
	global_load_dwordx4 v[106:109], v[142:143], off offset:1408
	s_waitcnt lgkmcnt(7)
	v_mfma_f32_32x32x16_f16 v[34:49], v[180:183], v[176:179], v[34:49]
	s_waitcnt vmcnt(8)
	ds_write_b128 v136, v[74:77] offset:4608
	s_waitcnt lgkmcnt(7)
	v_mfma_f32_32x32x16_f16 v[18:33], v[172:175], v[184:187], v[18:33]
	global_load_dwordx4 v[110:113], v[144:145], off offset:1408
	v_mfma_f32_32x32x16_f16 v[2:17], v[180:183], v[184:187], v[2:17]
	s_waitcnt vmcnt(8)
	ds_write_b128 v136, v[78:81] offset:41472
	ds_read_b128 v[172:175], v0 offset:55392
	ds_read_b128 v[176:179], v134 offset:18528
	ds_read_b128 v[180:183], v0 offset:60000
	ds_read_b128 v[184:187], v134 offset:23136
	s_waitcnt lgkmcnt(8)
	v_mfma_f32_32x32x16_f16 v[50:65], v[156:159], v[160:163], v[50:65]
	global_load_dwordx4 v[114:117], v[146:147], off offset:1408
	s_waitcnt lgkmcnt(7)
	v_mfma_f32_32x32x16_f16 v[34:49], v[164:167], v[160:163], v[34:49]
	s_waitcnt vmcnt(8)
	ds_write_b128 v136, v[82:85] offset:9216
	s_waitcnt lgkmcnt(7)
	v_mfma_f32_32x32x16_f16 v[18:33], v[156:159], v[168:171], v[18:33]
	global_load_dwordx4 v[118:121], v[148:149], off offset:1408
	v_mfma_f32_32x32x16_f16 v[2:17], v[164:167], v[168:171], v[2:17]
	s_waitcnt vmcnt(8)
	ds_write_b128 v136, v[86:89] offset:46080
	s_waitcnt lgkmcnt(4)
	v_mfma_f32_32x32x16_f16 v[50:65], v[172:175], v[176:179], v[50:65]
	global_load_dwordx4 v[122:125], v[150:151], off offset:1408
	s_waitcnt lgkmcnt(3)
	v_mfma_f32_32x32x16_f16 v[34:49], v[180:183], v[176:179], v[34:49]
	s_waitcnt vmcnt(8)
	ds_write_b128 v136, v[90:93] offset:13824
	s_waitcnt lgkmcnt(3)
	v_mfma_f32_32x32x16_f16 v[18:33], v[172:175], v[184:187], v[18:33]
	global_load_dwordx4 v[126:129], v[152:153], off offset:1408
	v_mfma_f32_32x32x16_f16 v[2:17], v[180:183], v[184:187], v[2:17]
	s_waitcnt vmcnt(8)
	ds_write_b128 v136, v[94:97] offset:50688
	s_setprio 0
	s_waitcnt lgkmcnt(0)
	s_barrier
	s_setprio 1
	ds_read_b128 v[156:159], v0 offset:36864
	ds_read_b128 v[160:163], v134
	ds_read_b128 v[164:167], v0 offset:41472
	ds_read_b128 v[168:171], v134 offset:4608
	ds_read_b128 v[172:175], v0 offset:36896
	ds_read_b128 v[176:179], v134 offset:32
	ds_read_b128 v[180:183], v0 offset:41504
	ds_read_b128 v[184:187], v134 offset:4640
	s_waitcnt lgkmcnt(6)
	v_mfma_f32_32x32x16_f16 v[50:65], v[156:159], v[160:163], v[50:65]
	global_load_dwordx4 v[66:69], v[138:139], off offset:1536
	s_waitcnt lgkmcnt(5)
	v_mfma_f32_32x32x16_f16 v[34:49], v[164:167], v[160:163], v[34:49]
	s_waitcnt vmcnt(8)
	ds_write_b128 v136, v[98:101] offset:18432
	s_waitcnt lgkmcnt(5)
	v_mfma_f32_32x32x16_f16 v[18:33], v[156:159], v[168:171], v[18:33]
	global_load_dwordx4 v[70:73], v[140:141], off offset:1536
	v_mfma_f32_32x32x16_f16 v[2:17], v[164:167], v[168:171], v[2:17]
	s_waitcnt vmcnt(8)
	ds_write_b128 v136, v[102:105] offset:55296
	ds_read_b128 v[156:159], v0 offset:36928
	ds_read_b128 v[160:163], v134 offset:64
	ds_read_b128 v[164:167], v0 offset:41536
	ds_read_b128 v[168:171], v134 offset:4672
	s_waitcnt lgkmcnt(8)
	v_mfma_f32_32x32x16_f16 v[50:65], v[172:175], v[176:179], v[50:65]
	global_load_dwordx4 v[74:77], v[142:143], off offset:1536
	s_waitcnt lgkmcnt(7)
	v_mfma_f32_32x32x16_f16 v[34:49], v[180:183], v[176:179], v[34:49]
	s_waitcnt vmcnt(8)
	ds_write_b128 v136, v[106:109] offset:23040
	s_waitcnt lgkmcnt(7)
	v_mfma_f32_32x32x16_f16 v[18:33], v[172:175], v[184:187], v[18:33]
	global_load_dwordx4 v[78:81], v[144:145], off offset:1536
	v_mfma_f32_32x32x16_f16 v[2:17], v[180:183], v[184:187], v[2:17]
	s_waitcnt vmcnt(8)
	ds_write_b128 v136, v[110:113] offset:59904
	ds_read_b128 v[172:175], v0 offset:36960
	ds_read_b128 v[176:179], v134 offset:96
	ds_read_b128 v[180:183], v0 offset:41568
	ds_read_b128 v[184:187], v134 offset:4704
	s_waitcnt lgkmcnt(8)
	v_mfma_f32_32x32x16_f16 v[50:65], v[156:159], v[160:163], v[50:65]
	global_load_dwordx4 v[82:85], v[146:147], off offset:1536
	s_waitcnt lgkmcnt(7)
	v_mfma_f32_32x32x16_f16 v[34:49], v[164:167], v[160:163], v[34:49]
	s_waitcnt vmcnt(8)
	ds_write_b128 v136, v[114:117] offset:27648
	s_waitcnt lgkmcnt(7)
	v_mfma_f32_32x32x16_f16 v[18:33], v[156:159], v[168:171], v[18:33]
	global_load_dwordx4 v[86:89], v[148:149], off offset:1536
	v_mfma_f32_32x32x16_f16 v[2:17], v[164:167], v[168:171], v[2:17]
	s_waitcnt vmcnt(8)
	ds_write_b128 v136, v[118:121] offset:64512
	s_waitcnt lgkmcnt(4)
	v_mfma_f32_32x32x16_f16 v[50:65], v[172:175], v[176:179], v[50:65]
	global_load_dwordx4 v[90:93], v[150:151], off offset:1536
	s_waitcnt lgkmcnt(3)
	v_mfma_f32_32x32x16_f16 v[34:49], v[180:183], v[176:179], v[34:49]
	s_waitcnt vmcnt(8)
	ds_write_b128 v136, v[122:125] offset:32256
	s_waitcnt lgkmcnt(3)
	v_mfma_f32_32x32x16_f16 v[18:33], v[172:175], v[184:187], v[18:33]
	global_load_dwordx4 v[94:97], v[152:153], off offset:1536
	v_mfma_f32_32x32x16_f16 v[2:17], v[180:183], v[184:187], v[2:17]
	s_waitcnt vmcnt(8)
	ds_write_b128 v137, v[126:129] offset:64512
	s_setprio 0
	s_waitcnt lgkmcnt(0)
	s_barrier
; #define GEMM_GLOAD(P, kt_) { GEMM_GL1(P, 0, kt_) GEMM_GL1(P, 1, kt_) GEMM_GL1(P, 2, kt_) GEMM_GL1(P, 3, kt_) }
; #define GEMM_LSTORE(P, buf_) { GEMM_LS1(P, 0, buf_) GEMM_LS1(P, 1, buf_) GEMM_LS1(P, 2, buf_) GEMM_LS1(P, 3, buf_) }
; template <bool DEEP>
; DI void gemm_mainloop_t(const u16* __restrict__ Ag, int lda, const u16* __restrict__ Bg, int ldb, int K, char* ldsraw,
;                         f32x16 (&acc)[2][2], int akstep) {
;     ...
;     for (int kt = 0; kt < nk; kt += 2) {
;       if (kt + 2 < nk) GEMM_GLOAD(x, kt + 2);
;       GEMM_COMPUTE(0);
;       GEMM_LSTORE(y, 1);
;       __syncthreads();
;       if (kt + 3 < nk) GEMM_GLOAD(y, kt + 3);
;       GEMM_COMPUTE(1);
;       if (kt + 2 < nk) GEMM_LSTORE(x, 0);
	s_setprio 1
	ds_read_b128 v[156:159], v0 offset:55296
	ds_read_b128 v[160:163], v134 offset:18432
	ds_read_b128 v[164:167], v0 offset:59904
	ds_read_b128 v[168:171], v134 offset:23040
	ds_read_b128 v[172:175], v0 offset:55328
	ds_read_b128 v[176:179], v134 offset:18464
	ds_read_b128 v[180:183], v0 offset:59936
	ds_read_b128 v[184:187], v134 offset:23072
	s_waitcnt lgkmcnt(6)
	v_mfma_f32_32x32x16_f16 v[50:65], v[156:159], v[160:163], v[50:65]
	global_load_dwordx4 v[98:101], v[138:139], off offset:1664
	s_waitcnt lgkmcnt(5)
	v_mfma_f32_32x32x16_f16 v[34:49], v[164:167], v[160:163], v[34:49]
	s_waitcnt vmcnt(8)
	ds_write_b128 v136, v[66:69]
	s_waitcnt lgkmcnt(5)
	v_mfma_f32_32x32x16_f16 v[18:33], v[156:159], v[168:171], v[18:33]
	global_load_dwordx4 v[102:105], v[140:141], off offset:1664
	v_mfma_f32_32x32x16_f16 v[2:17], v[164:167], v[168:171], v[2:17]
	s_waitcnt vmcnt(8)
	ds_write_b128 v136, v[70:73] offset:36864
	ds_read_b128 v[156:159], v0 offset:55360
	ds_read_b128 v[160:163], v134 offset:18496
	ds_read_b128 v[164:167], v0 offset:59968
	ds_read_b128 v[168:171], v134 offset:23104
	s_waitcnt lgkmcnt(8)
	v_mfma_f32_32x32x16_f16 v[50:65], v[172:175], v[176:179], v[50:65]
	global_load_dwordx4 v[106:109], v[142:143], off offset:1664
	s_waitcnt lgkmcnt(7)
	v_mfma_f32_32x32x16_f16 v[34:49], v[180:183], v[176:179], v[34:49]
	s_waitcnt vmcnt(8)
	ds_write_b128 v136, v[74:77] offset:4608
	s_waitcnt lgkmcnt(7)
	v_mfma_f32_32x32x16_f16 v[18:33], v[172:175], v[184:187], v[18:33]
	global_load_dwordx4 v[110:113], v[144:145], off offset:1664
	v_mfma_f32_32x32x16_f16 v[2:17], v[180:183], v[184:187], v[2:17]
	s_waitcnt vmcnt(8)
	ds_write_b128 v136, v[78:81] offset:41472
	ds_read_b128 v[172:175], v0 offset:55392
	ds_read_b128 v[176:179], v134 offset:18528
	ds_read_b128 v[180:183], v0 offset:60000
	ds_read_b128 v[184:187], v134 offset:23136
	s_waitcnt lgkmcnt(8)
	v_mfma_f32_32x32x16_f16 v[50:65], v[156:159], v[160:163], v[50:65]
	global_load_dwordx4 v[114:117], v[146:147], off offset:1664
	s_waitcnt lgkmcnt(7)
	v_mfma_f32_32x32x16_f16 v[34:49], v[164:167], v[160:163], v[34:49]
	s_waitcnt vmcnt(8)
	ds_write_b128 v136, v[82:85] offset:9216
	s_waitcnt lgkmcnt(7)
	v_mfma_f32_32x32x16_f16 v[18:33], v[156:159], v[168:171], v[18:33]
	global_load_dwordx4 v[118:121], v[148:149], off offset:1664
	v_mfma_f32_32x32x16_f16 v[2:17], v[164:167], v[168:171], v[2:17]
	s_waitcnt vmcnt(8)
	ds_write_b128 v136, v[86:89] offset:46080
	s_waitcnt lgkmcnt(4)
	v_mfma_f32_32x32x16_f16 v[50:65], v[172:175], v[176:179], v[50:65]
	global_load_dwordx4 v[122:125], v[150:151], off offset:1664
	s_waitcnt lgkmcnt(3)
	v_mfma_f32_32x32x16_f16 v[34:49], v[180:183], v[176:179], v[34:49]
	s_waitcnt vmcnt(8)
	ds_write_b128 v136, v[90:93] offset:13824
	s_waitcnt lgkmcnt(3)
	v_mfma_f32_32x32x16_f16 v[18:33], v[172:175], v[184:187], v[18:33]
	global_load_dwordx4 v[126:129], v[152:153], off offset:1664
	v_mfma_f32_32x32x16_f16 v[2:17], v[180:183], v[184:187], v[2:17]
	s_waitcnt vmcnt(8)
	ds_write_b128 v136, v[94:97] offset:50688
	s_setprio 0
	s_waitcnt lgkmcnt(0)
	s_barrier
	s_setprio 1
	ds_read_b128 v[156:159], v0 offset:36864
	ds_read_b128 v[160:163], v134
	ds_read_b128 v[164:167], v0 offset:41472
	ds_read_b128 v[168:171], v134 offset:4608
	ds_read_b128 v[172:175], v0 offset:36896
	ds_read_b128 v[176:179], v134 offset:32
	ds_read_b128 v[180:183], v0 offset:41504
	ds_read_b128 v[184:187], v134 offset:4640
	s_waitcnt lgkmcnt(6)
	v_mfma_f32_32x32x16_f16 v[50:65], v[156:159], v[160:163], v[50:65]
	global_load_dwordx4 v[66:69], v[138:139], off offset:1792
	s_waitcnt lgkmcnt(5)
	v_mfma_f32_32x32x16_f16 v[34:49], v[164:167], v[160:163], v[34:49]
	s_waitcnt vmcnt(8)
	ds_write_b128 v136, v[98:101] offset:18432
	s_waitcnt lgkmcnt(5)
	v_mfma_f32_32x32x16_f16 v[18:33], v[156:159], v[168:171], v[18:33]
	global_load_dwordx4 v[70:73], v[140:141], off offset:1792
	v_mfma_f32_32x32x16_f16 v[2:17], v[164:167], v[168:171], v[2:17]
	s_waitcnt vmcnt(8)
	ds_write_b128 v136, v[102:105] offset:55296
	ds_read_b128 v[156:159], v0 offset:36928
	ds_read_b128 v[160:163], v134 offset:64
	ds_read_b128 v[164:167], v0 offset:41536
	ds_read_b128 v[168:171], v134 offset:4672
	s_waitcnt lgkmcnt(8)
	v_mfma_f32_32x32x16_f16 v[50:65], v[172:175], v[176:179], v[50:65]
	global_load_dwordx4 v[74:77], v[142:143], off offset:1792
	s_waitcnt lgkmcnt(7)
	v_mfma_f32_32x32x16_f16 v[34:49], v[180:183], v[176:179], v[34:49]
	s_waitcnt vmcnt(8)
	ds_write_b128 v136, v[106:109] offset:23040
	s_waitcnt lgkmcnt(7)
	v_mfma_f32_32x32x16_f16 v[18:33], v[172:175], v[184:187], v[18:33]
	global_load_dwordx4 v[78:81], v[144:145], off offset:1792
	v_mfma_f32_32x32x16_f16 v[2:17], v[180:183], v[184:187], v[2:17]
	s_waitcnt vmcnt(8)
	ds_write_b128 v136, v[110:113] offset:59904
	ds_read_b128 v[172:175], v0 offset:36960
	ds_read_b128 v[176:179], v134 offset:96
	ds_read_b128 v[180:183], v0 offset:41568
	ds_read_b128 v[184:187], v134 offset:4704
	s_waitcnt lgkmcnt(8)
	v_mfma_f32_32x32x16_f16 v[50:65], v[156:159], v[160:163], v[50:65]
	global_load_dwordx4 v[82:85], v[146:147], off offset:1792
	s_waitcnt lgkmcnt(7)
	v_mfma_f32_32x32x16_f16 v[34:49], v[164:167], v[160:163], v[34:49]
	s_waitcnt vmcnt(8)
	ds_write_b128 v136, v[114:117] offset:27648
	s_waitcnt lgkmcnt(7)
	v_mfma_f32_32x32x16_f16 v[18:33], v[156:159], v[168:171], v[18:33]
	global_load_dwordx4 v[86:89], v[148:149], off offset:1792
	v_mfma_f32_32x32x16_f16 v[2:17], v[164:167], v[168:171], v[2:17]
	s_waitcnt vmcnt(8)
	ds_write_b128 v136, v[118:121] offset:64512
	s_waitcnt lgkmcnt(4)
	v_mfma_f32_32x32x16_f16 v[50:65], v[172:175], v[176:179], v[50:65]
	global_load_dwordx4 v[90:93], v[150:151], off offset:1792
	s_waitcnt lgkmcnt(3)
	v_mfma_f32_32x32x16_f16 v[34:49], v[180:183], v[176:179], v[34:49]
	s_waitcnt vmcnt(8)
	ds_write_b128 v136, v[122:125] offset:32256
	s_waitcnt lgkmcnt(3)
	v_mfma_f32_32x32x16_f16 v[18:33], v[172:175], v[184:187], v[18:33]
	global_load_dwordx4 v[94:97], v[152:153], off offset:1792
	v_mfma_f32_32x32x16_f16 v[2:17], v[180:183], v[184:187], v[2:17]
	s_waitcnt vmcnt(8)
	ds_write_b128 v137, v[126:129] offset:64512
	s_setprio 0
	s_waitcnt lgkmcnt(0)
	s_barrier
; #define GEMM_GLOAD(P, kt_) { GEMM_GL1(P, 0, kt_) GEMM_GL1(P, 1, kt_) GEMM_GL1(P, 2, kt_) GEMM_GL1(P, 3, kt_) }
; #define GEMM_LSTORE(P, buf_) { GEMM_LS1(P, 0, buf_) GEMM_LS1(P, 1, buf_) GEMM_LS1(P, 2, buf_) GEMM_LS1(P, 3, buf_) }
; template <bool DEEP>
; DI void gemm_mainloop_t(const u16* __restrict__ Ag, int lda, const u16* __restrict__ Bg, int ldb, int K, char* ldsraw,
;                         f32x16 (&acc)[2][2], int akstep) {
;     ...
;     for (int kt = 0; kt < nk; kt += 2) {
;       if (kt + 2 < nk) GEMM_GLOAD(x, kt + 2);
;       GEMM_COMPUTE(0);
;       GEMM_LSTORE(y, 1);
;       __syncthreads();
;       if (kt + 3 < nk) GEMM_GLOAD(y, kt + 3);
;       GEMM_COMPUTE(1);
;       if (kt + 2 < nk) GEMM_LSTORE(x, 0);
	global_load_dwordx4 v[98:101], v[138:139], off offset:1920
	global_load_dwordx4 v[102:105], v[140:141], off offset:1920
	global_load_dwordx4 v[106:109], v[142:143], off offset:1920
	global_load_dwordx4 v[110:113], v[144:145], off offset:1920
	global_load_dwordx4 v[114:117], v[146:147], off offset:1920
	global_load_dwordx4 v[118:121], v[148:149], off offset:1920
	global_load_dwordx4 v[122:125], v[150:151], off offset:1920
	global_load_dwordx4 v[126:129], v[152:153], off offset:1920
	s_setprio 1
	ds_read_b128 v[156:159], v0 offset:55296
	ds_read_b128 v[160:163], v134 offset:18432
	ds_read_b128 v[164:167], v0 offset:59904
	ds_read_b128 v[168:171], v134 offset:23040
	ds_read_b128 v[172:175], v0 offset:55328
	ds_read_b128 v[176:179], v134 offset:18464
	ds_read_b128 v[180:183], v0 offset:59936
	ds_read_b128 v[184:187], v134 offset:23072
	s_waitcnt lgkmcnt(6)
	v_mfma_f32_32x32x16_f16 v[50:65], v[156:159], v[160:163], v[50:65]
	s_waitcnt lgkmcnt(5)
	v_mfma_f32_32x32x16_f16 v[34:49], v[164:167], v[160:163], v[34:49]
	s_waitcnt vmcnt(15)
	ds_write_b128 v136, v[66:69]
	s_waitcnt lgkmcnt(5)
	v_mfma_f32_32x32x16_f16 v[18:33], v[156:159], v[168:171], v[18:33]
	v_mfma_f32_32x32x16_f16 v[2:17], v[164:167], v[168:171], v[2:17]
	s_waitcnt vmcnt(14)
	ds_write_b128 v136, v[70:73] offset:36864
	ds_read_b128 v[156:159], v0 offset:55360
	ds_read_b128 v[160:163], v134 offset:18496
	ds_read_b128 v[164:167], v0 offset:59968
	ds_read_b128 v[168:171], v134 offset:23104
	s_waitcnt lgkmcnt(8)
	v_mfma_f32_32x32x16_f16 v[50:65], v[172:175], v[176:179], v[50:65]
	s_waitcnt lgkmcnt(7)
	v_mfma_f32_32x32x16_f16 v[34:49], v[180:183], v[176:179], v[34:49]
	s_waitcnt vmcnt(13)
	ds_write_b128 v136, v[74:77] offset:4608
	s_waitcnt lgkmcnt(7)
	v_mfma_f32_32x32x16_f16 v[18:33], v[172:175], v[184:187], v[18:33]
	v_mfma_f32_32x32x16_f16 v[2:17], v[180:183], v[184:187], v[2:17]
	s_waitcnt vmcnt(12)
	ds_write_b128 v136, v[78:81] offset:41472
	ds_read_b128 v[172:175], v0 offset:55392
	ds_read_b128 v[176:179], v134 offset:18528
	ds_read_b128 v[180:183], v0 offset:60000
	ds_read_b128 v[184:187], v134 offset:23136
	s_waitcnt lgkmcnt(8)
	v_mfma_f32_32x32x16_f16 v[50:65], v[156:159], v[160:163], v[50:65]
	s_waitcnt lgkmcnt(7)
	v_mfma_f32_32x32x16_f16 v[34:49], v[164:167], v[160:163], v[34:49]
	s_waitcnt vmcnt(11)
	ds_write_b128 v136, v[82:85] offset:9216
	s_waitcnt lgkmcnt(7)
	v_mfma_f32_32x32x16_f16 v[18:33], v[156:159], v[168:171], v[18:33]
	v_mfma_f32_32x32x16_f16 v[2:17], v[164:167], v[168:171], v[2:17]
	s_waitcnt vmcnt(10)
	ds_write_b128 v136, v[86:89] offset:46080
	s_waitcnt lgkmcnt(4)
	v_mfma_f32_32x32x16_f16 v[50:65], v[172:175], v[176:179], v[50:65]
	s_waitcnt lgkmcnt(3)
	v_mfma_f32_32x32x16_f16 v[34:49], v[180:183], v[176:179], v[34:49]
	s_waitcnt vmcnt(9)
	ds_write_b128 v136, v[90:93] offset:13824
	s_waitcnt lgkmcnt(3)
	v_mfma_f32_32x32x16_f16 v[18:33], v[172:175], v[184:187], v[18:33]
	v_mfma_f32_32x32x16_f16 v[2:17], v[180:183], v[184:187], v[2:17]
	s_waitcnt vmcnt(8)
	ds_write_b128 v136, v[94:97] offset:50688
	s_setprio 0
	s_waitcnt lgkmcnt(0)
	s_barrier
; #define GEMM_GLOAD(P, kt_) { GEMM_GL1(P, 0, kt_) GEMM_GL1(P, 1, kt_) GEMM_GL1(P, 2, kt_) GEMM_GL1(P, 3, kt_) }
; #define GEMM_LSTORE(P, buf_) { GEMM_LS1(P, 0, buf_) GEMM_LS1(P, 1, buf_) GEMM_LS1(P, 2, buf_) GEMM_LS1(P, 3, buf_) }
; template <bool DEEP>
; DI void gemm_mainloop_t(const u16* __restrict__ Ag, int lda, const u16* __restrict__ Bg, int ldb, int K, char* ldsraw,
;                         f32x16 (&acc)[2][2], int akstep) {
;     ...
;     for (int kt = 0; kt < nk; kt += 2) {
;       if (kt + 2 < nk) GEMM_GLOAD(x, kt + 2);
;       GEMM_COMPUTE(0);
;       GEMM_LSTORE(y, 1);
;       __syncthreads();
;       if (kt + 3 < nk) GEMM_GLOAD(y, kt + 3);
;       GEMM_COMPUTE(1);
;       if (kt + 2 < nk) GEMM_LSTORE(x, 0);
;       __syncthreads();
; DI void phase1(const Params& p, int l, char* lds) {
;     ...
;     {
;       const int col0 = nt * 128 + wn * 64;
;       const float* gain = nullptr;
;       float sc = 1.f;
;       if (col0 < 512) { gain = p.qn_a + l * 64; sc = QSCALE; }
;       else if (col0 < 1024) { gain = p.kn_a + l * 64; }
;       else if (col0 >= QC && col0 < QC + 512) { gain = p.qn_c + l * 64; sc = QSCALE; }
;       else if ((col0 >= KSC && col0 < KSC + 128) || (col0 >= KWC && col0 < KWC + 128)) { gain = p.kn_c + l * 64; }
	s_setprio 1
	ds_read_b128 v[156:159], v0 offset:36864
	ds_read_b128 v[160:163], v134
	ds_read_b128 v[164:167], v0 offset:41472
	ds_read_b128 v[168:171], v134 offset:4608
	ds_read_b128 v[172:175], v0 offset:36896
	ds_read_b128 v[176:179], v134 offset:32
	ds_read_b128 v[180:183], v0 offset:41504
	ds_read_b128 v[184:187], v134 offset:4640
	s_waitcnt lgkmcnt(6)
	v_mfma_f32_32x32x16_f16 v[50:65], v[156:159], v[160:163], v[50:65]
	s_waitcnt lgkmcnt(5)
	v_mfma_f32_32x32x16_f16 v[34:49], v[164:167], v[160:163], v[34:49]
	s_waitcnt vmcnt(7)
	ds_write_b128 v136, v[98:101] offset:18432
	s_waitcnt lgkmcnt(5)
	v_mfma_f32_32x32x16_f16 v[18:33], v[156:159], v[168:171], v[18:33]
	v_mfma_f32_32x32x16_f16 v[2:17], v[164:167], v[168:171], v[2:17]
	s_waitcnt vmcnt(6)
	ds_write_b128 v136, v[102:105] offset:55296
	ds_read_b128 v[156:159], v0 offset:36928
	ds_read_b128 v[160:163], v134 offset:64
	ds_read_b128 v[164:167], v0 offset:41536
	ds_read_b128 v[168:171], v134 offset:4672
	s_waitcnt lgkmcnt(8)
	v_mfma_f32_32x32x16_f16 v[50:65], v[172:175], v[176:179], v[50:65]
	s_waitcnt lgkmcnt(7)
	v_mfma_f32_32x32x16_f16 v[34:49], v[180:183], v[176:179], v[34:49]
	s_waitcnt vmcnt(5)
	ds_write_b128 v136, v[106:109] offset:23040
	s_waitcnt lgkmcnt(7)
	v_mfma_f32_32x32x16_f16 v[18:33], v[172:175], v[184:187], v[18:33]
	v_mfma_f32_32x32x16_f16 v[2:17], v[180:183], v[184:187], v[2:17]
	s_waitcnt vmcnt(4)
	ds_write_b128 v136, v[110:113] offset:59904
	ds_read_b128 v[172:175], v0 offset:36960
	ds_read_b128 v[176:179], v134 offset:96
	ds_read_b128 v[180:183], v0 offset:41568
	ds_read_b128 v[184:187], v134 offset:4704
	s_waitcnt lgkmcnt(8)
	v_mfma_f32_32x32x16_f16 v[50:65], v[156:159], v[160:163], v[50:65]
	s_waitcnt lgkmcnt(7)
	v_mfma_f32_32x32x16_f16 v[34:49], v[164:167], v[160:163], v[34:49]
	s_waitcnt vmcnt(3)
	ds_write_b128 v136, v[114:117] offset:27648
	s_waitcnt lgkmcnt(7)
	v_mfma_f32_32x32x16_f16 v[18:33], v[156:159], v[168:171], v[18:33]
	v_mfma_f32_32x32x16_f16 v[2:17], v[164:167], v[168:171], v[2:17]
	s_waitcnt vmcnt(2)
	ds_write_b128 v136, v[118:121] offset:64512
	s_waitcnt lgkmcnt(4)
	v_mfma_f32_32x32x16_f16 v[50:65], v[172:175], v[176:179], v[50:65]
	s_waitcnt lgkmcnt(3)
	v_mfma_f32_32x32x16_f16 v[34:49], v[180:183], v[176:179], v[34:49]
	s_waitcnt vmcnt(1)
	ds_write_b128 v136, v[122:125] offset:32256
	s_waitcnt lgkmcnt(3)
	v_mfma_f32_32x32x16_f16 v[18:33], v[172:175], v[184:187], v[18:33]
	v_mfma_f32_32x32x16_f16 v[2:17], v[180:183], v[184:187], v[2:17]
	s_waitcnt vmcnt(0)
	ds_write_b128 v137, v[126:129] offset:64512
	s_setprio 0
	s_waitcnt lgkmcnt(0)
	s_barrier
	s_setprio 1
	ds_read_b128 v[156:159], v0 offset:55296
	ds_read_b128 v[160:163], v134 offset:18432
	ds_read_b128 v[164:167], v0 offset:59904
	ds_read_b128 v[168:171], v134 offset:23040
	ds_read_b128 v[172:175], v0 offset:55328
	ds_read_b128 v[176:179], v134 offset:18464
	ds_read_b128 v[180:183], v0 offset:59936
	ds_read_b128 v[184:187], v134 offset:23072
	s_waitcnt lgkmcnt(6)
	v_mfma_f32_32x32x16_f16 v[50:65], v[156:159], v[160:163], v[50:65]
	s_waitcnt lgkmcnt(5)
	v_mfma_f32_32x32x16_f16 v[34:49], v[164:167], v[160:163], v[34:49]
	s_waitcnt lgkmcnt(4)
	v_mfma_f32_32x32x16_f16 v[18:33], v[156:159], v[168:171], v[18:33]
	v_mfma_f32_32x32x16_f16 v[2:17], v[164:167], v[168:171], v[2:17]
	ds_read_b128 v[156:159], v0 offset:55360
	ds_read_b128 v[160:163], v134 offset:18496
	ds_read_b128 v[164:167], v0 offset:59968
	ds_read_b128 v[168:171], v134 offset:23104
	s_waitcnt lgkmcnt(6)
	v_mfma_f32_32x32x16_f16 v[50:65], v[172:175], v[176:179], v[50:65]
	s_waitcnt lgkmcnt(5)
	v_mfma_f32_32x32x16_f16 v[34:49], v[180:183], v[176:179], v[34:49]
	s_waitcnt lgkmcnt(4)
	v_mfma_f32_32x32x16_f16 v[18:33], v[172:175], v[184:187], v[18:33]
	v_mfma_f32_32x32x16_f16 v[2:17], v[180:183], v[184:187], v[2:17]
	ds_read_b128 v[172:175], v0 offset:55392
	ds_read_b128 v[176:179], v134 offset:18528
	ds_read_b128 v[180:183], v0 offset:60000
	ds_read_b128 v[184:187], v134 offset:23136
	s_waitcnt lgkmcnt(6)
	v_mfma_f32_32x32x16_f16 v[50:65], v[156:159], v[160:163], v[50:65]
	s_waitcnt lgkmcnt(5)
	v_mfma_f32_32x32x16_f16 v[34:49], v[164:167], v[160:163], v[34:49]
	s_waitcnt lgkmcnt(4)
	v_mfma_f32_32x32x16_f16 v[18:33], v[156:159], v[168:171], v[18:33]
	v_mfma_f32_32x32x16_f16 v[2:17], v[164:167], v[168:171], v[2:17]
	s_waitcnt lgkmcnt(2)
	v_mfma_f32_32x32x16_f16 v[50:65], v[172:175], v[176:179], v[50:65]
	s_waitcnt lgkmcnt(1)
	v_mfma_f32_32x32x16_f16 v[34:49], v[180:183], v[176:179], v[34:49]
	s_waitcnt lgkmcnt(0)
	v_mfma_f32_32x32x16_f16 v[18:33], v[172:175], v[184:187], v[18:33]
	v_mfma_f32_32x32x16_f16 v[2:17], v[180:183], v[184:187], v[2:17]
	s_setprio 0
	s_lshl_b32 s16, s0, 7
	v_or_b32_e32 v83, s16, v131
	s_movk_i32 s1, 0x1ff
	v_cmp_lt_i32_e32 vcc, s1, v83
	v_mov_b32_e32 v68, 0x3e38aa3b
	v_mov_b64_e32 v[66:67], s[10:11]
	s_barrier
	s_and_saveexec_b64 s[14:15], vcc
	s_cbranch_execz .LBB0_230
	s_mov_b32 s1, 1.0
	s_cmpk_lt_u32 s16, 0x400
	s_mov_b64 s[16:17], s[8:9]
	s_cbranch_scc1 .LBB0_229
	s_and_b32 s16, s18, 0x3fffff80
	s_mov_b32 s1, 0x3e38aa3b
	s_cmpk_eq_i32 s16, 0x300
	s_mov_b64 s[16:17], s[6:7]
	s_cbranch_scc1 .LBB0_229
	s_cmp_lt_i32 s0, 32
	s_cbranch_scc1 .LBB0_224
	s_cmp_eq_u32 s0, 32
	s_cselect_b64 s[16:17], -1, 0
	s_cbranch_execz .LBB0_225
	s_branch .LBB0_226

; DI void phase1(const Params& p, int l, char* lds) {
;     ...
;   for (int tile = blockIdx.x; tile < 128 * 51; tile += gridDim.x) {
.LBB0_232:
	v_readlane_b32 s0, v253, 1
	v_readlane_b32 s1, v253, 2
	v_lshlrev_b32_e32 v66, 4, v209
	s_nop 4
	global_load_dwordx4 v[168:171], v66, s[0:1]
	v_add_u32_e32 v66, 0x1000, v66
	global_load_dwordx4 v[172:175], v66, s[0:1]
	v_add_u32_e32 v66, 0x1000, v66
	global_load_dwordx4 v[176:179], v66, s[0:1]
	v_add_u32_e32 v66, 0x1000, v66
	global_load_dwordx4 v[180:183], v66, s[0:1]
	v_add_u32_e32 v66, 0x1000, v66
	global_load_dwordx4 v[184:187], v66, s[0:1]
	v_add_u32_e32 v66, 0x1000, v66
	s_waitcnt vmcnt(0)
	s_mov_b32 s19, s25

; DI unsigned pk2(float a, float b) { f2_t v = {a, b}; bf2_t r = __builtin_convertvector(v, bf2_t); return __builtin_bit_cast(unsigned, r); }
; DI void phase4(const Params& p, int l, char* lds) {
;     ...
;   for (int tile = blockIdx.x; tile < 128 * 8; tile += gridDim.x) {
;     const int nt = tile & 7, mt = tile >> 3;
;     ...
; #pragma unroll
;     for (int mi = 0; mi < 2; ++mi) {
;       const size_t row = (size_t)mt * 128 + wm * 64 + mi * 32 + r;
; #pragma unroll
;       for (int ni = 0; ni < 2; ++ni)
; #pragma unroll
;         for (int a = 0; a < 4; ++a) {
;           const int col = nt * 128 + wn * 64 + ni * 32 + 8 * a + 4 * h;
;           uint2 o;
;           o.x = pk2(mg[mi][ni][4 * a], mg[mi][ni][4 * a + 1]);
;           o.y = pk2(mg[mi][ni][4 * a + 2], mg[mi][ni][4 * a + 3]);
;           *(uint2*)(p.z + row * ZS + col) = o;
;         }
;     }
.LBB0_1052:
	s_lshl_b32 s0, s17, 7
	s_and_b32 s4, s0, 0x380
	s_lshl_b32 s0, s2, 7
	v_readlane_b32 s80, v253, 12
	v_readlane_b32 s86, v253, 18
	v_readlane_b32 s87, v253, 19
	v_readlane_b32 s88, v253, 20
	v_readlane_b32 s89, v253, 21
	v_readlane_b32 s81, v253, 13
	v_readlane_b32 s82, v253, 14
	v_readlane_b32 s83, v253, 15
	v_readlane_b32 s84, v253, 16
	v_readlane_b32 s85, v253, 17
	v_readlane_b32 s90, v253, 22
	v_readlane_b32 s91, v253, 23
	v_readlane_b32 s92, v253, 24
	v_readlane_b32 s93, v253, 25
	v_readlane_b32 s94, v253, 26
	v_readlane_b32 s95, v253, 27
	v_and_b32_e32 v170, 63, v209
	v_lshrrev_b32_e32 v171, 3, v170
	v_and_b32_e32 v172, 7, v170
	v_lshrrev_b32_e32 v173, 7, v209
	v_lshl_add_u32 v173, v173, 6, v171
	v_add_u32_e32 v174, s0, v173
	v_mul_lo_u32 v174, v174, s75
	v_and_b32_e32 v175, 64, v209
	v_add_u32_e32 v175, s4, v175
	v_lshlrev_b32_e32 v175, 1, v175
	v_lshl_add_u32 v175, v172, 4, v175
	v_add_u32_e32 v174, v174, v175
	v_lshrrev_b32_e32 v176, 6, v209
	v_mul_u32_u24_e32 v177, 0x2400, v176
	v_lshrrev_b32_e32 v176, 1, v176
	v_mul_u32_u24_e32 v176, 0x4800, v176
	v_add_u32_e32 v177, v177, v176
	v_add_u32_e32 v177, 0x4800, v177
	v_and_b32_e32 v178, 31, v170
	v_lshrrev_b32_e32 v179, 5, v170
	v_mul_u32_u24_e32 v178, 0x90, v178
	v_lshl_add_u32 v178, v179, 3, v178
	v_add_u32_e32 v178, v178, v177
	v_mul_u32_u24_e32 v179, 0x90, v171
	v_lshl_add_u32 v179, v172, 4, v179
	v_add_u32_e32 v179, v179, v177
	v_cvt_pk_f16_f32 v2, v144, v145
	v_cvt_pk_f16_f32 v3, v146, v147
	v_cvt_pk_f16_f32 v4, v140, v141
	v_cvt_pk_f16_f32 v5, v142, v143
	v_cvt_pk_f16_f32 v6, v136, v137
	v_cvt_pk_f16_f32 v7, v138, v139
	v_cvt_pk_f16_f32 v8, v134, v135
	v_cvt_pk_f16_f32 v9, v132, v133
	v_cvt_pk_f16_f32 v10, v128, v129
	v_cvt_pk_f16_f32 v11, v130, v131
	v_cvt_pk_f16_f32 v12, v124, v125
	v_cvt_pk_f16_f32 v13, v126, v127
	v_cvt_pk_f16_f32 v14, v120, v121
	v_cvt_pk_f16_f32 v15, v122, v123
	v_cvt_pk_f16_f32 v16, v118, v119
	v_cvt_pk_f16_f32 v17, v116, v117
	v_cvt_pk_f16_f32 v18, v112, v113
	v_cvt_pk_f16_f32 v19, v114, v115
	v_cvt_pk_f16_f32 v20, v108, v109
	v_cvt_pk_f16_f32 v21, v110, v111
	v_cvt_pk_f16_f32 v22, v104, v105
	v_cvt_pk_f16_f32 v23, v106, v107
	v_cvt_pk_f16_f32 v24, v102, v103
	v_cvt_pk_f16_f32 v25, v100, v101
	v_cvt_pk_f16_f32 v26, v96, v97
	v_cvt_pk_f16_f32 v27, v98, v99
	v_cvt_pk_f16_f32 v28, v92, v93
	v_cvt_pk_f16_f32 v29, v94, v95
	v_cvt_pk_f16_f32 v30, v88, v89
	v_cvt_pk_f16_f32 v31, v90, v91
	v_cvt_pk_f16_f32 v32, v86, v87
	v_cvt_pk_f16_f32 v33, v84, v85
	ds_write_b64 v178, v[2:3]
	ds_write_b64 v178, v[4:5] offset:16
	ds_write_b64 v178, v[6:7] offset:32
	ds_write_b64 v178, v[8:9] offset:48
	ds_write_b64 v178, v[10:11] offset:64
	ds_write_b64 v178, v[12:13] offset:80
	ds_write_b64 v178, v[14:15] offset:96
	ds_write_b64 v178, v[16:17] offset:112
	ds_write_b64 v178, v[18:19] offset:4608
	ds_write_b64 v178, v[20:21] offset:4624
	ds_write_b64 v178, v[22:23] offset:4640
	ds_write_b64 v178, v[24:25] offset:4656
	ds_write_b64 v178, v[26:27] offset:4672
	ds_write_b64 v178, v[28:29] offset:4688
	ds_write_b64 v178, v[30:31] offset:4704
	ds_write_b64 v178, v[32:33] offset:4720
	s_waitcnt lgkmcnt(0)
	ds_read_b128 v[34:37], v179
	ds_read_b128 v[38:41], v179 offset:1152
	ds_read_b128 v[42:45], v179 offset:2304
	ds_read_b128 v[46:49], v179 offset:3456
	ds_read_b128 v[50:53], v179 offset:4608
	ds_read_b128 v[54:57], v179 offset:5760
	ds_read_b128 v[58:61], v179 offset:6912
	ds_read_b128 v[62:65], v179 offset:8064
	s_add_i32 s17, s17, s30
	s_add_i32 s16, s16, s55
	s_waitcnt lgkmcnt(7)
	global_store_dwordx4 v174, v[34:37], s[86:87]
	v_add_u32_e32 v174, 0x19800, v174
	s_waitcnt lgkmcnt(6)
	global_store_dwordx4 v174, v[38:41], s[86:87]
	v_add_u32_e32 v174, 0x19800, v174
	s_waitcnt lgkmcnt(5)
	global_store_dwordx4 v174, v[42:45], s[86:87]
	v_add_u32_e32 v174, 0x19800, v174
	s_waitcnt lgkmcnt(4)
	global_store_dwordx4 v174, v[46:49], s[86:87]
	v_add_u32_e32 v174, 0x19800, v174
	s_waitcnt lgkmcnt(3)
	global_store_dwordx4 v174, v[50:53], s[86:87]
	v_add_u32_e32 v174, 0x19800, v174
	s_waitcnt lgkmcnt(2)
	global_store_dwordx4 v174, v[54:57], s[86:87]
	v_add_u32_e32 v174, 0x19800, v174
	s_waitcnt lgkmcnt(1)
	global_store_dwordx4 v174, v[58:61], s[86:87]
	v_add_u32_e32 v174, 0x19800, v174
	s_waitcnt lgkmcnt(0)
	global_store_dwordx4 v174, v[62:65], s[86:87]
	s_cmpk_gt_i32 s17, 0x3ff
	s_cbranch_scc1 .LBB0_1060

; #define GEMM_GLOAD(P, kt_) { GEMM_GL1(P, 0, kt_) GEMM_GL1(P, 1, kt_) GEMM_GL1(P, 2, kt_) GEMM_GL1(P, 3, kt_) }
; #define GEMM_LSTORE(P, buf_) { GEMM_LS1(P, 0, buf_) GEMM_LS1(P, 1, buf_) GEMM_LS1(P, 2, buf_) GEMM_LS1(P, 3, buf_) }
; template <bool DEEP>
; DI void gemm_mainloop_t(const u16* __restrict__ Ag, int lda, const u16* __restrict__ Bg, int ldb, int K, char* ldsraw,
;                         f32x16 (&acc)[2][2], int akstep) {
;     ...
;   } else {
;     GEMM_GLOAD(x, 0);
;     GEMM_LSTORE(x, 0);
;     __syncthreads();
;     for (int kt = 0; kt < nk; kt += 2) {
;       GEMM_GLOAD(x, kt + 1);
;       GEMM_COMPUTE(0);
;       GEMM_LSTORE(x, 1);
;       __syncthreads();
; DI void phase4(const Params& p, int l, char* lds) {
;     ...
;       const int yoff = (n == 0) ? GA : ((n == 1) ? GB : ((n == 2) ? GC : GD));
;       gemm_mainloop_shallow(p.z + (size_t)mt * 128 * ZS + yoff, ZS, WBT(l) + ((size_t)n * 1024 + nt * 128) * 512, 512, 512, lds,
;                     acc);
.LBB0_1054:
	s_lshl_b64 s[8:9], s[8:9], 1
	v_mov_b32_e32 v36, v209
	s_add_u32 s8, s20, s8
	s_addc_u32 s9, s21, s9
	v_ashrrev_i32_e32 v34, 3, v36
	v_ashrrev_i32_e32 v35, 31, v34
	v_mov_b64_e32 v[26:27], s[8:9]
	v_lshlrev_b64 v[6:7], 10, v[34:35]
	v_and_b32_e32 v8, 7, v36
	v_add_u32_e32 v10, 32, v34
	v_mad_i64_i32 v[2:3], s[8:9], v34, s75, v[26:27]
	v_lshlrev_b32_e32 v0, 4, v36
	v_lshl_or_b32 v6, v8, 4, v6
	v_mad_i64_i32 v[10:11], s[8:9], v10, s75, v[26:27]
	v_and_b32_e32 v0, 0x70, v0
	v_lshl_add_u64 v[154:155], s[0:1], 0, v[6:7]
	s_mov_b32 s8, 0x8000
	v_lshl_add_u64 v[152:153], v[2:3], 0, v[0:1]
	v_lshl_add_u64 v[156:157], v[10:11], 0, v[0:1]
	v_add_co_u32_e32 v158, vcc, s8, v154
	v_add_u32_e32 v18, 64, v34
	global_load_dwordx4 v[2:5], v[152:153], off
	global_load_dwordx4 v[10:13], v[156:157], off
	v_addc_co_u32_e32 v159, vcc, 0, v155, vcc
	v_mad_i64_i32 v[18:19], s[8:9], v18, s75, v[26:27]
	v_add_u32_e32 v28, 0x60, v34
	global_load_dwordx4 v[6:9], v[154:155], off
	global_load_dwordx4 v[14:17], v[158:159], off
	v_lshl_add_u64 v[160:161], v[18:19], 0, v[0:1]
	v_add_co_u32_e32 v162, vcc, s59, v154
	v_mad_i64_i32 v[26:27], s[8:9], v28, s75, v[26:27]
	global_load_dwordx4 v[18:21], v[160:161], off
	v_addc_co_u32_e32 v163, vcc, 0, v155, vcc
	s_mov_b32 s8, 0x18000
	global_load_dwordx4 v[22:25], v[162:163], off
	v_lshl_add_u64 v[164:165], v[26:27], 0, v[0:1]
	v_add_co_u32_e32 v166, vcc, s8, v154
	global_load_dwordx4 v[26:29], v[164:165], off
	s_nop 0
	v_addc_co_u32_e32 v167, vcc, 0, v155, vcc
	global_load_dwordx4 v[30:33], v[166:167], off
	v_mad_u64_u32 v[150:151], s[8:9], v34, s76, v[0:1]
	v_and_b32_e32 v0, 31, v36
	v_add_u32_e32 v151, 0x1200, v150
	s_waitcnt vmcnt(7)
	ds_write_b128 v150, v[2:5]
	s_waitcnt vmcnt(5)
	ds_write_b128 v150, v[6:9] offset:36864
	ds_write_b128 v150, v[10:13] offset:4608
	s_waitcnt vmcnt(4)
	ds_write_b128 v150, v[14:17] offset:41472
	s_waitcnt vmcnt(3)
	ds_write_b128 v150, v[18:21] offset:9216
	s_waitcnt vmcnt(2)
	ds_write_b128 v150, v[22:25] offset:46080
	s_waitcnt vmcnt(1)
	ds_write_b128 v150, v[26:29] offset:13824
	s_waitcnt vmcnt(0)
	ds_write_b128 v150, v[30:33] offset:50688
	s_waitcnt lgkmcnt(0)
	s_barrier
	global_load_dwordx4 v[170:173], v[152:153], off offset:128
	global_load_dwordx4 v[174:177], v[154:155], off offset:128
	global_load_dwordx4 v[178:181], v[156:157], off offset:128
	global_load_dwordx4 v[182:185], v[158:159], off offset:128
	global_load_dwordx4 v[186:189], v[160:161], off offset:128
	global_load_dwordx4 v[190:193], v[162:163], off offset:128
	global_load_dwordx4 v[194:197], v[164:165], off offset:128
	global_load_dwordx4 v[198:201], v[166:167], off offset:128
	v_lshrrev_b32_e32 v2, 1, v36
	v_and_or_b32 v3, v2, s74, v0
	v_and_b32_e32 v0, 16, v2
	v_and_b32_e32 v2, 0x5f, v36
	v_mul_u32_u24_e32 v2, 0x48, v2
	v_mad_u64_u32 v[148:149], s[8:9], v3, s76, v[0:1]
	v_lshl_add_u32 v0, v2, 1, v0
	s_setprio 1
	ds_read_b128 v[2:5], v0 offset:36864
	ds_read_b128 v[6:9], v148
	ds_read_b128 v[10:13], v0 offset:41472
	s_waitcnt lgkmcnt(1)
	v_mfma_f32_32x32x16_f16 v[50:65], v[2:5], v[6:9], 0
	s_waitcnt lgkmcnt(0)
	v_mfma_f32_32x32x16_f16 v[34:49], v[10:13], v[6:9], 0
	ds_read_b128 v[6:9], v148 offset:4608
	ds_read_b128 v[202:205], v0 offset:36896
	ds_read_b128 v[212:215], v148 offset:32
	ds_read_b128 v[216:219], v0 offset:41504
	s_waitcnt lgkmcnt(3)
	v_mfma_f32_32x32x16_f16 v[18:33], v[2:5], v[6:9], 0
	v_mfma_f32_32x32x16_f16 v[2:17], v[10:13], v[6:9], 0
	s_waitcnt lgkmcnt(1)
	v_mfma_f32_32x32x16_f16 v[50:65], v[202:205], v[212:215], v[50:65]
	s_waitcnt lgkmcnt(0)
	v_mfma_f32_32x32x16_f16 v[34:49], v[216:219], v[212:215], v[34:49]
	ds_read_b128 v[212:215], v148 offset:4640
	s_waitcnt lgkmcnt(0)
	v_mfma_f32_32x32x16_f16 v[18:33], v[202:205], v[212:215], v[18:33]
	v_mfma_f32_32x32x16_f16 v[2:17], v[216:219], v[212:215], v[2:17]
	ds_read_b128 v[202:205], v0 offset:36928
	ds_read_b128 v[212:215], v148 offset:64
	ds_read_b128 v[216:219], v0 offset:41536
	s_waitcnt lgkmcnt(1)
	v_mfma_f32_32x32x16_f16 v[50:65], v[202:205], v[212:215], v[50:65]
	s_waitcnt lgkmcnt(0)
	v_mfma_f32_32x32x16_f16 v[34:49], v[216:219], v[212:215], v[34:49]
	ds_read_b128 v[212:215], v148 offset:4672
	s_waitcnt lgkmcnt(0)
	v_mfma_f32_32x32x16_f16 v[18:33], v[202:205], v[212:215], v[18:33]
	v_mfma_f32_32x32x16_f16 v[2:17], v[216:219], v[212:215], v[2:17]
	ds_read_b128 v[202:205], v0 offset:36960
	ds_read_b128 v[212:215], v148 offset:96
	ds_read_b128 v[216:219], v0 offset:41568
	s_waitcnt lgkmcnt(1)
	v_mfma_f32_32x32x16_f16 v[50:65], v[202:205], v[212:215], v[50:65]
	s_waitcnt lgkmcnt(0)
	v_mfma_f32_32x32x16_f16 v[34:49], v[216:219], v[212:215], v[34:49]
	ds_read_b128 v[212:215], v148 offset:4704
	s_waitcnt lgkmcnt(0)
	v_mfma_f32_32x32x16_f16 v[18:33], v[202:205], v[212:215], v[18:33]
	v_mfma_f32_32x32x16_f16 v[2:17], v[216:219], v[212:215], v[2:17]
	s_setprio 0
	s_waitcnt vmcnt(7)
	ds_write_b128 v150, v[170:173] offset:18432
	s_waitcnt vmcnt(6)
	ds_write_b128 v150, v[174:177] offset:55296
	s_waitcnt vmcnt(5)
	ds_write_b128 v150, v[178:181] offset:23040
	s_waitcnt vmcnt(4)
	ds_write_b128 v150, v[182:185] offset:59904
	s_waitcnt vmcnt(3)
	ds_write_b128 v150, v[186:189] offset:27648
	s_waitcnt vmcnt(2)
	ds_write_b128 v150, v[190:193] offset:64512
	s_waitcnt vmcnt(1)
	ds_write_b128 v150, v[194:197] offset:32256
	s_waitcnt vmcnt(0)
	ds_write_b128 v151, v[198:201] offset:64512
	s_waitcnt lgkmcnt(0)
	s_barrier
; #define GEMM_GLOAD(P, kt_) { GEMM_GL1(P, 0, kt_) GEMM_GL1(P, 1, kt_) GEMM_GL1(P, 2, kt_) GEMM_GL1(P, 3, kt_) }
; #define GEMM_LSTORE(P, buf_) { GEMM_LS1(P, 0, buf_) GEMM_LS1(P, 1, buf_) GEMM_LS1(P, 2, buf_) GEMM_LS1(P, 3, buf_) }
; template <bool DEEP>
; DI void gemm_mainloop_t(const u16* __restrict__ Ag, int lda, const u16* __restrict__ Bg, int ldb, int K, char* ldsraw,
;                         f32x16 (&acc)[2][2], int akstep) {
;     ...
;     for (int kt = 0; kt < nk; kt += 2) {
;       GEMM_GLOAD(x, kt + 1);
;       GEMM_COMPUTE(0);
;       GEMM_LSTORE(x, 1);
;       __syncthreads();
;       if (kt + 2 < nk) GEMM_GLOAD(x, kt + 2);
;       GEMM_COMPUTE(1);
;       if (kt + 2 < nk) GEMM_LSTORE(x, 0);
;       __syncthreads();
	global_load_dwordx4 v[170:173], v[152:153], off offset:256
	global_load_dwordx4 v[174:177], v[154:155], off offset:256
	global_load_dwordx4 v[178:181], v[156:157], off offset:256
	global_load_dwordx4 v[182:185], v[158:159], off offset:256
	global_load_dwordx4 v[186:189], v[160:161], off offset:256
	global_load_dwordx4 v[190:193], v[162:163], off offset:256
	global_load_dwordx4 v[194:197], v[164:165], off offset:256
	global_load_dwordx4 v[198:201], v[166:167], off offset:256
	s_setprio 1
	ds_read_b128 v[202:205], v0 offset:55296
	ds_read_b128 v[212:215], v148 offset:18432
	ds_read_b128 v[216:219], v0 offset:59904
	s_waitcnt lgkmcnt(1)
	v_mfma_f32_32x32x16_f16 v[50:65], v[202:205], v[212:215], v[50:65]
	s_waitcnt lgkmcnt(0)
	v_mfma_f32_32x32x16_f16 v[34:49], v[216:219], v[212:215], v[34:49]
	ds_read_b128 v[212:215], v148 offset:23040
	s_waitcnt lgkmcnt(0)
	v_mfma_f32_32x32x16_f16 v[18:33], v[202:205], v[212:215], v[18:33]
	v_mfma_f32_32x32x16_f16 v[2:17], v[216:219], v[212:215], v[2:17]
	ds_read_b128 v[202:205], v0 offset:55328
	ds_read_b128 v[212:215], v148 offset:18464
	ds_read_b128 v[216:219], v0 offset:59936
	s_waitcnt lgkmcnt(1)
	v_mfma_f32_32x32x16_f16 v[50:65], v[202:205], v[212:215], v[50:65]
	s_waitcnt lgkmcnt(0)
	v_mfma_f32_32x32x16_f16 v[34:49], v[216:219], v[212:215], v[34:49]
	ds_read_b128 v[212:215], v148 offset:23072
	s_waitcnt lgkmcnt(0)
	v_mfma_f32_32x32x16_f16 v[18:33], v[202:205], v[212:215], v[18:33]
	v_mfma_f32_32x32x16_f16 v[2:17], v[216:219], v[212:215], v[2:17]
	ds_read_b128 v[202:205], v0 offset:55360
	ds_read_b128 v[212:215], v148 offset:18496
	ds_read_b128 v[216:219], v0 offset:59968
	s_waitcnt lgkmcnt(1)
	v_mfma_f32_32x32x16_f16 v[50:65], v[202:205], v[212:215], v[50:65]
	s_waitcnt lgkmcnt(0)
	v_mfma_f32_32x32x16_f16 v[34:49], v[216:219], v[212:215], v[34:49]
	ds_read_b128 v[212:215], v148 offset:23104
	s_waitcnt lgkmcnt(0)
	v_mfma_f32_32x32x16_f16 v[18:33], v[202:205], v[212:215], v[18:33]
	v_mfma_f32_32x32x16_f16 v[2:17], v[216:219], v[212:215], v[2:17]
	ds_read_b128 v[202:205], v0 offset:55392
	ds_read_b128 v[212:215], v148 offset:18528
	ds_read_b128 v[216:219], v0 offset:60000
	s_waitcnt lgkmcnt(1)
	v_mfma_f32_32x32x16_f16 v[50:65], v[202:205], v[212:215], v[50:65]
	s_waitcnt lgkmcnt(0)
	v_mfma_f32_32x32x16_f16 v[34:49], v[216:219], v[212:215], v[34:49]
	ds_read_b128 v[212:215], v148 offset:23136
	s_waitcnt lgkmcnt(0)
	v_mfma_f32_32x32x16_f16 v[18:33], v[202:205], v[212:215], v[18:33]
	v_mfma_f32_32x32x16_f16 v[2:17], v[216:219], v[212:215], v[2:17]
	s_setprio 0
	s_waitcnt vmcnt(7)
	ds_write_b128 v150, v[170:173]
	s_waitcnt vmcnt(6)
	ds_write_b128 v150, v[174:177] offset:36864
	s_waitcnt vmcnt(5)
	ds_write_b128 v150, v[178:181] offset:4608
	s_waitcnt vmcnt(4)
	ds_write_b128 v150, v[182:185] offset:41472
	s_waitcnt vmcnt(3)
	ds_write_b128 v150, v[186:189] offset:9216
	s_waitcnt vmcnt(2)
	ds_write_b128 v150, v[190:193] offset:46080
	s_waitcnt vmcnt(1)
	ds_write_b128 v150, v[194:197] offset:13824
	s_waitcnt vmcnt(0)
	ds_write_b128 v150, v[198:201] offset:50688
	s_waitcnt lgkmcnt(0)
	s_barrier
	global_load_dwordx4 v[170:173], v[152:153], off offset:384
	global_load_dwordx4 v[174:177], v[154:155], off offset:384
	global_load_dwordx4 v[178:181], v[156:157], off offset:384
	global_load_dwordx4 v[182:185], v[158:159], off offset:384
	global_load_dwordx4 v[186:189], v[160:161], off offset:384
	global_load_dwordx4 v[190:193], v[162:163], off offset:384
	global_load_dwordx4 v[194:197], v[164:165], off offset:384
	global_load_dwordx4 v[198:201], v[166:167], off offset:384
	s_setprio 1
	ds_read_b128 v[202:205], v0 offset:36864
	ds_read_b128 v[212:215], v148
	ds_read_b128 v[216:219], v0 offset:41472
	s_waitcnt lgkmcnt(1)
	v_mfma_f32_32x32x16_f16 v[50:65], v[202:205], v[212:215], v[50:65]
	s_waitcnt lgkmcnt(0)
	v_mfma_f32_32x32x16_f16 v[34:49], v[216:219], v[212:215], v[34:49]
	ds_read_b128 v[212:215], v148 offset:4608
	s_waitcnt lgkmcnt(0)
	v_mfma_f32_32x32x16_f16 v[18:33], v[202:205], v[212:215], v[18:33]
	v_mfma_f32_32x32x16_f16 v[2:17], v[216:219], v[212:215], v[2:17]
	ds_read_b128 v[202:205], v0 offset:36896
	ds_read_b128 v[212:215], v148 offset:32
	ds_read_b128 v[216:219], v0 offset:41504
	s_waitcnt lgkmcnt(1)
	v_mfma_f32_32x32x16_f16 v[50:65], v[202:205], v[212:215], v[50:65]
	s_waitcnt lgkmcnt(0)
	v_mfma_f32_32x32x16_f16 v[34:49], v[216:219], v[212:215], v[34:49]
	ds_read_b128 v[212:215], v148 offset:4640
	s_waitcnt lgkmcnt(0)
	v_mfma_f32_32x32x16_f16 v[18:33], v[202:205], v[212:215], v[18:33]
	v_mfma_f32_32x32x16_f16 v[2:17], v[216:219], v[212:215], v[2:17]
	ds_read_b128 v[202:205], v0 offset:36928
	ds_read_b128 v[212:215], v148 offset:64
	ds_read_b128 v[216:219], v0 offset:41536
	s_waitcnt lgkmcnt(1)
	v_mfma_f32_32x32x16_f16 v[50:65], v[202:205], v[212:215], v[50:65]
	s_waitcnt lgkmcnt(0)
	v_mfma_f32_32x32x16_f16 v[34:49], v[216:219], v[212:215], v[34:49]
	ds_read_b128 v[212:215], v148 offset:4672
	s_waitcnt lgkmcnt(0)
	v_mfma_f32_32x32x16_f16 v[18:33], v[202:205], v[212:215], v[18:33]
	v_mfma_f32_32x32x16_f16 v[2:17], v[216:219], v[212:215], v[2:17]
	ds_read_b128 v[202:205], v0 offset:36960
	ds_read_b128 v[212:215], v148 offset:96
	ds_read_b128 v[216:219], v0 offset:41568
	s_waitcnt lgkmcnt(1)
	v_mfma_f32_32x32x16_f16 v[50:65], v[202:205], v[212:215], v[50:65]
	s_waitcnt lgkmcnt(0)
	v_mfma_f32_32x32x16_f16 v[34:49], v[216:219], v[212:215], v[34:49]
	ds_read_b128 v[212:215], v148 offset:4704
	s_waitcnt lgkmcnt(0)
	v_mfma_f32_32x32x16_f16 v[18:33], v[202:205], v[212:215], v[18:33]
	v_mfma_f32_32x32x16_f16 v[2:17], v[216:219], v[212:215], v[2:17]
	s_setprio 0
	s_waitcnt vmcnt(7)
	ds_write_b128 v150, v[170:173] offset:18432
	s_waitcnt vmcnt(6)
	ds_write_b128 v150, v[174:177] offset:55296
	s_waitcnt vmcnt(5)
	ds_write_b128 v150, v[178:181] offset:23040
	s_waitcnt vmcnt(4)
	ds_write_b128 v150, v[182:185] offset:59904
	s_waitcnt vmcnt(3)
	ds_write_b128 v150, v[186:189] offset:27648
	s_waitcnt vmcnt(2)
	ds_write_b128 v150, v[190:193] offset:64512
	s_waitcnt vmcnt(1)
	ds_write_b128 v150, v[194:197] offset:32256
	s_waitcnt vmcnt(0)
	ds_write_b128 v151, v[198:201] offset:64512
	s_waitcnt lgkmcnt(0)
	s_barrier
; #define GEMM_GLOAD(P, kt_) { GEMM_GL1(P, 0, kt_) GEMM_GL1(P, 1, kt_) GEMM_GL1(P, 2, kt_) GEMM_GL1(P, 3, kt_) }
; #define GEMM_LSTORE(P, buf_) { GEMM_LS1(P, 0, buf_) GEMM_LS1(P, 1, buf_) GEMM_LS1(P, 2, buf_) GEMM_LS1(P, 3, buf_) }
; template <bool DEEP>
; DI void gemm_mainloop_t(const u16* __restrict__ Ag, int lda, const u16* __restrict__ Bg, int ldb, int K, char* ldsraw,
;                         f32x16 (&acc)[2][2], int akstep) {
;     ...
;     for (int kt = 0; kt < nk; kt += 2) {
;       GEMM_GLOAD(x, kt + 1);
;       GEMM_COMPUTE(0);
;       GEMM_LSTORE(x, 1);
;       __syncthreads();
;       if (kt + 2 < nk) GEMM_GLOAD(x, kt + 2);
;       GEMM_COMPUTE(1);
;       if (kt + 2 < nk) GEMM_LSTORE(x, 0);
;       __syncthreads();
	global_load_dwordx4 v[170:173], v[152:153], off offset:512
	global_load_dwordx4 v[174:177], v[154:155], off offset:512
	global_load_dwordx4 v[178:181], v[156:157], off offset:512
	global_load_dwordx4 v[182:185], v[158:159], off offset:512
	global_load_dwordx4 v[186:189], v[160:161], off offset:512
	global_load_dwordx4 v[190:193], v[162:163], off offset:512
	global_load_dwordx4 v[194:197], v[164:165], off offset:512
	global_load_dwordx4 v[198:201], v[166:167], off offset:512
	s_setprio 1
	ds_read_b128 v[202:205], v0 offset:55296
	ds_read_b128 v[212:215], v148 offset:18432
	ds_read_b128 v[216:219], v0 offset:59904
	s_waitcnt lgkmcnt(1)
	v_mfma_f32_32x32x16_f16 v[50:65], v[202:205], v[212:215], v[50:65]
	s_waitcnt lgkmcnt(0)
	v_mfma_f32_32x32x16_f16 v[34:49], v[216:219], v[212:215], v[34:49]
	ds_read_b128 v[212:215], v148 offset:23040
	s_waitcnt lgkmcnt(0)
	v_mfma_f32_32x32x16_f16 v[18:33], v[202:205], v[212:215], v[18:33]
	v_mfma_f32_32x32x16_f16 v[2:17], v[216:219], v[212:215], v[2:17]
	ds_read_b128 v[202:205], v0 offset:55328
	ds_read_b128 v[212:215], v148 offset:18464
	ds_read_b128 v[216:219], v0 offset:59936
	s_waitcnt lgkmcnt(1)
	v_mfma_f32_32x32x16_f16 v[50:65], v[202:205], v[212:215], v[50:65]
	s_waitcnt lgkmcnt(0)
	v_mfma_f32_32x32x16_f16 v[34:49], v[216:219], v[212:215], v[34:49]
	ds_read_b128 v[212:215], v148 offset:23072
	s_waitcnt lgkmcnt(0)
	v_mfma_f32_32x32x16_f16 v[18:33], v[202:205], v[212:215], v[18:33]
	v_mfma_f32_32x32x16_f16 v[2:17], v[216:219], v[212:215], v[2:17]
	ds_read_b128 v[202:205], v0 offset:55360
	ds_read_b128 v[212:215], v148 offset:18496
	ds_read_b128 v[216:219], v0 offset:59968
	s_waitcnt lgkmcnt(1)
	v_mfma_f32_32x32x16_f16 v[50:65], v[202:205], v[212:215], v[50:65]
	s_waitcnt lgkmcnt(0)
	v_mfma_f32_32x32x16_f16 v[34:49], v[216:219], v[212:215], v[34:49]
	ds_read_b128 v[212:215], v148 offset:23104
	s_waitcnt lgkmcnt(0)
	v_mfma_f32_32x32x16_f16 v[18:33], v[202:205], v[212:215], v[18:33]
	v_mfma_f32_32x32x16_f16 v[2:17], v[216:219], v[212:215], v[2:17]
	ds_read_b128 v[202:205], v0 offset:55392
	ds_read_b128 v[212:215], v148 offset:18528
	ds_read_b128 v[216:219], v0 offset:60000
	s_waitcnt lgkmcnt(1)
	v_mfma_f32_32x32x16_f16 v[50:65], v[202:205], v[212:215], v[50:65]
	s_waitcnt lgkmcnt(0)
	v_mfma_f32_32x32x16_f16 v[34:49], v[216:219], v[212:215], v[34:49]
	ds_read_b128 v[212:215], v148 offset:23136
	s_waitcnt lgkmcnt(0)
	v_mfma_f32_32x32x16_f16 v[18:33], v[202:205], v[212:215], v[18:33]
	v_mfma_f32_32x32x16_f16 v[2:17], v[216:219], v[212:215], v[2:17]
	s_setprio 0
	s_waitcnt vmcnt(7)
	ds_write_b128 v150, v[170:173]
	s_waitcnt vmcnt(6)
	ds_write_b128 v150, v[174:177] offset:36864
	s_waitcnt vmcnt(5)
	ds_write_b128 v150, v[178:181] offset:4608
	s_waitcnt vmcnt(4)
	ds_write_b128 v150, v[182:185] offset:41472
	s_waitcnt vmcnt(3)
	ds_write_b128 v150, v[186:189] offset:9216
	s_waitcnt vmcnt(2)
	ds_write_b128 v150, v[190:193] offset:46080
	s_waitcnt vmcnt(1)
	ds_write_b128 v150, v[194:197] offset:13824
	s_waitcnt vmcnt(0)
	ds_write_b128 v150, v[198:201] offset:50688
	s_waitcnt lgkmcnt(0)
	s_barrier
	global_load_dwordx4 v[170:173], v[152:153], off offset:640
	global_load_dwordx4 v[174:177], v[154:155], off offset:640
	global_load_dwordx4 v[178:181], v[156:157], off offset:640
	global_load_dwordx4 v[182:185], v[158:159], off offset:640
	global_load_dwordx4 v[186:189], v[160:161], off offset:640
	global_load_dwordx4 v[190:193], v[162:163], off offset:640
	global_load_dwordx4 v[194:197], v[164:165], off offset:640
	global_load_dwordx4 v[198:201], v[166:167], off offset:640
	s_setprio 1
	ds_read_b128 v[202:205], v0 offset:36864
	ds_read_b128 v[212:215], v148
	ds_read_b128 v[216:219], v0 offset:41472
	s_waitcnt lgkmcnt(1)
	v_mfma_f32_32x32x16_f16 v[50:65], v[202:205], v[212:215], v[50:65]
	s_waitcnt lgkmcnt(0)
	v_mfma_f32_32x32x16_f16 v[34:49], v[216:219], v[212:215], v[34:49]
	ds_read_b128 v[212:215], v148 offset:4608
	s_waitcnt lgkmcnt(0)
	v_mfma_f32_32x32x16_f16 v[18:33], v[202:205], v[212:215], v[18:33]
	v_mfma_f32_32x32x16_f16 v[2:17], v[216:219], v[212:215], v[2:17]
	ds_read_b128 v[202:205], v0 offset:36896
	ds_read_b128 v[212:215], v148 offset:32
	ds_read_b128 v[216:219], v0 offset:41504
	s_waitcnt lgkmcnt(1)
	v_mfma_f32_32x32x16_f16 v[50:65], v[202:205], v[212:215], v[50:65]
	s_waitcnt lgkmcnt(0)
	v_mfma_f32_32x32x16_f16 v[34:49], v[216:219], v[212:215], v[34:49]
	ds_read_b128 v[212:215], v148 offset:4640
	s_waitcnt lgkmcnt(0)
	v_mfma_f32_32x32x16_f16 v[18:33], v[202:205], v[212:215], v[18:33]
	v_mfma_f32_32x32x16_f16 v[2:17], v[216:219], v[212:215], v[2:17]
	ds_read_b128 v[202:205], v0 offset:36928
	ds_read_b128 v[212:215], v148 offset:64
	ds_read_b128 v[216:219], v0 offset:41536
	s_waitcnt lgkmcnt(1)
	v_mfma_f32_32x32x16_f16 v[50:65], v[202:205], v[212:215], v[50:65]
	s_waitcnt lgkmcnt(0)
	v_mfma_f32_32x32x16_f16 v[34:49], v[216:219], v[212:215], v[34:49]
	ds_read_b128 v[212:215], v148 offset:4672
	s_waitcnt lgkmcnt(0)
	v_mfma_f32_32x32x16_f16 v[18:33], v[202:205], v[212:215], v[18:33]
	v_mfma_f32_32x32x16_f16 v[2:17], v[216:219], v[212:215], v[2:17]
	ds_read_b128 v[202:205], v0 offset:36960
	ds_read_b128 v[212:215], v148 offset:96
	ds_read_b128 v[216:219], v0 offset:41568
	s_waitcnt lgkmcnt(1)
	v_mfma_f32_32x32x16_f16 v[50:65], v[202:205], v[212:215], v[50:65]
	s_waitcnt lgkmcnt(0)
	v_mfma_f32_32x32x16_f16 v[34:49], v[216:219], v[212:215], v[34:49]
	ds_read_b128 v[212:215], v148 offset:4704
	s_waitcnt lgkmcnt(0)
	v_mfma_f32_32x32x16_f16 v[18:33], v[202:205], v[212:215], v[18:33]
	v_mfma_f32_32x32x16_f16 v[2:17], v[216:219], v[212:215], v[2:17]
	s_setprio 0
	s_waitcnt vmcnt(7)
	ds_write_b128 v150, v[170:173] offset:18432
	s_waitcnt vmcnt(6)
	ds_write_b128 v150, v[174:177] offset:55296
	s_waitcnt vmcnt(5)
	ds_write_b128 v150, v[178:181] offset:23040
	s_waitcnt vmcnt(4)
	ds_write_b128 v150, v[182:185] offset:59904
	s_waitcnt vmcnt(3)
	ds_write_b128 v150, v[186:189] offset:27648
	s_waitcnt vmcnt(2)
	ds_write_b128 v150, v[190:193] offset:64512
	s_waitcnt vmcnt(1)
	ds_write_b128 v150, v[194:197] offset:32256
	s_waitcnt vmcnt(0)
	ds_write_b128 v151, v[198:201] offset:64512
	s_waitcnt lgkmcnt(0)
	s_barrier
; #define GEMM_GLOAD(P, kt_) { GEMM_GL1(P, 0, kt_) GEMM_GL1(P, 1, kt_) GEMM_GL1(P, 2, kt_) GEMM_GL1(P, 3, kt_) }
; #define GEMM_LSTORE(P, buf_) { GEMM_LS1(P, 0, buf_) GEMM_LS1(P, 1, buf_) GEMM_LS1(P, 2, buf_) GEMM_LS1(P, 3, buf_) }
; template <bool DEEP>
; DI void gemm_mainloop_t(const u16* __restrict__ Ag, int lda, const u16* __restrict__ Bg, int ldb, int K, char* ldsraw,
;                         f32x16 (&acc)[2][2], int akstep) {
;     ...
;     for (int kt = 0; kt < nk; kt += 2) {
;       GEMM_GLOAD(x, kt + 1);
;       GEMM_COMPUTE(0);
;       GEMM_LSTORE(x, 1);
;       __syncthreads();
;       if (kt + 2 < nk) GEMM_GLOAD(x, kt + 2);
;       GEMM_COMPUTE(1);
;       if (kt + 2 < nk) GEMM_LSTORE(x, 0);
;       __syncthreads();
	global_load_dwordx4 v[170:173], v[152:153], off offset:768
	global_load_dwordx4 v[174:177], v[154:155], off offset:768
	global_load_dwordx4 v[178:181], v[156:157], off offset:768
	global_load_dwordx4 v[182:185], v[158:159], off offset:768
	global_load_dwordx4 v[186:189], v[160:161], off offset:768
	global_load_dwordx4 v[190:193], v[162:163], off offset:768
	global_load_dwordx4 v[194:197], v[164:165], off offset:768
	global_load_dwordx4 v[198:201], v[166:167], off offset:768
	s_setprio 1
	ds_read_b128 v[202:205], v0 offset:55296
	ds_read_b128 v[212:215], v148 offset:18432
	ds_read_b128 v[216:219], v0 offset:59904
	s_waitcnt lgkmcnt(1)
	v_mfma_f32_32x32x16_f16 v[50:65], v[202:205], v[212:215], v[50:65]
	s_waitcnt lgkmcnt(0)
	v_mfma_f32_32x32x16_f16 v[34:49], v[216:219], v[212:215], v[34:49]
	ds_read_b128 v[212:215], v148 offset:23040
	s_waitcnt lgkmcnt(0)
	v_mfma_f32_32x32x16_f16 v[18:33], v[202:205], v[212:215], v[18:33]
	v_mfma_f32_32x32x16_f16 v[2:17], v[216:219], v[212:215], v[2:17]
	ds_read_b128 v[202:205], v0 offset:55328
	ds_read_b128 v[212:215], v148 offset:18464
	ds_read_b128 v[216:219], v0 offset:59936
	s_waitcnt lgkmcnt(1)
	v_mfma_f32_32x32x16_f16 v[50:65], v[202:205], v[212:215], v[50:65]
	s_waitcnt lgkmcnt(0)
	v_mfma_f32_32x32x16_f16 v[34:49], v[216:219], v[212:215], v[34:49]
	ds_read_b128 v[212:215], v148 offset:23072
	s_waitcnt lgkmcnt(0)
	v_mfma_f32_32x32x16_f16 v[18:33], v[202:205], v[212:215], v[18:33]
	v_mfma_f32_32x32x16_f16 v[2:17], v[216:219], v[212:215], v[2:17]
	ds_read_b128 v[202:205], v0 offset:55360
	ds_read_b128 v[212:215], v148 offset:18496
	ds_read_b128 v[216:219], v0 offset:59968
	s_waitcnt lgkmcnt(1)
	v_mfma_f32_32x32x16_f16 v[50:65], v[202:205], v[212:215], v[50:65]
	s_waitcnt lgkmcnt(0)
	v_mfma_f32_32x32x16_f16 v[34:49], v[216:219], v[212:215], v[34:49]
	ds_read_b128 v[212:215], v148 offset:23104
	s_waitcnt lgkmcnt(0)
	v_mfma_f32_32x32x16_f16 v[18:33], v[202:205], v[212:215], v[18:33]
	v_mfma_f32_32x32x16_f16 v[2:17], v[216:219], v[212:215], v[2:17]
	ds_read_b128 v[202:205], v0 offset:55392
	ds_read_b128 v[212:215], v148 offset:18528
	ds_read_b128 v[216:219], v0 offset:60000
	s_waitcnt lgkmcnt(1)
	v_mfma_f32_32x32x16_f16 v[50:65], v[202:205], v[212:215], v[50:65]
	s_waitcnt lgkmcnt(0)
	v_mfma_f32_32x32x16_f16 v[34:49], v[216:219], v[212:215], v[34:49]
	ds_read_b128 v[212:215], v148 offset:23136
	s_waitcnt lgkmcnt(0)
	v_mfma_f32_32x32x16_f16 v[18:33], v[202:205], v[212:215], v[18:33]
	v_mfma_f32_32x32x16_f16 v[2:17], v[216:219], v[212:215], v[2:17]
	s_setprio 0
	s_waitcnt vmcnt(7)
	ds_write_b128 v150, v[170:173]
	s_waitcnt vmcnt(6)
	ds_write_b128 v150, v[174:177] offset:36864
	s_waitcnt vmcnt(5)
	ds_write_b128 v150, v[178:181] offset:4608
	s_waitcnt vmcnt(4)
	ds_write_b128 v150, v[182:185] offset:41472
	s_waitcnt vmcnt(3)
	ds_write_b128 v150, v[186:189] offset:9216
	s_waitcnt vmcnt(2)
	ds_write_b128 v150, v[190:193] offset:46080
	s_waitcnt vmcnt(1)
	ds_write_b128 v150, v[194:197] offset:13824
	s_waitcnt vmcnt(0)
	ds_write_b128 v150, v[198:201] offset:50688
	s_waitcnt lgkmcnt(0)
	s_barrier
	global_load_dwordx4 v[170:173], v[152:153], off offset:896
	s_nop 0
	global_load_dwordx4 v[152:155], v[154:155], off offset:896
	s_nop 0
	global_load_dwordx4 v[174:177], v[156:157], off offset:896
	s_nop 0
	global_load_dwordx4 v[156:159], v[158:159], off offset:896
	s_nop 0
	global_load_dwordx4 v[178:181], v[160:161], off offset:896
	s_nop 0
	global_load_dwordx4 v[160:163], v[162:163], off offset:896
	s_nop 0
	global_load_dwordx4 v[182:185], v[164:165], off offset:896
	s_nop 0
	global_load_dwordx4 v[164:167], v[166:167], off offset:896
	s_setprio 1
	ds_read_b128 v[186:189], v0 offset:36864
	ds_read_b128 v[190:193], v148
	ds_read_b128 v[194:197], v0 offset:41472
	s_waitcnt lgkmcnt(1)
	v_mfma_f32_32x32x16_f16 v[50:65], v[186:189], v[190:193], v[50:65]
	s_waitcnt lgkmcnt(0)
	v_mfma_f32_32x32x16_f16 v[34:49], v[194:197], v[190:193], v[34:49]
	ds_read_b128 v[190:193], v148 offset:4608
	s_waitcnt lgkmcnt(0)
	v_mfma_f32_32x32x16_f16 v[18:33], v[186:189], v[190:193], v[18:33]
	v_mfma_f32_32x32x16_f16 v[2:17], v[194:197], v[190:193], v[2:17]
	ds_read_b128 v[186:189], v0 offset:36896
	ds_read_b128 v[190:193], v148 offset:32
	ds_read_b128 v[194:197], v0 offset:41504
	s_waitcnt lgkmcnt(1)
	v_mfma_f32_32x32x16_f16 v[50:65], v[186:189], v[190:193], v[50:65]
	s_waitcnt lgkmcnt(0)
	v_mfma_f32_32x32x16_f16 v[34:49], v[194:197], v[190:193], v[34:49]
	ds_read_b128 v[190:193], v148 offset:4640
	s_waitcnt lgkmcnt(0)
	v_mfma_f32_32x32x16_f16 v[18:33], v[186:189], v[190:193], v[18:33]
	v_mfma_f32_32x32x16_f16 v[2:17], v[194:197], v[190:193], v[2:17]
	ds_read_b128 v[186:189], v0 offset:36928
	ds_read_b128 v[190:193], v148 offset:64
	ds_read_b128 v[194:197], v0 offset:41536
	s_waitcnt lgkmcnt(1)
	v_mfma_f32_32x32x16_f16 v[50:65], v[186:189], v[190:193], v[50:65]
	s_waitcnt lgkmcnt(0)
	v_mfma_f32_32x32x16_f16 v[34:49], v[194:197], v[190:193], v[34:49]
	ds_read_b128 v[190:193], v148 offset:4672
	s_waitcnt lgkmcnt(0)
	v_mfma_f32_32x32x16_f16 v[18:33], v[186:189], v[190:193], v[18:33]
	v_mfma_f32_32x32x16_f16 v[2:17], v[194:197], v[190:193], v[2:17]
	ds_read_b128 v[186:189], v0 offset:36960
	ds_read_b128 v[190:193], v148 offset:96
	ds_read_b128 v[194:197], v0 offset:41568
	s_waitcnt lgkmcnt(1)
	v_mfma_f32_32x32x16_f16 v[50:65], v[186:189], v[190:193], v[50:65]
	s_waitcnt lgkmcnt(0)
	v_mfma_f32_32x32x16_f16 v[34:49], v[194:197], v[190:193], v[34:49]
	ds_read_b128 v[190:193], v148 offset:4704
	s_waitcnt lgkmcnt(0)
	v_mfma_f32_32x32x16_f16 v[18:33], v[186:189], v[190:193], v[18:33]
	v_mfma_f32_32x32x16_f16 v[2:17], v[194:197], v[190:193], v[2:17]
	s_setprio 0
	s_waitcnt vmcnt(7)
	ds_write_b128 v150, v[170:173] offset:18432
	s_waitcnt vmcnt(6)
	ds_write_b128 v150, v[152:155] offset:55296
	s_waitcnt vmcnt(5)
	ds_write_b128 v150, v[174:177] offset:23040
	s_waitcnt vmcnt(4)
	ds_write_b128 v150, v[156:159] offset:59904
	s_waitcnt vmcnt(3)
	ds_write_b128 v150, v[178:181] offset:27648
	s_waitcnt vmcnt(2)
	ds_write_b128 v150, v[160:163] offset:64512
	s_waitcnt vmcnt(1)
	ds_write_b128 v150, v[182:185] offset:32256
	s_waitcnt vmcnt(0)
	ds_write_b128 v151, v[164:167] offset:64512
	s_waitcnt lgkmcnt(0)
	s_barrier
; template <bool DEEP>
; DI void gemm_mainloop_t(const u16* __restrict__ Ag, int lda, const u16* __restrict__ Bg, int ldb, int K, char* ldsraw,
;                         f32x16 (&acc)[2][2], int akstep) {
;     ...
;       GEMM_COMPUTE(1);
	s_setprio 1
	ds_read_b128 v[150:153], v0 offset:55296
	ds_read_b128 v[154:157], v148 offset:18432
	ds_read_b128 v[158:161], v0 offset:59904
	s_waitcnt lgkmcnt(1)
	v_mfma_f32_32x32x16_f16 v[50:65], v[150:153], v[154:157], v[50:65]
	s_waitcnt lgkmcnt(0)
	v_mfma_f32_32x32x16_f16 v[34:49], v[158:161], v[154:157], v[34:49]
	ds_read_b128 v[154:157], v148 offset:23040
	s_waitcnt lgkmcnt(0)
	v_mfma_f32_32x32x16_f16 v[18:33], v[150:153], v[154:157], v[18:33]
	v_mfma_f32_32x32x16_f16 v[2:17], v[158:161], v[154:157], v[2:17]
	ds_read_b128 v[150:153], v0 offset:55328
	ds_read_b128 v[154:157], v148 offset:18464
	ds_read_b128 v[158:161], v0 offset:59936
	s_waitcnt lgkmcnt(1)
	v_mfma_f32_32x32x16_f16 v[50:65], v[150:153], v[154:157], v[50:65]
	s_waitcnt lgkmcnt(0)
	v_mfma_f32_32x32x16_f16 v[34:49], v[158:161], v[154:157], v[34:49]
	ds_read_b128 v[154:157], v148 offset:23072
	s_waitcnt lgkmcnt(0)
	v_mfma_f32_32x32x16_f16 v[18:33], v[150:153], v[154:157], v[18:33]
	v_mfma_f32_32x32x16_f16 v[2:17], v[158:161], v[154:157], v[2:17]
	ds_read_b128 v[150:153], v0 offset:55360
	ds_read_b128 v[154:157], v148 offset:18496
	ds_read_b128 v[158:161], v0 offset:59968
	s_waitcnt lgkmcnt(1)
	v_mfma_f32_32x32x16_f16 v[50:65], v[150:153], v[154:157], v[50:65]
	s_waitcnt lgkmcnt(0)
	v_mfma_f32_32x32x16_f16 v[34:49], v[158:161], v[154:157], v[34:49]
	ds_read_b128 v[154:157], v148 offset:23104
	s_waitcnt lgkmcnt(0)
	v_mfma_f32_32x32x16_f16 v[18:33], v[150:153], v[154:157], v[18:33]
	v_mfma_f32_32x32x16_f16 v[2:17], v[158:161], v[154:157], v[2:17]
	ds_read_b128 v[150:153], v0 offset:55392
	ds_read_b128 v[154:157], v148 offset:18528
	ds_read_b128 v[158:161], v0 offset:60000
	s_waitcnt lgkmcnt(1)
	v_mfma_f32_32x32x16_f16 v[50:65], v[150:153], v[154:157], v[50:65]
	s_waitcnt lgkmcnt(0)
	v_mfma_f32_32x32x16_f16 v[34:49], v[158:161], v[154:157], v[34:49]
	ds_read_b128 v[154:157], v148 offset:23136
	s_waitcnt lgkmcnt(0)
	v_mfma_f32_32x32x16_f16 v[18:33], v[150:153], v[154:157], v[18:33]
	v_mfma_f32_32x32x16_f16 v[2:17], v[158:161], v[154:157], v[2:17]
	s_setprio 0
	s_barrier
; DI float bflo(unsigned u) { return (float)__builtin_bit_cast(bf2_t, u)[0]; }
; DI float bfhi(unsigned u) { return (float)__builtin_bit_cast(bf2_t, u)[1]; }
; DI void phase4(const Params& p, int l, char* lds) {
;     ...
; #pragma unroll
;       for (int a = 0; a < 2; ++a)
; #pragma unroll
;         for (int b = 0; b < 2; ++b)
; #pragma unroll
;           for (int i = 0; i < 2; ++i) {
;             const uint4 o = scr[((a * 2 + b) * 2 + i) * 256];
;             mg[a][b][8 * i] += bflo(o.x) * acc[a][b][8 * i];
;             mg[a][b][8 * i + 1] += bfhi(o.x) * acc[a][b][8 * i + 1];
;             mg[a][b][8 * i + 2] += bflo(o.y) * acc[a][b][8 * i + 2];
;             mg[a][b][8 * i + 3] += bfhi(o.y) * acc[a][b][8 * i + 3];
;             mg[a][b][8 * i + 4] += bflo(o.z) * acc[a][b][8 * i + 4];
;             mg[a][b][8 * i + 5] += bfhi(o.z) * acc[a][b][8 * i + 5];
;             mg[a][b][8 * i + 6] += bflo(o.w) * acc[a][b][8 * i + 6];
;             mg[a][b][8 * i + 7] += bfhi(o.w) * acc[a][b][8 * i + 7];
;           }
	global_load_dwordx4 v[170:173], v[68:69], off
	global_load_dwordx4 v[174:177], v[70:71], off
	global_load_dwordx4 v[178:181], v[72:73], off
	global_load_dwordx4 v[182:185], v[74:75], off
	global_load_dwordx4 v[186:189], v[76:77], off
	global_load_dwordx4 v[190:193], v[78:79], off
	global_load_dwordx4 v[194:197], v[80:81], off
	global_load_dwordx4 v[198:201], v[82:83], off
	s_add_i32 s22, s22, 1
	s_add_u32 s6, s6, 0x200000
	s_addc_u32 s7, s7, 0
	s_add_u32 s0, s0, 0x100000
	s_addc_u32 s1, s1, 0
	s_cmp_eq_u32 s6, 0x800000
	s_waitcnt vmcnt(7)
	v_cvt_f32_f16_sdwa v153, v170 dst_sel:DWORD dst_unused:UNUSED_PAD src0_sel:WORD_1
	v_cvt_f32_f16_e32 v152, v170
	v_pk_fma_f32 v[144:145], v[50:51], v[152:153], v[144:145]
	v_cvt_f32_f16_sdwa v51, v171 dst_sel:DWORD dst_unused:UNUSED_PAD src0_sel:WORD_1
	v_cvt_f32_f16_e32 v50, v171
	v_pk_fma_f32 v[146:147], v[52:53], v[50:51], v[146:147]
	v_cvt_f32_f16_sdwa v51, v172 dst_sel:DWORD dst_unused:UNUSED_PAD src0_sel:WORD_1
	v_cvt_f32_f16_e32 v50, v172
	v_pk_fma_f32 v[140:141], v[54:55], v[50:51], v[140:141]
	v_cvt_f32_f16_sdwa v51, v173 dst_sel:DWORD dst_unused:UNUSED_PAD src0_sel:WORD_1
	v_cvt_f32_f16_e32 v50, v173
	v_pk_fma_f32 v[142:143], v[56:57], v[50:51], v[142:143]
	s_waitcnt vmcnt(6)
	v_cvt_f32_f16_sdwa v55, v174 dst_sel:DWORD dst_unused:UNUSED_PAD src0_sel:WORD_1
	v_cvt_f32_f16_e32 v54, v174
	v_cvt_f32_f16_e32 v50, v176
	v_pk_fma_f32 v[136:137], v[58:59], v[54:55], v[136:137]
	v_cvt_f32_f16_sdwa v55, v175 dst_sel:DWORD dst_unused:UNUSED_PAD src0_sel:WORD_1
	v_cvt_f32_f16_e32 v54, v175
	v_cvt_f32_f16_sdwa v51, v176 dst_sel:DWORD dst_unused:UNUSED_PAD src0_sel:WORD_1
	v_pk_fma_f32 v[138:139], v[60:61], v[54:55], v[138:139]
	v_pk_fma_f32 v[134:135], v[62:63], v[50:51], v[134:135]
	v_cvt_f32_f16_sdwa v51, v177 dst_sel:DWORD dst_unused:UNUSED_PAD src0_sel:WORD_1
	v_cvt_f32_f16_e32 v50, v177
	v_pk_fma_f32 v[132:133], v[64:65], v[50:51], v[132:133]
	s_waitcnt vmcnt(5)
	v_cvt_f32_f16_sdwa v55, v178 dst_sel:DWORD dst_unused:UNUSED_PAD src0_sel:WORD_1
	v_cvt_f32_f16_e32 v54, v178
	v_pk_fma_f32 v[128:129], v[34:35], v[54:55], v[128:129]
	v_cvt_f32_f16_sdwa v35, v179 dst_sel:DWORD dst_unused:UNUSED_PAD src0_sel:WORD_1
	v_cvt_f32_f16_e32 v34, v179
	v_pk_fma_f32 v[130:131], v[36:37], v[34:35], v[130:131]
	v_cvt_f32_f16_sdwa v35, v180 dst_sel:DWORD dst_unused:UNUSED_PAD src0_sel:WORD_1
	v_cvt_f32_f16_e32 v34, v180
	v_pk_fma_f32 v[124:125], v[38:39], v[34:35], v[124:125]
	v_cvt_f32_f16_sdwa v35, v181 dst_sel:DWORD dst_unused:UNUSED_PAD src0_sel:WORD_1
	v_cvt_f32_f16_e32 v34, v181
	v_pk_fma_f32 v[126:127], v[40:41], v[34:35], v[126:127]
	s_waitcnt vmcnt(4)
	v_cvt_f32_f16_sdwa v39, v182 dst_sel:DWORD dst_unused:UNUSED_PAD src0_sel:WORD_1
	v_cvt_f32_f16_e32 v38, v182
	v_cvt_f32_f16_e32 v34, v184
	v_pk_fma_f32 v[120:121], v[42:43], v[38:39], v[120:121]
	v_cvt_f32_f16_sdwa v39, v183 dst_sel:DWORD dst_unused:UNUSED_PAD src0_sel:WORD_1
	v_cvt_f32_f16_e32 v38, v183
	v_cvt_f32_f16_sdwa v35, v184 dst_sel:DWORD dst_unused:UNUSED_PAD src0_sel:WORD_1
	v_pk_fma_f32 v[122:123], v[44:45], v[38:39], v[122:123]
	v_pk_fma_f32 v[118:119], v[46:47], v[34:35], v[118:119]
	v_cvt_f32_f16_sdwa v35, v185 dst_sel:DWORD dst_unused:UNUSED_PAD src0_sel:WORD_1
	v_cvt_f32_f16_e32 v34, v185
	v_pk_fma_f32 v[116:117], v[48:49], v[34:35], v[116:117]
	s_waitcnt vmcnt(3)
	v_cvt_f32_f16_sdwa v39, v186 dst_sel:DWORD dst_unused:UNUSED_PAD src0_sel:WORD_1
	v_cvt_f32_f16_e32 v38, v186
	v_pk_fma_f32 v[112:113], v[18:19], v[38:39], v[112:113]
	v_cvt_f32_f16_sdwa v19, v187 dst_sel:DWORD dst_unused:UNUSED_PAD src0_sel:WORD_1
	v_cvt_f32_f16_e32 v18, v187
	v_pk_fma_f32 v[114:115], v[20:21], v[18:19], v[114:115]
	v_cvt_f32_f16_sdwa v19, v188 dst_sel:DWORD dst_unused:UNUSED_PAD src0_sel:WORD_1
	v_cvt_f32_f16_e32 v18, v188
	v_pk_fma_f32 v[108:109], v[22:23], v[18:19], v[108:109]
	v_cvt_f32_f16_sdwa v19, v189 dst_sel:DWORD dst_unused:UNUSED_PAD src0_sel:WORD_1
	v_cvt_f32_f16_e32 v18, v189
	v_pk_fma_f32 v[110:111], v[24:25], v[18:19], v[110:111]
	s_waitcnt vmcnt(2)
	v_cvt_f32_f16_sdwa v23, v190 dst_sel:DWORD dst_unused:UNUSED_PAD src0_sel:WORD_1
	v_cvt_f32_f16_e32 v22, v190
	v_cvt_f32_f16_e32 v18, v192
	v_pk_fma_f32 v[104:105], v[26:27], v[22:23], v[104:105]
	v_cvt_f32_f16_sdwa v23, v191 dst_sel:DWORD dst_unused:UNUSED_PAD src0_sel:WORD_1
	v_cvt_f32_f16_e32 v22, v191
	v_cvt_f32_f16_sdwa v19, v192 dst_sel:DWORD dst_unused:UNUSED_PAD src0_sel:WORD_1
	v_pk_fma_f32 v[106:107], v[28:29], v[22:23], v[106:107]
	v_pk_fma_f32 v[102:103], v[30:31], v[18:19], v[102:103]
	v_cvt_f32_f16_sdwa v19, v193 dst_sel:DWORD dst_unused:UNUSED_PAD src0_sel:WORD_1
	v_cvt_f32_f16_e32 v18, v193
	v_pk_fma_f32 v[100:101], v[32:33], v[18:19], v[100:101]
	s_waitcnt vmcnt(1)
	v_cvt_f32_f16_sdwa v23, v194 dst_sel:DWORD dst_unused:UNUSED_PAD src0_sel:WORD_1
	v_cvt_f32_f16_e32 v22, v194
	v_pk_fma_f32 v[96:97], v[2:3], v[22:23], v[96:97]
	v_cvt_f32_f16_sdwa v3, v195 dst_sel:DWORD dst_unused:UNUSED_PAD src0_sel:WORD_1
	v_cvt_f32_f16_e32 v2, v195
	v_pk_fma_f32 v[98:99], v[4:5], v[2:3], v[98:99]
	v_cvt_f32_f16_sdwa v3, v196 dst_sel:DWORD dst_unused:UNUSED_PAD src0_sel:WORD_1
	v_cvt_f32_f16_e32 v2, v196
	v_pk_fma_f32 v[92:93], v[6:7], v[2:3], v[92:93]
	v_cvt_f32_f16_sdwa v3, v197 dst_sel:DWORD dst_unused:UNUSED_PAD src0_sel:WORD_1
	v_cvt_f32_f16_e32 v2, v197
	v_pk_fma_f32 v[94:95], v[8:9], v[2:3], v[94:95]
	s_waitcnt vmcnt(0)
	v_cvt_f32_f16_sdwa v7, v198 dst_sel:DWORD dst_unused:UNUSED_PAD src0_sel:WORD_1
	v_cvt_f32_f16_e32 v6, v198
	v_cvt_f32_f16_e32 v2, v200
	v_pk_fma_f32 v[88:89], v[10:11], v[6:7], v[88:89]
	v_cvt_f32_f16_sdwa v7, v199 dst_sel:DWORD dst_unused:UNUSED_PAD src0_sel:WORD_1
	v_cvt_f32_f16_e32 v6, v199
	v_cvt_f32_f16_sdwa v3, v200 dst_sel:DWORD dst_unused:UNUSED_PAD src0_sel:WORD_1
	v_pk_fma_f32 v[90:91], v[12:13], v[6:7], v[90:91]
	v_pk_fma_f32 v[86:87], v[14:15], v[2:3], v[86:87]
	v_cvt_f32_f16_sdwa v3, v201 dst_sel:DWORD dst_unused:UNUSED_PAD src0_sel:WORD_1
	v_cvt_f32_f16_e32 v2, v201
	v_pk_fma_f32 v[84:85], v[16:17], v[2:3], v[84:85]
	s_cbranch_scc1 .LBB0_1052

; DI int TID() { int t = threadIdx.x; asm volatile("" : "+v"(t)); return t; }
; #define GEMM_GLOAD(P, kt_) { GEMM_GL1(P, 0, kt_) GEMM_GL1(P, 1, kt_) GEMM_GL1(P, 2, kt_) GEMM_GL1(P, 3, kt_) }
; #define GEMM_LSTORE(P, buf_) { GEMM_LS1(P, 0, buf_) GEMM_LS1(P, 1, buf_) GEMM_LS1(P, 2, buf_) GEMM_LS1(P, 3, buf_) }
; template <bool DEEP>
; DI void gemm_mainloop_t(const u16* __restrict__ Ag, int lda, const u16* __restrict__ Bg, int ldb, int K, char* ldsraw,
;                         f32x16 (&acc)[2][2], int akstep) {
;     ...
;   if (DEEP) {
;     uint4 ya0, ya1, ya2, ya3, yb0, yb1, yb2, yb3;
;     GEMM_GLOAD(x, 0);
;     GEMM_GLOAD(y, 1);
;     GEMM_LSTORE(x, 0);
;     __syncthreads();
; DI void phase5(const Params& p, int l, const float* xin, float* xout, char* lds) {
;   const int tid = TID(), lane = tid & 63, w = tid >> 6, wm = w >> 1, wn = w & 1, r = lane & 31, h = lane >> 5;
;   for (int tile = blockIdx.x; tile < 128 * 8; tile += gridDim.x) {
;     const int nt = tile & 7, mt = tile >> 3;
;     f32x16 acc[2][2];
;     zero_acc(acc);
;     gemm_mainloop(p.z + (size_t)mt * 128 * ZS, ZS, WOT(l) + (size_t)nt * 128 * 1024, 1024, 1024, lds, acc);
.LBB0_1114:
	s_or_b64 exec, exec, s[0:1]
	v_readlane_b32 s0, v253, 3
	v_readlane_b32 s1, v253, 4
	v_mov_b32_e32 v0, v209
	s_and_b64 vcc, exec, s[0:1]
	s_waitcnt lgkmcnt(0)
	s_barrier
	s_cbranch_vccz .LBB0_1118
	s_mov_b32 s25, s19
	v_readlane_b32 s4, v251, 34
	v_readlane_b32 s8, v251, 38
	v_readlane_b32 s9, v251, 39
	v_readlane_b32 s10, v251, 40
	v_readlane_b32 s11, v251, 41
	v_readlane_b32 s12, v251, 42
	v_readlane_b32 s13, v251, 43
	v_readlane_b32 s14, v251, 44
	v_readlane_b32 s15, v251, 45
	v_readlane_b32 s16, v251, 46
	v_readlane_b32 s17, v251, 47
	v_readlane_b32 s18, v251, 48
	v_readlane_b32 s19, v251, 49
	v_readlane_b32 s0, v254, 14
	v_ashrrev_i32_e32 v2, 1, v0
	v_lshrrev_b32_e32 v4, 3, v0
	v_readlane_b32 s8, v253, 12
	v_readlane_b32 s1, v254, 15
	s_lshl_b32 s0, s0, 21
	v_and_b32_e32 v2, 0xffffffc0, v2
	v_and_b32_e32 v4, 4, v4
	v_readlane_b32 s12, v253, 16
	v_readlane_b32 s13, v253, 17
	v_readlane_b32 s5, v251, 35
	s_add_u32 s2, s4, s0
	v_ashrrev_i32_e32 v3, 31, v2
	v_and_or_b32 v2, v0, 31, v2
	v_and_or_b32 v0, v0, 64, v4
	v_readlane_b32 s0, v253, 36
	v_readlane_b32 s12, v254, 3
	s_addc_u32 s3, s5, 0
	v_lshlrev_b64 v[130:131], 10, v[2:3]
	v_lshlrev_b32_e32 v152, 2, v0
	s_mov_b32 s4, s0
	v_readlane_b32 s10, v253, 14
	v_readlane_b32 s11, v253, 15
	v_readlane_b32 s14, v253, 18
	v_readlane_b32 s15, v253, 19
	v_readlane_b32 s13, v254, 4
	v_readlane_b32 s6, v251, 36
	v_readlane_b32 s7, v251, 37
	v_readlane_b32 s1, v253, 37
	v_readlane_b32 s9, v253, 13
	v_readlane_b32 s16, v253, 20
	v_readlane_b32 s17, v253, 21
	v_readlane_b32 s18, v253, 22
	v_readlane_b32 s19, v253, 23
	v_readlane_b32 s20, v253, 24
	v_readlane_b32 s21, v253, 25
	v_readlane_b32 s22, v253, 26
	v_readlane_b32 s23, v253, 27
	v_readlane_b32 s6, v253, 1
	v_readlane_b32 s7, v253, 2
	v_lshlrev_b32_e32 v66, 4, v209
	s_nop 4
	global_store_dwordx4 v66, v[166:169], s[6:7]
	v_add_u32_e32 v66, 0x1000, v66
	global_store_dwordx4 v66, v[170:173], s[6:7]
	v_add_u32_e32 v66, 0x1000, v66
	global_store_dwordx4 v66, v[174:177], s[6:7]
	v_add_u32_e32 v66, 0x1000, v66
	global_store_dwordx4 v66, v[178:181], s[6:7]
	v_add_u32_e32 v66, 0x1000, v66
	global_store_dwordx4 v66, v[182:185], s[6:7]
	v_add_u32_e32 v66, 0x1000, v66
.LBB0_1116:
	s_ashr_i32 s0, s4, 3
	s_and_b32 s5, s4, 7
	s_ashr_i32 s1, s0, 31
	s_mul_i32 s6, s0, 0x198000
	s_waitcnt vmcnt(31)
	v_mov_b32_e32 v36, v209
	s_mul_hi_i32 s7, s0, 0x198000
	s_add_u32 s6, s14, s6
	s_addc_u32 s7, s15, s7
	v_ashrrev_i32_e32 v34, 3, v36
	s_lshl_b32 s8, s5, 18
	v_add_u32_e32 v14, 32, v34
	s_add_u32 s8, s2, s8
	v_ashrrev_i32_e32 v35, 31, v34
	v_mov_b64_e32 v[26:27], s[6:7]
	v_lshlrev_b32_e32 v0, 4, v36
	v_ashrrev_i32_e32 v15, 31, v14
	s_addc_u32 s9, s3, 0
	v_mad_i64_i32 v[2:3], s[6:7], v34, s75, v[26:27]
	v_and_b32_e32 v0, 0x70, v0
	v_lshlrev_b64 v[6:7], 11, v[34:35]
	v_mad_i64_i32 v[10:11], s[6:7], v14, s75, v[26:27]
	v_lshlrev_b64 v[14:15], 11, v[14:15]
	v_add_u32_e32 v22, 64, v34
	v_lshl_add_u64 v[136:137], v[2:3], 0, v[0:1]
	v_lshl_add_u64 v[6:7], s[8:9], 0, v[6:7]
	v_lshl_add_u64 v[140:141], v[10:11], 0, v[0:1]
	v_lshl_add_u64 v[14:15], s[8:9], 0, v[14:15]
	v_ashrrev_i32_e32 v23, 31, v22
	global_load_dwordx4 v[2:5], v[136:137], off
	v_lshl_add_u64 v[138:139], v[6:7], 0, v[0:1]
	global_load_dwordx4 v[10:13], v[140:141], off
	v_lshl_add_u64 v[142:143], v[14:15], 0, v[0:1]
	v_mad_i64_i32 v[18:19], s[6:7], v22, s75, v[26:27]
	v_lshlrev_b64 v[22:23], 11, v[22:23]
	global_load_dwordx4 v[6:9], v[138:139], off
	global_load_dwordx4 v[14:17], v[142:143], off
	v_lshl_add_u64 v[144:145], v[18:19], 0, v[0:1]
	v_lshl_add_u64 v[22:23], s[8:9], 0, v[22:23]
	v_add_u32_e32 v30, 0x60, v34
	global_load_dwordx4 v[18:21], v[144:145], off
	v_lshl_add_u64 v[146:147], v[22:23], 0, v[0:1]
	v_mad_i64_i32 v[26:27], s[6:7], v30, s75, v[26:27]
	global_load_dwordx4 v[22:25], v[146:147], off
	v_lshl_add_u64 v[148:149], v[26:27], 0, v[0:1]
	v_ashrrev_i32_e32 v31, 31, v30
	global_load_dwordx4 v[26:29], v[148:149], off
	v_lshlrev_b64 v[30:31], 11, v[30:31]
	v_lshl_add_u64 v[30:31], s[8:9], 0, v[30:31]
	v_lshl_add_u64 v[150:151], v[30:31], 0, v[0:1]
	global_load_dwordx4 v[30:33], v[150:151], off
	global_load_dwordx4 v[98:101], v[136:137], off offset:128
	global_load_dwordx4 v[102:105], v[138:139], off offset:128
	global_load_dwordx4 v[106:109], v[140:141], off offset:128
	global_load_dwordx4 v[110:113], v[142:143], off offset:128
	global_load_dwordx4 v[114:117], v[144:145], off offset:128
	global_load_dwordx4 v[118:121], v[146:147], off offset:128
	global_load_dwordx4 v[122:125], v[148:149], off offset:128
	global_load_dwordx4 v[126:129], v[150:151], off offset:128
	v_mad_u64_u32 v[134:135], s[6:7], v34, s76, v[0:1]
	v_and_b32_e32 v0, 31, v36
	v_add_u32_e32 v135, 0x1200, v134
	s_waitcnt vmcnt(15)
	ds_write_b128 v134, v[2:5]
	s_waitcnt vmcnt(13)
	ds_write_b128 v134, v[6:9] offset:36864
	ds_write_b128 v134, v[10:13] offset:4608
	s_waitcnt vmcnt(12)
	ds_write_b128 v134, v[14:17] offset:41472
	s_waitcnt vmcnt(11)
	ds_write_b128 v134, v[18:21] offset:9216
	s_waitcnt vmcnt(10)
	ds_write_b128 v134, v[22:25] offset:46080
	s_waitcnt vmcnt(9)
	ds_write_b128 v134, v[26:29] offset:13824
	s_waitcnt vmcnt(8)
	ds_write_b128 v134, v[30:33] offset:50688
	s_waitcnt lgkmcnt(0)
	s_barrier
; #define GEMM_GLOAD(P, kt_) { GEMM_GL1(P, 0, kt_) GEMM_GL1(P, 1, kt_) GEMM_GL1(P, 2, kt_) GEMM_GL1(P, 3, kt_) }
; #define GEMM_LSTORE(P, buf_) { GEMM_LS1(P, 0, buf_) GEMM_LS1(P, 1, buf_) GEMM_LS1(P, 2, buf_) GEMM_LS1(P, 3, buf_) }
; template <bool DEEP>
; DI void gemm_mainloop_t(const u16* __restrict__ Ag, int lda, const u16* __restrict__ Bg, int ldb, int K, char* ldsraw,
;                         f32x16 (&acc)[2][2], int akstep) {
;     ...
;     for (int kt = 0; kt < nk; kt += 2) {
;       if (kt + 2 < nk) GEMM_GLOAD(x, kt + 2);
;       GEMM_COMPUTE(0);
;       GEMM_LSTORE(y, 1);
;       __syncthreads();
;       if (kt + 3 < nk) GEMM_GLOAD(y, kt + 3);
;       GEMM_COMPUTE(1);
;       if (kt + 2 < nk) GEMM_LSTORE(x, 0);
;       __syncthreads();
	v_lshrrev_b32_e32 v2, 1, v36
	v_and_or_b32 v3, v2, s74, v0
	v_and_b32_e32 v0, 16, v2
	v_and_b32_e32 v2, 0x5f, v36
	v_mul_u32_u24_e32 v2, 0x48, v2
	v_mad_u64_u32 v[132:133], s[6:7], v3, s76, v[0:1]
	v_lshl_add_u32 v0, v2, 1, v0
	s_setprio 1
	ds_read_b128 v[154:157], v0 offset:36864
	ds_read_b128 v[158:161], v132
	ds_read_b128 v[162:165], v0 offset:41472
	ds_read_b128 v[166:169], v132 offset:4608
	ds_read_b128 v[170:173], v0 offset:36896
	ds_read_b128 v[174:177], v132 offset:32
	ds_read_b128 v[178:181], v0 offset:41504
	ds_read_b128 v[182:185], v132 offset:4640
	s_waitcnt lgkmcnt(6)
	v_mfma_f32_32x32x16_f16 v[50:65], v[154:157], v[158:161], 0
	global_load_dwordx4 v[66:69], v[136:137], off offset:256
	s_waitcnt lgkmcnt(5)
	v_mfma_f32_32x32x16_f16 v[34:49], v[162:165], v[158:161], 0
	s_waitcnt vmcnt(8)
	ds_write_b128 v134, v[98:101] offset:18432
	s_waitcnt lgkmcnt(5)
	v_mfma_f32_32x32x16_f16 v[18:33], v[154:157], v[166:169], 0
	global_load_dwordx4 v[70:73], v[138:139], off offset:256
	v_mfma_f32_32x32x16_f16 v[2:17], v[162:165], v[166:169], 0
	s_waitcnt vmcnt(8)
	ds_write_b128 v134, v[102:105] offset:55296
	ds_read_b128 v[154:157], v0 offset:36928
	ds_read_b128 v[158:161], v132 offset:64
	ds_read_b128 v[162:165], v0 offset:41536
	ds_read_b128 v[166:169], v132 offset:4672
	s_waitcnt lgkmcnt(8)
	v_mfma_f32_32x32x16_f16 v[50:65], v[170:173], v[174:177], v[50:65]
	global_load_dwordx4 v[74:77], v[140:141], off offset:256
	s_waitcnt lgkmcnt(7)
	v_mfma_f32_32x32x16_f16 v[34:49], v[178:181], v[174:177], v[34:49]
	s_waitcnt vmcnt(8)
	ds_write_b128 v134, v[106:109] offset:23040
	s_waitcnt lgkmcnt(7)
	v_mfma_f32_32x32x16_f16 v[18:33], v[170:173], v[182:185], v[18:33]
	global_load_dwordx4 v[78:81], v[142:143], off offset:256
	v_mfma_f32_32x32x16_f16 v[2:17], v[178:181], v[182:185], v[2:17]
	s_waitcnt vmcnt(8)
	ds_write_b128 v134, v[110:113] offset:59904
	ds_read_b128 v[170:173], v0 offset:36960
	ds_read_b128 v[174:177], v132 offset:96
	ds_read_b128 v[178:181], v0 offset:41568
	ds_read_b128 v[182:185], v132 offset:4704
	s_waitcnt lgkmcnt(8)
	v_mfma_f32_32x32x16_f16 v[50:65], v[154:157], v[158:161], v[50:65]
	global_load_dwordx4 v[82:85], v[144:145], off offset:256
	s_waitcnt lgkmcnt(7)
	v_mfma_f32_32x32x16_f16 v[34:49], v[162:165], v[158:161], v[34:49]
	s_waitcnt vmcnt(8)
	ds_write_b128 v134, v[114:117] offset:27648
	s_waitcnt lgkmcnt(7)
	v_mfma_f32_32x32x16_f16 v[18:33], v[154:157], v[166:169], v[18:33]
	global_load_dwordx4 v[86:89], v[146:147], off offset:256
	v_mfma_f32_32x32x16_f16 v[2:17], v[162:165], v[166:169], v[2:17]
	s_waitcnt vmcnt(8)
	ds_write_b128 v134, v[118:121] offset:64512
	s_waitcnt lgkmcnt(4)
	v_mfma_f32_32x32x16_f16 v[50:65], v[170:173], v[174:177], v[50:65]
	global_load_dwordx4 v[90:93], v[148:149], off offset:256
	s_waitcnt lgkmcnt(3)
	v_mfma_f32_32x32x16_f16 v[34:49], v[178:181], v[174:177], v[34:49]
	s_waitcnt vmcnt(8)
	ds_write_b128 v134, v[122:125] offset:32256
	s_waitcnt lgkmcnt(3)
	v_mfma_f32_32x32x16_f16 v[18:33], v[170:173], v[182:185], v[18:33]
	global_load_dwordx4 v[94:97], v[150:151], off offset:256
	v_mfma_f32_32x32x16_f16 v[2:17], v[178:181], v[182:185], v[2:17]
	s_waitcnt vmcnt(8)
	ds_write_b128 v135, v[126:129] offset:64512
	s_setprio 0
	s_waitcnt lgkmcnt(0)
	s_barrier
	s_setprio 1
	ds_read_b128 v[154:157], v0 offset:55296
	ds_read_b128 v[158:161], v132 offset:18432
	ds_read_b128 v[162:165], v0 offset:59904
	ds_read_b128 v[166:169], v132 offset:23040
	ds_read_b128 v[170:173], v0 offset:55328
	ds_read_b128 v[174:177], v132 offset:18464
	ds_read_b128 v[178:181], v0 offset:59936
	ds_read_b128 v[182:185], v132 offset:23072
	s_waitcnt lgkmcnt(6)
	v_mfma_f32_32x32x16_f16 v[50:65], v[154:157], v[158:161], v[50:65]
	global_load_dwordx4 v[98:101], v[136:137], off offset:384
	s_waitcnt lgkmcnt(5)
	v_mfma_f32_32x32x16_f16 v[34:49], v[162:165], v[158:161], v[34:49]
	s_waitcnt vmcnt(8)
	ds_write_b128 v134, v[66:69]
	s_waitcnt lgkmcnt(5)
	v_mfma_f32_32x32x16_f16 v[18:33], v[154:157], v[166:169], v[18:33]
	global_load_dwordx4 v[102:105], v[138:139], off offset:384
	v_mfma_f32_32x32x16_f16 v[2:17], v[162:165], v[166:169], v[2:17]
	s_waitcnt vmcnt(8)
	ds_write_b128 v134, v[70:73] offset:36864
	ds_read_b128 v[154:157], v0 offset:55360
	ds_read_b128 v[158:161], v132 offset:18496
	ds_read_b128 v[162:165], v0 offset:59968
	ds_read_b128 v[166:169], v132 offset:23104
	s_waitcnt lgkmcnt(8)
	v_mfma_f32_32x32x16_f16 v[50:65], v[170:173], v[174:177], v[50:65]
	global_load_dwordx4 v[106:109], v[140:141], off offset:384
	s_waitcnt lgkmcnt(7)
	v_mfma_f32_32x32x16_f16 v[34:49], v[178:181], v[174:177], v[34:49]
	s_waitcnt vmcnt(8)
	ds_write_b128 v134, v[74:77] offset:4608
	s_waitcnt lgkmcnt(7)
	v_mfma_f32_32x32x16_f16 v[18:33], v[170:173], v[182:185], v[18:33]
	global_load_dwordx4 v[110:113], v[142:143], off offset:384
	v_mfma_f32_32x32x16_f16 v[2:17], v[178:181], v[182:185], v[2:17]
	s_waitcnt vmcnt(8)
	ds_write_b128 v134, v[78:81] offset:41472
	ds_read_b128 v[170:173], v0 offset:55392
	ds_read_b128 v[174:177], v132 offset:18528
	ds_read_b128 v[178:181], v0 offset:60000
	ds_read_b128 v[182:185], v132 offset:23136
	s_waitcnt lgkmcnt(8)
	v_mfma_f32_32x32x16_f16 v[50:65], v[154:157], v[158:161], v[50:65]
	global_load_dwordx4 v[114:117], v[144:145], off offset:384
	s_waitcnt lgkmcnt(7)
	v_mfma_f32_32x32x16_f16 v[34:49], v[162:165], v[158:161], v[34:49]
	s_waitcnt vmcnt(8)
	ds_write_b128 v134, v[82:85] offset:9216
	s_waitcnt lgkmcnt(7)
	v_mfma_f32_32x32x16_f16 v[18:33], v[154:157], v[166:169], v[18:33]
	global_load_dwordx4 v[118:121], v[146:147], off offset:384
	v_mfma_f32_32x32x16_f16 v[2:17], v[162:165], v[166:169], v[2:17]
	s_waitcnt vmcnt(8)
	ds_write_b128 v134, v[86:89] offset:46080
	s_waitcnt lgkmcnt(4)
	v_mfma_f32_32x32x16_f16 v[50:65], v[170:173], v[174:177], v[50:65]
	global_load_dwordx4 v[122:125], v[148:149], off offset:384
	s_waitcnt lgkmcnt(3)
	v_mfma_f32_32x32x16_f16 v[34:49], v[178:181], v[174:177], v[34:49]
	s_waitcnt vmcnt(8)
	ds_write_b128 v134, v[90:93] offset:13824
	s_waitcnt lgkmcnt(3)
	v_mfma_f32_32x32x16_f16 v[18:33], v[170:173], v[182:185], v[18:33]
	global_load_dwordx4 v[126:129], v[150:151], off offset:384
	v_mfma_f32_32x32x16_f16 v[2:17], v[178:181], v[182:185], v[2:17]
	s_waitcnt vmcnt(8)
	ds_write_b128 v134, v[94:97] offset:50688
	s_setprio 0
	s_waitcnt lgkmcnt(0)
	s_barrier
; #define GEMM_GLOAD(P, kt_) { GEMM_GL1(P, 0, kt_) GEMM_GL1(P, 1, kt_) GEMM_GL1(P, 2, kt_) GEMM_GL1(P, 3, kt_) }
; #define GEMM_LSTORE(P, buf_) { GEMM_LS1(P, 0, buf_) GEMM_LS1(P, 1, buf_) GEMM_LS1(P, 2, buf_) GEMM_LS1(P, 3, buf_) }
; template <bool DEEP>
; DI void gemm_mainloop_t(const u16* __restrict__ Ag, int lda, const u16* __restrict__ Bg, int ldb, int K, char* ldsraw,
;                         f32x16 (&acc)[2][2], int akstep) {
;     ...
;     for (int kt = 0; kt < nk; kt += 2) {
;       if (kt + 2 < nk) GEMM_GLOAD(x, kt + 2);
;       GEMM_COMPUTE(0);
;       GEMM_LSTORE(y, 1);
;       __syncthreads();
;       if (kt + 3 < nk) GEMM_GLOAD(y, kt + 3);
;       GEMM_COMPUTE(1);
;       if (kt + 2 < nk) GEMM_LSTORE(x, 0);
;       __syncthreads();
	s_setprio 1
	ds_read_b128 v[154:157], v0 offset:36864
	ds_read_b128 v[158:161], v132
	ds_read_b128 v[162:165], v0 offset:41472
	ds_read_b128 v[166:169], v132 offset:4608
	ds_read_b128 v[170:173], v0 offset:36896
	ds_read_b128 v[174:177], v132 offset:32
	ds_read_b128 v[178:181], v0 offset:41504
	ds_read_b128 v[182:185], v132 offset:4640
	s_waitcnt lgkmcnt(6)
	v_mfma_f32_32x32x16_f16 v[50:65], v[154:157], v[158:161], v[50:65]
	global_load_dwordx4 v[66:69], v[136:137], off offset:512
	s_waitcnt lgkmcnt(5)
	v_mfma_f32_32x32x16_f16 v[34:49], v[162:165], v[158:161], v[34:49]
	s_waitcnt vmcnt(8)
	ds_write_b128 v134, v[98:101] offset:18432
	s_waitcnt lgkmcnt(5)
	v_mfma_f32_32x32x16_f16 v[18:33], v[154:157], v[166:169], v[18:33]
	global_load_dwordx4 v[70:73], v[138:139], off offset:512
	v_mfma_f32_32x32x16_f16 v[2:17], v[162:165], v[166:169], v[2:17]
	s_waitcnt vmcnt(8)
	ds_write_b128 v134, v[102:105] offset:55296
	ds_read_b128 v[154:157], v0 offset:36928
	ds_read_b128 v[158:161], v132 offset:64
	ds_read_b128 v[162:165], v0 offset:41536
	ds_read_b128 v[166:169], v132 offset:4672
	s_waitcnt lgkmcnt(8)
	v_mfma_f32_32x32x16_f16 v[50:65], v[170:173], v[174:177], v[50:65]
	global_load_dwordx4 v[74:77], v[140:141], off offset:512
	s_waitcnt lgkmcnt(7)
	v_mfma_f32_32x32x16_f16 v[34:49], v[178:181], v[174:177], v[34:49]
	s_waitcnt vmcnt(8)
	ds_write_b128 v134, v[106:109] offset:23040
	s_waitcnt lgkmcnt(7)
	v_mfma_f32_32x32x16_f16 v[18:33], v[170:173], v[182:185], v[18:33]
	global_load_dwordx4 v[78:81], v[142:143], off offset:512
	v_mfma_f32_32x32x16_f16 v[2:17], v[178:181], v[182:185], v[2:17]
	s_waitcnt vmcnt(8)
	ds_write_b128 v134, v[110:113] offset:59904
	ds_read_b128 v[170:173], v0 offset:36960
	ds_read_b128 v[174:177], v132 offset:96
	ds_read_b128 v[178:181], v0 offset:41568
	ds_read_b128 v[182:185], v132 offset:4704
	s_waitcnt lgkmcnt(8)
	v_mfma_f32_32x32x16_f16 v[50:65], v[154:157], v[158:161], v[50:65]
	global_load_dwordx4 v[82:85], v[144:145], off offset:512
	s_waitcnt lgkmcnt(7)
	v_mfma_f32_32x32x16_f16 v[34:49], v[162:165], v[158:161], v[34:49]
	s_waitcnt vmcnt(8)
	ds_write_b128 v134, v[114:117] offset:27648
	s_waitcnt lgkmcnt(7)
	v_mfma_f32_32x32x16_f16 v[18:33], v[154:157], v[166:169], v[18:33]
	global_load_dwordx4 v[86:89], v[146:147], off offset:512
	v_mfma_f32_32x32x16_f16 v[2:17], v[162:165], v[166:169], v[2:17]
	s_waitcnt vmcnt(8)
	ds_write_b128 v134, v[118:121] offset:64512
	s_waitcnt lgkmcnt(4)
	v_mfma_f32_32x32x16_f16 v[50:65], v[170:173], v[174:177], v[50:65]
	global_load_dwordx4 v[90:93], v[148:149], off offset:512
	s_waitcnt lgkmcnt(3)
	v_mfma_f32_32x32x16_f16 v[34:49], v[178:181], v[174:177], v[34:49]
	s_waitcnt vmcnt(8)
	ds_write_b128 v134, v[122:125] offset:32256
	s_waitcnt lgkmcnt(3)
	v_mfma_f32_32x32x16_f16 v[18:33], v[170:173], v[182:185], v[18:33]
	global_load_dwordx4 v[94:97], v[150:151], off offset:512
	v_mfma_f32_32x32x16_f16 v[2:17], v[178:181], v[182:185], v[2:17]
	s_waitcnt vmcnt(8)
	ds_write_b128 v135, v[126:129] offset:64512
	s_setprio 0
	s_waitcnt lgkmcnt(0)
	s_barrier
	s_setprio 1
	ds_read_b128 v[154:157], v0 offset:55296
	ds_read_b128 v[158:161], v132 offset:18432
	ds_read_b128 v[162:165], v0 offset:59904
	ds_read_b128 v[166:169], v132 offset:23040
	ds_read_b128 v[170:173], v0 offset:55328
	ds_read_b128 v[174:177], v132 offset:18464
	ds_read_b128 v[178:181], v0 offset:59936
	ds_read_b128 v[182:185], v132 offset:23072
	s_waitcnt lgkmcnt(6)
	v_mfma_f32_32x32x16_f16 v[50:65], v[154:157], v[158:161], v[50:65]
	global_load_dwordx4 v[98:101], v[136:137], off offset:640
	s_waitcnt lgkmcnt(5)
	v_mfma_f32_32x32x16_f16 v[34:49], v[162:165], v[158:161], v[34:49]
	s_waitcnt vmcnt(8)
	ds_write_b128 v134, v[66:69]
	s_waitcnt lgkmcnt(5)
	v_mfma_f32_32x32x16_f16 v[18:33], v[154:157], v[166:169], v[18:33]
	global_load_dwordx4 v[102:105], v[138:139], off offset:640
	v_mfma_f32_32x32x16_f16 v[2:17], v[162:165], v[166:169], v[2:17]
	s_waitcnt vmcnt(8)
	ds_write_b128 v134, v[70:73] offset:36864
	ds_read_b128 v[154:157], v0 offset:55360
	ds_read_b128 v[158:161], v132 offset:18496
	ds_read_b128 v[162:165], v0 offset:59968
	ds_read_b128 v[166:169], v132 offset:23104
	s_waitcnt lgkmcnt(8)
	v_mfma_f32_32x32x16_f16 v[50:65], v[170:173], v[174:177], v[50:65]
	global_load_dwordx4 v[106:109], v[140:141], off offset:640
	s_waitcnt lgkmcnt(7)
	v_mfma_f32_32x32x16_f16 v[34:49], v[178:181], v[174:177], v[34:49]
	s_waitcnt vmcnt(8)
	ds_write_b128 v134, v[74:77] offset:4608
	s_waitcnt lgkmcnt(7)
	v_mfma_f32_32x32x16_f16 v[18:33], v[170:173], v[182:185], v[18:33]
	global_load_dwordx4 v[110:113], v[142:143], off offset:640
	v_mfma_f32_32x32x16_f16 v[2:17], v[178:181], v[182:185], v[2:17]
	s_waitcnt vmcnt(8)
	ds_write_b128 v134, v[78:81] offset:41472
	ds_read_b128 v[170:173], v0 offset:55392
	ds_read_b128 v[174:177], v132 offset:18528
	ds_read_b128 v[178:181], v0 offset:60000
	ds_read_b128 v[182:185], v132 offset:23136
	s_waitcnt lgkmcnt(8)
	v_mfma_f32_32x32x16_f16 v[50:65], v[154:157], v[158:161], v[50:65]
	global_load_dwordx4 v[114:117], v[144:145], off offset:640
	s_waitcnt lgkmcnt(7)
	v_mfma_f32_32x32x16_f16 v[34:49], v[162:165], v[158:161], v[34:49]
	s_waitcnt vmcnt(8)
	ds_write_b128 v134, v[82:85] offset:9216
	s_waitcnt lgkmcnt(7)
	v_mfma_f32_32x32x16_f16 v[18:33], v[154:157], v[166:169], v[18:33]
	global_load_dwordx4 v[118:121], v[146:147], off offset:640
	v_mfma_f32_32x32x16_f16 v[2:17], v[162:165], v[166:169], v[2:17]
	s_waitcnt vmcnt(8)
	ds_write_b128 v134, v[86:89] offset:46080
	s_waitcnt lgkmcnt(4)
	v_mfma_f32_32x32x16_f16 v[50:65], v[170:173], v[174:177], v[50:65]
	global_load_dwordx4 v[122:125], v[148:149], off offset:640
	s_waitcnt lgkmcnt(3)
	v_mfma_f32_32x32x16_f16 v[34:49], v[178:181], v[174:177], v[34:49]
	s_waitcnt vmcnt(8)
	ds_write_b128 v134, v[90:93] offset:13824
	s_waitcnt lgkmcnt(3)
	v_mfma_f32_32x32x16_f16 v[18:33], v[170:173], v[182:185], v[18:33]
	global_load_dwordx4 v[126:129], v[150:151], off offset:640
	v_mfma_f32_32x32x16_f16 v[2:17], v[178:181], v[182:185], v[2:17]
	s_waitcnt vmcnt(8)
	ds_write_b128 v134, v[94:97] offset:50688
	s_setprio 0
	s_waitcnt lgkmcnt(0)
	s_barrier
; #define GEMM_GLOAD(P, kt_) { GEMM_GL1(P, 0, kt_) GEMM_GL1(P, 1, kt_) GEMM_GL1(P, 2, kt_) GEMM_GL1(P, 3, kt_) }
; #define GEMM_LSTORE(P, buf_) { GEMM_LS1(P, 0, buf_) GEMM_LS1(P, 1, buf_) GEMM_LS1(P, 2, buf_) GEMM_LS1(P, 3, buf_) }
; template <bool DEEP>
; DI void gemm_mainloop_t(const u16* __restrict__ Ag, int lda, const u16* __restrict__ Bg, int ldb, int K, char* ldsraw,
;                         f32x16 (&acc)[2][2], int akstep) {
;     ...
;     for (int kt = 0; kt < nk; kt += 2) {
;       if (kt + 2 < nk) GEMM_GLOAD(x, kt + 2);
;       GEMM_COMPUTE(0);
;       GEMM_LSTORE(y, 1);
;       __syncthreads();
;       if (kt + 3 < nk) GEMM_GLOAD(y, kt + 3);
;       GEMM_COMPUTE(1);
;       if (kt + 2 < nk) GEMM_LSTORE(x, 0);
;       __syncthreads();
	s_setprio 1
	ds_read_b128 v[154:157], v0 offset:36864
	ds_read_b128 v[158:161], v132
	ds_read_b128 v[162:165], v0 offset:41472
	ds_read_b128 v[166:169], v132 offset:4608
	ds_read_b128 v[170:173], v0 offset:36896
	ds_read_b128 v[174:177], v132 offset:32
	ds_read_b128 v[178:181], v0 offset:41504
	ds_read_b128 v[182:185], v132 offset:4640
	s_waitcnt lgkmcnt(6)
	v_mfma_f32_32x32x16_f16 v[50:65], v[154:157], v[158:161], v[50:65]
	global_load_dwordx4 v[66:69], v[136:137], off offset:768
	s_waitcnt lgkmcnt(5)
	v_mfma_f32_32x32x16_f16 v[34:49], v[162:165], v[158:161], v[34:49]
	s_waitcnt vmcnt(8)
	ds_write_b128 v134, v[98:101] offset:18432
	s_waitcnt lgkmcnt(5)
	v_mfma_f32_32x32x16_f16 v[18:33], v[154:157], v[166:169], v[18:33]
	global_load_dwordx4 v[70:73], v[138:139], off offset:768
	v_mfma_f32_32x32x16_f16 v[2:17], v[162:165], v[166:169], v[2:17]
	s_waitcnt vmcnt(8)
	ds_write_b128 v134, v[102:105] offset:55296
	ds_read_b128 v[154:157], v0 offset:36928
	ds_read_b128 v[158:161], v132 offset:64
	ds_read_b128 v[162:165], v0 offset:41536
	ds_read_b128 v[166:169], v132 offset:4672
	s_waitcnt lgkmcnt(8)
	v_mfma_f32_32x32x16_f16 v[50:65], v[170:173], v[174:177], v[50:65]
	global_load_dwordx4 v[74:77], v[140:141], off offset:768
	s_waitcnt lgkmcnt(7)
	v_mfma_f32_32x32x16_f16 v[34:49], v[178:181], v[174:177], v[34:49]
	s_waitcnt vmcnt(8)
	ds_write_b128 v134, v[106:109] offset:23040
	s_waitcnt lgkmcnt(7)
	v_mfma_f32_32x32x16_f16 v[18:33], v[170:173], v[182:185], v[18:33]
	global_load_dwordx4 v[78:81], v[142:143], off offset:768
	v_mfma_f32_32x32x16_f16 v[2:17], v[178:181], v[182:185], v[2:17]
	s_waitcnt vmcnt(8)
	ds_write_b128 v134, v[110:113] offset:59904
	ds_read_b128 v[170:173], v0 offset:36960
	ds_read_b128 v[174:177], v132 offset:96
	ds_read_b128 v[178:181], v0 offset:41568
	ds_read_b128 v[182:185], v132 offset:4704
	s_waitcnt lgkmcnt(8)
	v_mfma_f32_32x32x16_f16 v[50:65], v[154:157], v[158:161], v[50:65]
	global_load_dwordx4 v[82:85], v[144:145], off offset:768
	s_waitcnt lgkmcnt(7)
	v_mfma_f32_32x32x16_f16 v[34:49], v[162:165], v[158:161], v[34:49]
	s_waitcnt vmcnt(8)
	ds_write_b128 v134, v[114:117] offset:27648
	s_waitcnt lgkmcnt(7)
	v_mfma_f32_32x32x16_f16 v[18:33], v[154:157], v[166:169], v[18:33]
	global_load_dwordx4 v[86:89], v[146:147], off offset:768
	v_mfma_f32_32x32x16_f16 v[2:17], v[162:165], v[166:169], v[2:17]
	s_waitcnt vmcnt(8)
	ds_write_b128 v134, v[118:121] offset:64512
	s_waitcnt lgkmcnt(4)
	v_mfma_f32_32x32x16_f16 v[50:65], v[170:173], v[174:177], v[50:65]
	global_load_dwordx4 v[90:93], v[148:149], off offset:768
	s_waitcnt lgkmcnt(3)
	v_mfma_f32_32x32x16_f16 v[34:49], v[178:181], v[174:177], v[34:49]
	s_waitcnt vmcnt(8)
	ds_write_b128 v134, v[122:125] offset:32256
	s_waitcnt lgkmcnt(3)
	v_mfma_f32_32x32x16_f16 v[18:33], v[170:173], v[182:185], v[18:33]
	global_load_dwordx4 v[94:97], v[150:151], off offset:768
	v_mfma_f32_32x32x16_f16 v[2:17], v[178:181], v[182:185], v[2:17]
	s_waitcnt vmcnt(8)
	ds_write_b128 v135, v[126:129] offset:64512
	s_setprio 0
	s_waitcnt lgkmcnt(0)
	s_barrier
	s_setprio 1
	ds_read_b128 v[154:157], v0 offset:55296
	ds_read_b128 v[158:161], v132 offset:18432
	ds_read_b128 v[162:165], v0 offset:59904
	ds_read_b128 v[166:169], v132 offset:23040
	ds_read_b128 v[170:173], v0 offset:55328
	ds_read_b128 v[174:177], v132 offset:18464
	ds_read_b128 v[178:181], v0 offset:59936
	ds_read_b128 v[182:185], v132 offset:23072
	s_waitcnt lgkmcnt(6)
	v_mfma_f32_32x32x16_f16 v[50:65], v[154:157], v[158:161], v[50:65]
	global_load_dwordx4 v[98:101], v[136:137], off offset:896
	s_waitcnt lgkmcnt(5)
	v_mfma_f32_32x32x16_f16 v[34:49], v[162:165], v[158:161], v[34:49]
	s_waitcnt vmcnt(8)
	ds_write_b128 v134, v[66:69]
	s_waitcnt lgkmcnt(5)
	v_mfma_f32_32x32x16_f16 v[18:33], v[154:157], v[166:169], v[18:33]
	global_load_dwordx4 v[102:105], v[138:139], off offset:896
	v_mfma_f32_32x32x16_f16 v[2:17], v[162:165], v[166:169], v[2:17]
	s_waitcnt vmcnt(8)
	ds_write_b128 v134, v[70:73] offset:36864
	ds_read_b128 v[154:157], v0 offset:55360
	ds_read_b128 v[158:161], v132 offset:18496
	ds_read_b128 v[162:165], v0 offset:59968
	ds_read_b128 v[166:169], v132 offset:23104
	s_waitcnt lgkmcnt(8)
	v_mfma_f32_32x32x16_f16 v[50:65], v[170:173], v[174:177], v[50:65]
	global_load_dwordx4 v[106:109], v[140:141], off offset:896
	s_waitcnt lgkmcnt(7)
	v_mfma_f32_32x32x16_f16 v[34:49], v[178:181], v[174:177], v[34:49]
	s_waitcnt vmcnt(8)
	ds_write_b128 v134, v[74:77] offset:4608
	s_waitcnt lgkmcnt(7)
	v_mfma_f32_32x32x16_f16 v[18:33], v[170:173], v[182:185], v[18:33]
	global_load_dwordx4 v[110:113], v[142:143], off offset:896
	v_mfma_f32_32x32x16_f16 v[2:17], v[178:181], v[182:185], v[2:17]
	s_waitcnt vmcnt(8)
	ds_write_b128 v134, v[78:81] offset:41472
	ds_read_b128 v[170:173], v0 offset:55392
	ds_read_b128 v[174:177], v132 offset:18528
	ds_read_b128 v[178:181], v0 offset:60000
	ds_read_b128 v[182:185], v132 offset:23136
	s_waitcnt lgkmcnt(8)
	v_mfma_f32_32x32x16_f16 v[50:65], v[154:157], v[158:161], v[50:65]
	global_load_dwordx4 v[114:117], v[144:145], off offset:896
	s_waitcnt lgkmcnt(7)
	v_mfma_f32_32x32x16_f16 v[34:49], v[162:165], v[158:161], v[34:49]
	s_waitcnt vmcnt(8)
	ds_write_b128 v134, v[82:85] offset:9216
	s_waitcnt lgkmcnt(7)
	v_mfma_f32_32x32x16_f16 v[18:33], v[154:157], v[166:169], v[18:33]
	global_load_dwordx4 v[118:121], v[146:147], off offset:896
	v_mfma_f32_32x32x16_f16 v[2:17], v[162:165], v[166:169], v[2:17]
	s_waitcnt vmcnt(8)
	ds_write_b128 v134, v[86:89] offset:46080
	s_waitcnt lgkmcnt(4)
	v_mfma_f32_32x32x16_f16 v[50:65], v[170:173], v[174:177], v[50:65]
	global_load_dwordx4 v[122:125], v[148:149], off offset:896
	s_waitcnt lgkmcnt(3)
	v_mfma_f32_32x32x16_f16 v[34:49], v[178:181], v[174:177], v[34:49]
	s_waitcnt vmcnt(8)
	ds_write_b128 v134, v[90:93] offset:13824
	s_waitcnt lgkmcnt(3)
	v_mfma_f32_32x32x16_f16 v[18:33], v[170:173], v[182:185], v[18:33]
	global_load_dwordx4 v[126:129], v[150:151], off offset:896
	v_mfma_f32_32x32x16_f16 v[2:17], v[178:181], v[182:185], v[2:17]
	s_waitcnt vmcnt(8)
	ds_write_b128 v134, v[94:97] offset:50688
	s_setprio 0
	s_waitcnt lgkmcnt(0)
	s_barrier
; #define GEMM_GLOAD(P, kt_) { GEMM_GL1(P, 0, kt_) GEMM_GL1(P, 1, kt_) GEMM_GL1(P, 2, kt_) GEMM_GL1(P, 3, kt_) }
; #define GEMM_LSTORE(P, buf_) { GEMM_LS1(P, 0, buf_) GEMM_LS1(P, 1, buf_) GEMM_LS1(P, 2, buf_) GEMM_LS1(P, 3, buf_) }
; template <bool DEEP>
; DI void gemm_mainloop_t(const u16* __restrict__ Ag, int lda, const u16* __restrict__ Bg, int ldb, int K, char* ldsraw,
;                         f32x16 (&acc)[2][2], int akstep) {
;     ...
;     for (int kt = 0; kt < nk; kt += 2) {
;       if (kt + 2 < nk) GEMM_GLOAD(x, kt + 2);
;       GEMM_COMPUTE(0);
;       GEMM_LSTORE(y, 1);
;       __syncthreads();
;       if (kt + 3 < nk) GEMM_GLOAD(y, kt + 3);
;       GEMM_COMPUTE(1);
;       if (kt + 2 < nk) GEMM_LSTORE(x, 0);
;       __syncthreads();
	s_setprio 1
	ds_read_b128 v[154:157], v0 offset:36864
	ds_read_b128 v[158:161], v132
	ds_read_b128 v[162:165], v0 offset:41472
	ds_read_b128 v[166:169], v132 offset:4608
	ds_read_b128 v[170:173], v0 offset:36896
	ds_read_b128 v[174:177], v132 offset:32
	ds_read_b128 v[178:181], v0 offset:41504
	ds_read_b128 v[182:185], v132 offset:4640
	s_waitcnt lgkmcnt(6)
	v_mfma_f32_32x32x16_f16 v[50:65], v[154:157], v[158:161], v[50:65]
	global_load_dwordx4 v[66:69], v[136:137], off offset:1024
	s_waitcnt lgkmcnt(5)
	v_mfma_f32_32x32x16_f16 v[34:49], v[162:165], v[158:161], v[34:49]
	s_waitcnt vmcnt(8)
	ds_write_b128 v134, v[98:101] offset:18432
	s_waitcnt lgkmcnt(5)
	v_mfma_f32_32x32x16_f16 v[18:33], v[154:157], v[166:169], v[18:33]
	global_load_dwordx4 v[70:73], v[138:139], off offset:1024
	v_mfma_f32_32x32x16_f16 v[2:17], v[162:165], v[166:169], v[2:17]
	s_waitcnt vmcnt(8)
	ds_write_b128 v134, v[102:105] offset:55296
	ds_read_b128 v[154:157], v0 offset:36928
	ds_read_b128 v[158:161], v132 offset:64
	ds_read_b128 v[162:165], v0 offset:41536
	ds_read_b128 v[166:169], v132 offset:4672
	s_waitcnt lgkmcnt(8)
	v_mfma_f32_32x32x16_f16 v[50:65], v[170:173], v[174:177], v[50:65]
	global_load_dwordx4 v[74:77], v[140:141], off offset:1024
	s_waitcnt lgkmcnt(7)
	v_mfma_f32_32x32x16_f16 v[34:49], v[178:181], v[174:177], v[34:49]
	s_waitcnt vmcnt(8)
	ds_write_b128 v134, v[106:109] offset:23040
	s_waitcnt lgkmcnt(7)
	v_mfma_f32_32x32x16_f16 v[18:33], v[170:173], v[182:185], v[18:33]
	global_load_dwordx4 v[78:81], v[142:143], off offset:1024
	v_mfma_f32_32x32x16_f16 v[2:17], v[178:181], v[182:185], v[2:17]
	s_waitcnt vmcnt(8)
	ds_write_b128 v134, v[110:113] offset:59904
	ds_read_b128 v[170:173], v0 offset:36960
	ds_read_b128 v[174:177], v132 offset:96
	ds_read_b128 v[178:181], v0 offset:41568
	ds_read_b128 v[182:185], v132 offset:4704
	s_waitcnt lgkmcnt(8)
	v_mfma_f32_32x32x16_f16 v[50:65], v[154:157], v[158:161], v[50:65]
	global_load_dwordx4 v[82:85], v[144:145], off offset:1024
	s_waitcnt lgkmcnt(7)
	v_mfma_f32_32x32x16_f16 v[34:49], v[162:165], v[158:161], v[34:49]
	s_waitcnt vmcnt(8)
	ds_write_b128 v134, v[114:117] offset:27648
	s_waitcnt lgkmcnt(7)
	v_mfma_f32_32x32x16_f16 v[18:33], v[154:157], v[166:169], v[18:33]
	global_load_dwordx4 v[86:89], v[146:147], off offset:1024
	v_mfma_f32_32x32x16_f16 v[2:17], v[162:165], v[166:169], v[2:17]
	s_waitcnt vmcnt(8)
	ds_write_b128 v134, v[118:121] offset:64512
	s_waitcnt lgkmcnt(4)
	v_mfma_f32_32x32x16_f16 v[50:65], v[170:173], v[174:177], v[50:65]
	global_load_dwordx4 v[90:93], v[148:149], off offset:1024
	s_waitcnt lgkmcnt(3)
	v_mfma_f32_32x32x16_f16 v[34:49], v[178:181], v[174:177], v[34:49]
	s_waitcnt vmcnt(8)
	ds_write_b128 v134, v[122:125] offset:32256
	s_waitcnt lgkmcnt(3)
	v_mfma_f32_32x32x16_f16 v[18:33], v[170:173], v[182:185], v[18:33]
	global_load_dwordx4 v[94:97], v[150:151], off offset:1024
	v_mfma_f32_32x32x16_f16 v[2:17], v[178:181], v[182:185], v[2:17]
	s_waitcnt vmcnt(8)
	ds_write_b128 v135, v[126:129] offset:64512
	s_setprio 0
	s_waitcnt lgkmcnt(0)
	s_barrier
	s_setprio 1
	ds_read_b128 v[154:157], v0 offset:55296
	ds_read_b128 v[158:161], v132 offset:18432
	ds_read_b128 v[162:165], v0 offset:59904
	ds_read_b128 v[166:169], v132 offset:23040
	ds_read_b128 v[170:173], v0 offset:55328
	ds_read_b128 v[174:177], v132 offset:18464
	ds_read_b128 v[178:181], v0 offset:59936
	ds_read_b128 v[182:185], v132 offset:23072
	s_waitcnt lgkmcnt(6)
	v_mfma_f32_32x32x16_f16 v[50:65], v[154:157], v[158:161], v[50:65]
	global_load_dwordx4 v[98:101], v[136:137], off offset:1152
	s_waitcnt lgkmcnt(5)
	v_mfma_f32_32x32x16_f16 v[34:49], v[162:165], v[158:161], v[34:49]
	s_waitcnt vmcnt(8)
	ds_write_b128 v134, v[66:69]
	s_waitcnt lgkmcnt(5)
	v_mfma_f32_32x32x16_f16 v[18:33], v[154:157], v[166:169], v[18:33]
	global_load_dwordx4 v[102:105], v[138:139], off offset:1152
	v_mfma_f32_32x32x16_f16 v[2:17], v[162:165], v[166:169], v[2:17]
	s_waitcnt vmcnt(8)
	ds_write_b128 v134, v[70:73] offset:36864
	ds_read_b128 v[154:157], v0 offset:55360
	ds_read_b128 v[158:161], v132 offset:18496
	ds_read_b128 v[162:165], v0 offset:59968
	ds_read_b128 v[166:169], v132 offset:23104
	s_waitcnt lgkmcnt(8)
	v_mfma_f32_32x32x16_f16 v[50:65], v[170:173], v[174:177], v[50:65]
	global_load_dwordx4 v[106:109], v[140:141], off offset:1152
	s_waitcnt lgkmcnt(7)
	v_mfma_f32_32x32x16_f16 v[34:49], v[178:181], v[174:177], v[34:49]
	s_waitcnt vmcnt(8)
	ds_write_b128 v134, v[74:77] offset:4608
	s_waitcnt lgkmcnt(7)
	v_mfma_f32_32x32x16_f16 v[18:33], v[170:173], v[182:185], v[18:33]
	global_load_dwordx4 v[110:113], v[142:143], off offset:1152
	v_mfma_f32_32x32x16_f16 v[2:17], v[178:181], v[182:185], v[2:17]
	s_waitcnt vmcnt(8)
	ds_write_b128 v134, v[78:81] offset:41472
	ds_read_b128 v[170:173], v0 offset:55392
	ds_read_b128 v[174:177], v132 offset:18528
	ds_read_b128 v[178:181], v0 offset:60000
	ds_read_b128 v[182:185], v132 offset:23136
	s_waitcnt lgkmcnt(8)
	v_mfma_f32_32x32x16_f16 v[50:65], v[154:157], v[158:161], v[50:65]
	global_load_dwordx4 v[114:117], v[144:145], off offset:1152
	s_waitcnt lgkmcnt(7)
	v_mfma_f32_32x32x16_f16 v[34:49], v[162:165], v[158:161], v[34:49]
	s_waitcnt vmcnt(8)
	ds_write_b128 v134, v[82:85] offset:9216
	s_waitcnt lgkmcnt(7)
	v_mfma_f32_32x32x16_f16 v[18:33], v[154:157], v[166:169], v[18:33]
	global_load_dwordx4 v[118:121], v[146:147], off offset:1152
	v_mfma_f32_32x32x16_f16 v[2:17], v[162:165], v[166:169], v[2:17]
	s_waitcnt vmcnt(8)
	ds_write_b128 v134, v[86:89] offset:46080
	s_waitcnt lgkmcnt(4)
	v_mfma_f32_32x32x16_f16 v[50:65], v[170:173], v[174:177], v[50:65]
	global_load_dwordx4 v[122:125], v[148:149], off offset:1152
	s_waitcnt lgkmcnt(3)
	v_mfma_f32_32x32x16_f16 v[34:49], v[178:181], v[174:177], v[34:49]
	s_waitcnt vmcnt(8)
	ds_write_b128 v134, v[90:93] offset:13824
	s_waitcnt lgkmcnt(3)
	v_mfma_f32_32x32x16_f16 v[18:33], v[170:173], v[182:185], v[18:33]
	global_load_dwordx4 v[126:129], v[150:151], off offset:1152
	v_mfma_f32_32x32x16_f16 v[2:17], v[178:181], v[182:185], v[2:17]
	s_waitcnt vmcnt(8)
	ds_write_b128 v134, v[94:97] offset:50688
	s_setprio 0
	s_waitcnt lgkmcnt(0)
	s_barrier
; #define GEMM_GLOAD(P, kt_) { GEMM_GL1(P, 0, kt_) GEMM_GL1(P, 1, kt_) GEMM_GL1(P, 2, kt_) GEMM_GL1(P, 3, kt_) }
; #define GEMM_LSTORE(P, buf_) { GEMM_LS1(P, 0, buf_) GEMM_LS1(P, 1, buf_) GEMM_LS1(P, 2, buf_) GEMM_LS1(P, 3, buf_) }
; template <bool DEEP>
; DI void gemm_mainloop_t(const u16* __restrict__ Ag, int lda, const u16* __restrict__ Bg, int ldb, int K, char* ldsraw,
;                         f32x16 (&acc)[2][2], int akstep) {
;     ...
;     for (int kt = 0; kt < nk; kt += 2) {
;       if (kt + 2 < nk) GEMM_GLOAD(x, kt + 2);
;       GEMM_COMPUTE(0);
;       GEMM_LSTORE(y, 1);
;       __syncthreads();
;       if (kt + 3 < nk) GEMM_GLOAD(y, kt + 3);
;       GEMM_COMPUTE(1);
;       if (kt + 2 < nk) GEMM_LSTORE(x, 0);
;       __syncthreads();
	s_setprio 1
	ds_read_b128 v[154:157], v0 offset:36864
	ds_read_b128 v[158:161], v132
	ds_read_b128 v[162:165], v0 offset:41472
	ds_read_b128 v[166:169], v132 offset:4608
	ds_read_b128 v[170:173], v0 offset:36896
	ds_read_b128 v[174:177], v132 offset:32
	ds_read_b128 v[178:181], v0 offset:41504
	ds_read_b128 v[182:185], v132 offset:4640
	s_waitcnt lgkmcnt(6)
	v_mfma_f32_32x32x16_f16 v[50:65], v[154:157], v[158:161], v[50:65]
	global_load_dwordx4 v[66:69], v[136:137], off offset:1280
	s_waitcnt lgkmcnt(5)
	v_mfma_f32_32x32x16_f16 v[34:49], v[162:165], v[158:161], v[34:49]
	s_waitcnt vmcnt(8)
	ds_write_b128 v134, v[98:101] offset:18432
	s_waitcnt lgkmcnt(5)
	v_mfma_f32_32x32x16_f16 v[18:33], v[154:157], v[166:169], v[18:33]
	global_load_dwordx4 v[70:73], v[138:139], off offset:1280
	v_mfma_f32_32x32x16_f16 v[2:17], v[162:165], v[166:169], v[2:17]
	s_waitcnt vmcnt(8)
	ds_write_b128 v134, v[102:105] offset:55296
	ds_read_b128 v[154:157], v0 offset:36928
	ds_read_b128 v[158:161], v132 offset:64
	ds_read_b128 v[162:165], v0 offset:41536
	ds_read_b128 v[166:169], v132 offset:4672
	s_waitcnt lgkmcnt(8)
	v_mfma_f32_32x32x16_f16 v[50:65], v[170:173], v[174:177], v[50:65]
	global_load_dwordx4 v[74:77], v[140:141], off offset:1280
	s_waitcnt lgkmcnt(7)
	v_mfma_f32_32x32x16_f16 v[34:49], v[178:181], v[174:177], v[34:49]
	s_waitcnt vmcnt(8)
	ds_write_b128 v134, v[106:109] offset:23040
	s_waitcnt lgkmcnt(7)
	v_mfma_f32_32x32x16_f16 v[18:33], v[170:173], v[182:185], v[18:33]
	global_load_dwordx4 v[78:81], v[142:143], off offset:1280
	v_mfma_f32_32x32x16_f16 v[2:17], v[178:181], v[182:185], v[2:17]
	s_waitcnt vmcnt(8)
	ds_write_b128 v134, v[110:113] offset:59904
	ds_read_b128 v[170:173], v0 offset:36960
	ds_read_b128 v[174:177], v132 offset:96
	ds_read_b128 v[178:181], v0 offset:41568
	ds_read_b128 v[182:185], v132 offset:4704
	s_waitcnt lgkmcnt(8)
	v_mfma_f32_32x32x16_f16 v[50:65], v[154:157], v[158:161], v[50:65]
	global_load_dwordx4 v[82:85], v[144:145], off offset:1280
	s_waitcnt lgkmcnt(7)
	v_mfma_f32_32x32x16_f16 v[34:49], v[162:165], v[158:161], v[34:49]
	s_waitcnt vmcnt(8)
	ds_write_b128 v134, v[114:117] offset:27648
	s_waitcnt lgkmcnt(7)
	v_mfma_f32_32x32x16_f16 v[18:33], v[154:157], v[166:169], v[18:33]
	global_load_dwordx4 v[86:89], v[146:147], off offset:1280
	v_mfma_f32_32x32x16_f16 v[2:17], v[162:165], v[166:169], v[2:17]
	s_waitcnt vmcnt(8)
	ds_write_b128 v134, v[118:121] offset:64512
	s_waitcnt lgkmcnt(4)
	v_mfma_f32_32x32x16_f16 v[50:65], v[170:173], v[174:177], v[50:65]
	global_load_dwordx4 v[90:93], v[148:149], off offset:1280
	s_waitcnt lgkmcnt(3)
	v_mfma_f32_32x32x16_f16 v[34:49], v[178:181], v[174:177], v[34:49]
	s_waitcnt vmcnt(8)
	ds_write_b128 v134, v[122:125] offset:32256
	s_waitcnt lgkmcnt(3)
	v_mfma_f32_32x32x16_f16 v[18:33], v[170:173], v[182:185], v[18:33]
	global_load_dwordx4 v[94:97], v[150:151], off offset:1280
	v_mfma_f32_32x32x16_f16 v[2:17], v[178:181], v[182:185], v[2:17]
	s_waitcnt vmcnt(8)
	ds_write_b128 v135, v[126:129] offset:64512
	s_setprio 0
	s_waitcnt lgkmcnt(0)
	s_barrier
	s_setprio 1
	ds_read_b128 v[154:157], v0 offset:55296
	ds_read_b128 v[158:161], v132 offset:18432
	ds_read_b128 v[162:165], v0 offset:59904
	ds_read_b128 v[166:169], v132 offset:23040
	ds_read_b128 v[170:173], v0 offset:55328
	ds_read_b128 v[174:177], v132 offset:18464
	ds_read_b128 v[178:181], v0 offset:59936
	ds_read_b128 v[182:185], v132 offset:23072
	s_waitcnt lgkmcnt(6)
	v_mfma_f32_32x32x16_f16 v[50:65], v[154:157], v[158:161], v[50:65]
	global_load_dwordx4 v[98:101], v[136:137], off offset:1408
	s_waitcnt lgkmcnt(5)
	v_mfma_f32_32x32x16_f16 v[34:49], v[162:165], v[158:161], v[34:49]
	s_waitcnt vmcnt(8)
	ds_write_b128 v134, v[66:69]
	s_waitcnt lgkmcnt(5)
	v_mfma_f32_32x32x16_f16 v[18:33], v[154:157], v[166:169], v[18:33]
	global_load_dwordx4 v[102:105], v[138:139], off offset:1408
	v_mfma_f32_32x32x16_f16 v[2:17], v[162:165], v[166:169], v[2:17]
	s_waitcnt vmcnt(8)
	ds_write_b128 v134, v[70:73] offset:36864
	ds_read_b128 v[154:157], v0 offset:55360
	ds_read_b128 v[158:161], v132 offset:18496
	ds_read_b128 v[162:165], v0 offset:59968
	ds_read_b128 v[166:169], v132 offset:23104
	s_waitcnt lgkmcnt(8)
	v_mfma_f32_32x32x16_f16 v[50:65], v[170:173], v[174:177], v[50:65]
	global_load_dwordx4 v[106:109], v[140:141], off offset:1408
	s_waitcnt lgkmcnt(7)
	v_mfma_f32_32x32x16_f16 v[34:49], v[178:181], v[174:177], v[34:49]
	s_waitcnt vmcnt(8)
	ds_write_b128 v134, v[74:77] offset:4608
	s_waitcnt lgkmcnt(7)
	v_mfma_f32_32x32x16_f16 v[18:33], v[170:173], v[182:185], v[18:33]
	global_load_dwordx4 v[110:113], v[142:143], off offset:1408
	v_mfma_f32_32x32x16_f16 v[2:17], v[178:181], v[182:185], v[2:17]
	s_waitcnt vmcnt(8)
	ds_write_b128 v134, v[78:81] offset:41472
	ds_read_b128 v[170:173], v0 offset:55392
	ds_read_b128 v[174:177], v132 offset:18528
	ds_read_b128 v[178:181], v0 offset:60000
	ds_read_b128 v[182:185], v132 offset:23136
	s_waitcnt lgkmcnt(8)
	v_mfma_f32_32x32x16_f16 v[50:65], v[154:157], v[158:161], v[50:65]
	global_load_dwordx4 v[114:117], v[144:145], off offset:1408
	s_waitcnt lgkmcnt(7)
	v_mfma_f32_32x32x16_f16 v[34:49], v[162:165], v[158:161], v[34:49]
	s_waitcnt vmcnt(8)
	ds_write_b128 v134, v[82:85] offset:9216
	s_waitcnt lgkmcnt(7)
	v_mfma_f32_32x32x16_f16 v[18:33], v[154:157], v[166:169], v[18:33]
	global_load_dwordx4 v[118:121], v[146:147], off offset:1408
	v_mfma_f32_32x32x16_f16 v[2:17], v[162:165], v[166:169], v[2:17]
	s_waitcnt vmcnt(8)
	ds_write_b128 v134, v[86:89] offset:46080
	s_waitcnt lgkmcnt(4)
	v_mfma_f32_32x32x16_f16 v[50:65], v[170:173], v[174:177], v[50:65]
	global_load_dwordx4 v[122:125], v[148:149], off offset:1408
	s_waitcnt lgkmcnt(3)
	v_mfma_f32_32x32x16_f16 v[34:49], v[178:181], v[174:177], v[34:49]
	s_waitcnt vmcnt(8)
	ds_write_b128 v134, v[90:93] offset:13824
	s_waitcnt lgkmcnt(3)
	v_mfma_f32_32x32x16_f16 v[18:33], v[170:173], v[182:185], v[18:33]
	global_load_dwordx4 v[126:129], v[150:151], off offset:1408
	v_mfma_f32_32x32x16_f16 v[2:17], v[178:181], v[182:185], v[2:17]
	s_waitcnt vmcnt(8)
	ds_write_b128 v134, v[94:97] offset:50688
	s_setprio 0
	s_waitcnt lgkmcnt(0)
	s_barrier
; #define GEMM_GLOAD(P, kt_) { GEMM_GL1(P, 0, kt_) GEMM_GL1(P, 1, kt_) GEMM_GL1(P, 2, kt_) GEMM_GL1(P, 3, kt_) }
; #define GEMM_LSTORE(P, buf_) { GEMM_LS1(P, 0, buf_) GEMM_LS1(P, 1, buf_) GEMM_LS1(P, 2, buf_) GEMM_LS1(P, 3, buf_) }
; template <bool DEEP>
; DI void gemm_mainloop_t(const u16* __restrict__ Ag, int lda, const u16* __restrict__ Bg, int ldb, int K, char* ldsraw,
;                         f32x16 (&acc)[2][2], int akstep) {
;     ...
;     for (int kt = 0; kt < nk; kt += 2) {
;       if (kt + 2 < nk) GEMM_GLOAD(x, kt + 2);
;       GEMM_COMPUTE(0);
;       GEMM_LSTORE(y, 1);
;       __syncthreads();
;       if (kt + 3 < nk) GEMM_GLOAD(y, kt + 3);
;       GEMM_COMPUTE(1);
;       if (kt + 2 < nk) GEMM_LSTORE(x, 0);
;       __syncthreads();
	s_setprio 1
	ds_read_b128 v[154:157], v0 offset:36864
	ds_read_b128 v[158:161], v132
	ds_read_b128 v[162:165], v0 offset:41472
	ds_read_b128 v[166:169], v132 offset:4608
	ds_read_b128 v[170:173], v0 offset:36896
	ds_read_b128 v[174:177], v132 offset:32
	ds_read_b128 v[178:181], v0 offset:41504
	ds_read_b128 v[182:185], v132 offset:4640
	s_waitcnt lgkmcnt(6)
	v_mfma_f32_32x32x16_f16 v[50:65], v[154:157], v[158:161], v[50:65]
	global_load_dwordx4 v[66:69], v[136:137], off offset:1536
	s_waitcnt lgkmcnt(5)
	v_mfma_f32_32x32x16_f16 v[34:49], v[162:165], v[158:161], v[34:49]
	s_waitcnt vmcnt(8)
	ds_write_b128 v134, v[98:101] offset:18432
	s_waitcnt lgkmcnt(5)
	v_mfma_f32_32x32x16_f16 v[18:33], v[154:157], v[166:169], v[18:33]
	global_load_dwordx4 v[70:73], v[138:139], off offset:1536
	v_mfma_f32_32x32x16_f16 v[2:17], v[162:165], v[166:169], v[2:17]
	s_waitcnt vmcnt(8)
	ds_write_b128 v134, v[102:105] offset:55296
	ds_read_b128 v[154:157], v0 offset:36928
	ds_read_b128 v[158:161], v132 offset:64
	ds_read_b128 v[162:165], v0 offset:41536
	ds_read_b128 v[166:169], v132 offset:4672
	s_waitcnt lgkmcnt(8)
	v_mfma_f32_32x32x16_f16 v[50:65], v[170:173], v[174:177], v[50:65]
	global_load_dwordx4 v[74:77], v[140:141], off offset:1536
	s_waitcnt lgkmcnt(7)
	v_mfma_f32_32x32x16_f16 v[34:49], v[178:181], v[174:177], v[34:49]
	s_waitcnt vmcnt(8)
	ds_write_b128 v134, v[106:109] offset:23040
	s_waitcnt lgkmcnt(7)
	v_mfma_f32_32x32x16_f16 v[18:33], v[170:173], v[182:185], v[18:33]
	global_load_dwordx4 v[78:81], v[142:143], off offset:1536
	v_mfma_f32_32x32x16_f16 v[2:17], v[178:181], v[182:185], v[2:17]
	s_waitcnt vmcnt(8)
	ds_write_b128 v134, v[110:113] offset:59904
	ds_read_b128 v[170:173], v0 offset:36960
	ds_read_b128 v[174:177], v132 offset:96
	ds_read_b128 v[178:181], v0 offset:41568
	ds_read_b128 v[182:185], v132 offset:4704
	s_waitcnt lgkmcnt(8)
	v_mfma_f32_32x32x16_f16 v[50:65], v[154:157], v[158:161], v[50:65]
	global_load_dwordx4 v[82:85], v[144:145], off offset:1536
	s_waitcnt lgkmcnt(7)
	v_mfma_f32_32x32x16_f16 v[34:49], v[162:165], v[158:161], v[34:49]
	s_waitcnt vmcnt(8)
	ds_write_b128 v134, v[114:117] offset:27648
	s_waitcnt lgkmcnt(7)
	v_mfma_f32_32x32x16_f16 v[18:33], v[154:157], v[166:169], v[18:33]
	global_load_dwordx4 v[86:89], v[146:147], off offset:1536
	v_mfma_f32_32x32x16_f16 v[2:17], v[162:165], v[166:169], v[2:17]
	s_waitcnt vmcnt(8)
	ds_write_b128 v134, v[118:121] offset:64512
	s_waitcnt lgkmcnt(4)
	v_mfma_f32_32x32x16_f16 v[50:65], v[170:173], v[174:177], v[50:65]
	global_load_dwordx4 v[90:93], v[148:149], off offset:1536
	s_waitcnt lgkmcnt(3)
	v_mfma_f32_32x32x16_f16 v[34:49], v[178:181], v[174:177], v[34:49]
	s_waitcnt vmcnt(8)
	ds_write_b128 v134, v[122:125] offset:32256
	s_waitcnt lgkmcnt(3)
	v_mfma_f32_32x32x16_f16 v[18:33], v[170:173], v[182:185], v[18:33]
	global_load_dwordx4 v[94:97], v[150:151], off offset:1536
	v_mfma_f32_32x32x16_f16 v[2:17], v[178:181], v[182:185], v[2:17]
	s_waitcnt vmcnt(8)
	ds_write_b128 v135, v[126:129] offset:64512
	s_setprio 0
	s_waitcnt lgkmcnt(0)
	s_barrier
	s_setprio 1
	ds_read_b128 v[154:157], v0 offset:55296
	ds_read_b128 v[158:161], v132 offset:18432
	ds_read_b128 v[162:165], v0 offset:59904
	ds_read_b128 v[166:169], v132 offset:23040
	ds_read_b128 v[170:173], v0 offset:55328
	ds_read_b128 v[174:177], v132 offset:18464
	ds_read_b128 v[178:181], v0 offset:59936
	ds_read_b128 v[182:185], v132 offset:23072
	s_waitcnt lgkmcnt(6)
	v_mfma_f32_32x32x16_f16 v[50:65], v[154:157], v[158:161], v[50:65]
	global_load_dwordx4 v[98:101], v[136:137], off offset:1664
	s_waitcnt lgkmcnt(5)
	v_mfma_f32_32x32x16_f16 v[34:49], v[162:165], v[158:161], v[34:49]
	s_waitcnt vmcnt(8)
	ds_write_b128 v134, v[66:69]
	s_waitcnt lgkmcnt(5)
	v_mfma_f32_32x32x16_f16 v[18:33], v[154:157], v[166:169], v[18:33]
	global_load_dwordx4 v[102:105], v[138:139], off offset:1664
	v_mfma_f32_32x32x16_f16 v[2:17], v[162:165], v[166:169], v[2:17]
	s_waitcnt vmcnt(8)
	ds_write_b128 v134, v[70:73] offset:36864
	ds_read_b128 v[154:157], v0 offset:55360
	ds_read_b128 v[158:161], v132 offset:18496
	ds_read_b128 v[162:165], v0 offset:59968
	ds_read_b128 v[166:169], v132 offset:23104
	s_waitcnt lgkmcnt(8)
	v_mfma_f32_32x32x16_f16 v[50:65], v[170:173], v[174:177], v[50:65]
	global_load_dwordx4 v[106:109], v[140:141], off offset:1664
	s_waitcnt lgkmcnt(7)
	v_mfma_f32_32x32x16_f16 v[34:49], v[178:181], v[174:177], v[34:49]
	s_waitcnt vmcnt(8)
	ds_write_b128 v134, v[74:77] offset:4608
	s_waitcnt lgkmcnt(7)
	v_mfma_f32_32x32x16_f16 v[18:33], v[170:173], v[182:185], v[18:33]
	global_load_dwordx4 v[110:113], v[142:143], off offset:1664
	v_mfma_f32_32x32x16_f16 v[2:17], v[178:181], v[182:185], v[2:17]
	s_waitcnt vmcnt(8)
	ds_write_b128 v134, v[78:81] offset:41472
	ds_read_b128 v[170:173], v0 offset:55392
	ds_read_b128 v[174:177], v132 offset:18528
	ds_read_b128 v[178:181], v0 offset:60000
	ds_read_b128 v[182:185], v132 offset:23136
	s_waitcnt lgkmcnt(8)
	v_mfma_f32_32x32x16_f16 v[50:65], v[154:157], v[158:161], v[50:65]
	global_load_dwordx4 v[114:117], v[144:145], off offset:1664
	s_waitcnt lgkmcnt(7)
	v_mfma_f32_32x32x16_f16 v[34:49], v[162:165], v[158:161], v[34:49]
	s_waitcnt vmcnt(8)
	ds_write_b128 v134, v[82:85] offset:9216
	s_waitcnt lgkmcnt(7)
	v_mfma_f32_32x32x16_f16 v[18:33], v[154:157], v[166:169], v[18:33]
	global_load_dwordx4 v[118:121], v[146:147], off offset:1664
	v_mfma_f32_32x32x16_f16 v[2:17], v[162:165], v[166:169], v[2:17]
	s_waitcnt vmcnt(8)
	ds_write_b128 v134, v[86:89] offset:46080
	s_waitcnt lgkmcnt(4)
	v_mfma_f32_32x32x16_f16 v[50:65], v[170:173], v[174:177], v[50:65]
	global_load_dwordx4 v[122:125], v[148:149], off offset:1664
	s_waitcnt lgkmcnt(3)
	v_mfma_f32_32x32x16_f16 v[34:49], v[178:181], v[174:177], v[34:49]
	s_waitcnt vmcnt(8)
	ds_write_b128 v134, v[90:93] offset:13824
	s_waitcnt lgkmcnt(3)
	v_mfma_f32_32x32x16_f16 v[18:33], v[170:173], v[182:185], v[18:33]
	global_load_dwordx4 v[126:129], v[150:151], off offset:1664
	v_mfma_f32_32x32x16_f16 v[2:17], v[178:181], v[182:185], v[2:17]
	s_waitcnt vmcnt(8)
	ds_write_b128 v134, v[94:97] offset:50688
	s_setprio 0
	s_waitcnt lgkmcnt(0)
	s_barrier
; #define GEMM_GLOAD(P, kt_) { GEMM_GL1(P, 0, kt_) GEMM_GL1(P, 1, kt_) GEMM_GL1(P, 2, kt_) GEMM_GL1(P, 3, kt_) }
; #define GEMM_LSTORE(P, buf_) { GEMM_LS1(P, 0, buf_) GEMM_LS1(P, 1, buf_) GEMM_LS1(P, 2, buf_) GEMM_LS1(P, 3, buf_) }
; template <bool DEEP>
; DI void gemm_mainloop_t(const u16* __restrict__ Ag, int lda, const u16* __restrict__ Bg, int ldb, int K, char* ldsraw,
;                         f32x16 (&acc)[2][2], int akstep) {
;     ...
;     for (int kt = 0; kt < nk; kt += 2) {
;       if (kt + 2 < nk) GEMM_GLOAD(x, kt + 2);
;       GEMM_COMPUTE(0);
;       GEMM_LSTORE(y, 1);
;       __syncthreads();
;       if (kt + 3 < nk) GEMM_GLOAD(y, kt + 3);
;       GEMM_COMPUTE(1);
;       if (kt + 2 < nk) GEMM_LSTORE(x, 0);
;       __syncthreads();
	s_setprio 1
	ds_read_b128 v[154:157], v0 offset:36864
	ds_read_b128 v[158:161], v132
	ds_read_b128 v[162:165], v0 offset:41472
	ds_read_b128 v[166:169], v132 offset:4608
	ds_read_b128 v[170:173], v0 offset:36896
	ds_read_b128 v[174:177], v132 offset:32
	ds_read_b128 v[178:181], v0 offset:41504
	ds_read_b128 v[182:185], v132 offset:4640
	s_waitcnt lgkmcnt(6)
	v_mfma_f32_32x32x16_f16 v[50:65], v[154:157], v[158:161], v[50:65]
	global_load_dwordx4 v[66:69], v[136:137], off offset:1792
	s_waitcnt lgkmcnt(5)
	v_mfma_f32_32x32x16_f16 v[34:49], v[162:165], v[158:161], v[34:49]
	s_waitcnt vmcnt(8)
	ds_write_b128 v134, v[98:101] offset:18432
	s_waitcnt lgkmcnt(5)
	v_mfma_f32_32x32x16_f16 v[18:33], v[154:157], v[166:169], v[18:33]
	global_load_dwordx4 v[70:73], v[138:139], off offset:1792
	v_mfma_f32_32x32x16_f16 v[2:17], v[162:165], v[166:169], v[2:17]
	s_waitcnt vmcnt(8)
	ds_write_b128 v134, v[102:105] offset:55296
	ds_read_b128 v[154:157], v0 offset:36928
	ds_read_b128 v[158:161], v132 offset:64
	ds_read_b128 v[162:165], v0 offset:41536
	ds_read_b128 v[166:169], v132 offset:4672
	s_waitcnt lgkmcnt(8)
	v_mfma_f32_32x32x16_f16 v[50:65], v[170:173], v[174:177], v[50:65]
	global_load_dwordx4 v[74:77], v[140:141], off offset:1792
	s_waitcnt lgkmcnt(7)
	v_mfma_f32_32x32x16_f16 v[34:49], v[178:181], v[174:177], v[34:49]
	s_waitcnt vmcnt(8)
	ds_write_b128 v134, v[106:109] offset:23040
	s_waitcnt lgkmcnt(7)
	v_mfma_f32_32x32x16_f16 v[18:33], v[170:173], v[182:185], v[18:33]
	global_load_dwordx4 v[78:81], v[142:143], off offset:1792
	v_mfma_f32_32x32x16_f16 v[2:17], v[178:181], v[182:185], v[2:17]
	s_waitcnt vmcnt(8)
	ds_write_b128 v134, v[110:113] offset:59904
	ds_read_b128 v[170:173], v0 offset:36960
	ds_read_b128 v[174:177], v132 offset:96
	ds_read_b128 v[178:181], v0 offset:41568
	ds_read_b128 v[182:185], v132 offset:4704
	s_waitcnt lgkmcnt(8)
	v_mfma_f32_32x32x16_f16 v[50:65], v[154:157], v[158:161], v[50:65]
	global_load_dwordx4 v[82:85], v[144:145], off offset:1792
	s_waitcnt lgkmcnt(7)
	v_mfma_f32_32x32x16_f16 v[34:49], v[162:165], v[158:161], v[34:49]
	s_waitcnt vmcnt(8)
	ds_write_b128 v134, v[114:117] offset:27648
	s_waitcnt lgkmcnt(7)
	v_mfma_f32_32x32x16_f16 v[18:33], v[154:157], v[166:169], v[18:33]
	global_load_dwordx4 v[86:89], v[146:147], off offset:1792
	v_mfma_f32_32x32x16_f16 v[2:17], v[162:165], v[166:169], v[2:17]
	s_waitcnt vmcnt(8)
	ds_write_b128 v134, v[118:121] offset:64512
	s_waitcnt lgkmcnt(4)
	v_mfma_f32_32x32x16_f16 v[50:65], v[170:173], v[174:177], v[50:65]
	global_load_dwordx4 v[90:93], v[148:149], off offset:1792
	s_waitcnt lgkmcnt(3)
	v_mfma_f32_32x32x16_f16 v[34:49], v[178:181], v[174:177], v[34:49]
	s_waitcnt vmcnt(8)
	ds_write_b128 v134, v[122:125] offset:32256
	s_waitcnt lgkmcnt(3)
	v_mfma_f32_32x32x16_f16 v[18:33], v[170:173], v[182:185], v[18:33]
	global_load_dwordx4 v[94:97], v[150:151], off offset:1792
	v_mfma_f32_32x32x16_f16 v[2:17], v[178:181], v[182:185], v[2:17]
	s_waitcnt vmcnt(8)
	ds_write_b128 v135, v[126:129] offset:64512
	s_setprio 0
	s_waitcnt lgkmcnt(0)
	s_barrier
	global_load_dwordx4 v[98:101], v[136:137], off offset:1920
	global_load_dwordx4 v[102:105], v[138:139], off offset:1920
	global_load_dwordx4 v[106:109], v[140:141], off offset:1920
	global_load_dwordx4 v[110:113], v[142:143], off offset:1920
	global_load_dwordx4 v[114:117], v[144:145], off offset:1920
	global_load_dwordx4 v[118:121], v[146:147], off offset:1920
	global_load_dwordx4 v[122:125], v[148:149], off offset:1920
	global_load_dwordx4 v[126:129], v[150:151], off offset:1920
	s_setprio 1
	ds_read_b128 v[154:157], v0 offset:55296
	ds_read_b128 v[158:161], v132 offset:18432
	ds_read_b128 v[162:165], v0 offset:59904
	ds_read_b128 v[166:169], v132 offset:23040
	ds_read_b128 v[170:173], v0 offset:55328
	ds_read_b128 v[174:177], v132 offset:18464
	ds_read_b128 v[178:181], v0 offset:59936
	ds_read_b128 v[182:185], v132 offset:23072
	s_waitcnt lgkmcnt(6)
	v_mfma_f32_32x32x16_f16 v[50:65], v[154:157], v[158:161], v[50:65]
	s_waitcnt lgkmcnt(5)
	v_mfma_f32_32x32x16_f16 v[34:49], v[162:165], v[158:161], v[34:49]
	s_waitcnt vmcnt(15)
	ds_write_b128 v134, v[66:69]
	s_waitcnt lgkmcnt(5)
	v_mfma_f32_32x32x16_f16 v[18:33], v[154:157], v[166:169], v[18:33]
	v_mfma_f32_32x32x16_f16 v[2:17], v[162:165], v[166:169], v[2:17]
	s_waitcnt vmcnt(14)
	ds_write_b128 v134, v[70:73] offset:36864
	ds_read_b128 v[154:157], v0 offset:55360
	ds_read_b128 v[158:161], v132 offset:18496
	ds_read_b128 v[162:165], v0 offset:59968
	ds_read_b128 v[166:169], v132 offset:23104
	s_waitcnt lgkmcnt(8)
	v_mfma_f32_32x32x16_f16 v[50:65], v[170:173], v[174:177], v[50:65]
	s_waitcnt lgkmcnt(7)
	v_mfma_f32_32x32x16_f16 v[34:49], v[178:181], v[174:177], v[34:49]
	s_waitcnt vmcnt(13)
	ds_write_b128 v134, v[74:77] offset:4608
	s_waitcnt lgkmcnt(7)
	v_mfma_f32_32x32x16_f16 v[18:33], v[170:173], v[182:185], v[18:33]
	v_mfma_f32_32x32x16_f16 v[2:17], v[178:181], v[182:185], v[2:17]
	s_waitcnt vmcnt(12)
	ds_write_b128 v134, v[78:81] offset:41472
	ds_read_b128 v[170:173], v0 offset:55392
	ds_read_b128 v[174:177], v132 offset:18528
	ds_read_b128 v[178:181], v0 offset:60000
	ds_read_b128 v[182:185], v132 offset:23136
	s_waitcnt lgkmcnt(8)
	v_mfma_f32_32x32x16_f16 v[50:65], v[154:157], v[158:161], v[50:65]
	s_waitcnt lgkmcnt(7)
	v_mfma_f32_32x32x16_f16 v[34:49], v[162:165], v[158:161], v[34:49]
	s_waitcnt vmcnt(11)
	ds_write_b128 v134, v[82:85] offset:9216
	s_waitcnt lgkmcnt(7)
	v_mfma_f32_32x32x16_f16 v[18:33], v[154:157], v[166:169], v[18:33]
	v_mfma_f32_32x32x16_f16 v[2:17], v[162:165], v[166:169], v[2:17]
	s_waitcnt vmcnt(10)
	ds_write_b128 v134, v[86:89] offset:46080
	s_waitcnt lgkmcnt(4)
	v_mfma_f32_32x32x16_f16 v[50:65], v[170:173], v[174:177], v[50:65]
	s_waitcnt lgkmcnt(3)
	v_mfma_f32_32x32x16_f16 v[34:49], v[178:181], v[174:177], v[34:49]
	s_waitcnt vmcnt(9)
	ds_write_b128 v134, v[90:93] offset:13824
	s_waitcnt lgkmcnt(3)
	v_mfma_f32_32x32x16_f16 v[18:33], v[170:173], v[182:185], v[18:33]
	v_mfma_f32_32x32x16_f16 v[2:17], v[178:181], v[182:185], v[2:17]
	s_waitcnt vmcnt(8)
	ds_write_b128 v134, v[94:97] offset:50688
	s_setprio 0
	s_waitcnt lgkmcnt(0)
	s_barrier
; #define GEMM_GLOAD(P, kt_) { GEMM_GL1(P, 0, kt_) GEMM_GL1(P, 1, kt_) GEMM_GL1(P, 2, kt_) GEMM_GL1(P, 3, kt_) }
; #define GEMM_LSTORE(P, buf_) { GEMM_LS1(P, 0, buf_) GEMM_LS1(P, 1, buf_) GEMM_LS1(P, 2, buf_) GEMM_LS1(P, 3, buf_) }
; template <bool DEEP>
; DI void gemm_mainloop_t(const u16* __restrict__ Ag, int lda, const u16* __restrict__ Bg, int ldb, int K, char* ldsraw,
;                         f32x16 (&acc)[2][2], int akstep) {
;     ...
;     for (int kt = 0; kt < nk; kt += 2) {
;       if (kt + 2 < nk) GEMM_GLOAD(x, kt + 2);
;       GEMM_COMPUTE(0);
;       GEMM_LSTORE(y, 1);
;       __syncthreads();
;       if (kt + 3 < nk) GEMM_GLOAD(y, kt + 3);
;       GEMM_COMPUTE(1);
;       if (kt + 2 < nk) GEMM_LSTORE(x, 0);
;       __syncthreads();
	s_setprio 1
	ds_read_b128 v[154:157], v0 offset:36864
	ds_read_b128 v[158:161], v132
	ds_read_b128 v[162:165], v0 offset:41472
	ds_read_b128 v[166:169], v132 offset:4608
	ds_read_b128 v[170:173], v0 offset:36896
	ds_read_b128 v[174:177], v132 offset:32
	ds_read_b128 v[178:181], v0 offset:41504
	ds_read_b128 v[182:185], v132 offset:4640
	s_waitcnt lgkmcnt(6)
	v_mfma_f32_32x32x16_f16 v[50:65], v[154:157], v[158:161], v[50:65]
	s_waitcnt lgkmcnt(5)
	v_mfma_f32_32x32x16_f16 v[34:49], v[162:165], v[158:161], v[34:49]
	s_waitcnt vmcnt(7)
	ds_write_b128 v134, v[98:101] offset:18432
	s_waitcnt lgkmcnt(5)
	v_mfma_f32_32x32x16_f16 v[18:33], v[154:157], v[166:169], v[18:33]
	v_mfma_f32_32x32x16_f16 v[2:17], v[162:165], v[166:169], v[2:17]
	s_waitcnt vmcnt(6)
	ds_write_b128 v134, v[102:105] offset:55296
	ds_read_b128 v[154:157], v0 offset:36928
	ds_read_b128 v[158:161], v132 offset:64
	ds_read_b128 v[162:165], v0 offset:41536
	ds_read_b128 v[166:169], v132 offset:4672
	s_waitcnt lgkmcnt(8)
	v_mfma_f32_32x32x16_f16 v[50:65], v[170:173], v[174:177], v[50:65]
	s_waitcnt lgkmcnt(7)
	v_mfma_f32_32x32x16_f16 v[34:49], v[178:181], v[174:177], v[34:49]
	s_waitcnt vmcnt(5)
	ds_write_b128 v134, v[106:109] offset:23040
	s_waitcnt lgkmcnt(7)
	v_mfma_f32_32x32x16_f16 v[18:33], v[170:173], v[182:185], v[18:33]
	v_mfma_f32_32x32x16_f16 v[2:17], v[178:181], v[182:185], v[2:17]
	s_waitcnt vmcnt(4)
	ds_write_b128 v134, v[110:113] offset:59904
	ds_read_b128 v[170:173], v0 offset:36960
	ds_read_b128 v[174:177], v132 offset:96
	ds_read_b128 v[178:181], v0 offset:41568
	ds_read_b128 v[182:185], v132 offset:4704
	s_waitcnt lgkmcnt(8)
	v_mfma_f32_32x32x16_f16 v[50:65], v[154:157], v[158:161], v[50:65]
	s_waitcnt lgkmcnt(7)
	v_mfma_f32_32x32x16_f16 v[34:49], v[162:165], v[158:161], v[34:49]
	s_waitcnt vmcnt(3)
	ds_write_b128 v134, v[114:117] offset:27648
	s_waitcnt lgkmcnt(7)
	v_mfma_f32_32x32x16_f16 v[18:33], v[154:157], v[166:169], v[18:33]
	v_mfma_f32_32x32x16_f16 v[2:17], v[162:165], v[166:169], v[2:17]
	s_waitcnt vmcnt(2)
	ds_write_b128 v134, v[118:121] offset:64512
	s_waitcnt lgkmcnt(4)
	v_mfma_f32_32x32x16_f16 v[50:65], v[170:173], v[174:177], v[50:65]
	s_waitcnt lgkmcnt(3)
	v_mfma_f32_32x32x16_f16 v[34:49], v[178:181], v[174:177], v[34:49]
	s_waitcnt vmcnt(1)
	ds_write_b128 v134, v[122:125] offset:32256
	s_waitcnt lgkmcnt(3)
	v_mfma_f32_32x32x16_f16 v[18:33], v[170:173], v[182:185], v[18:33]
	v_mfma_f32_32x32x16_f16 v[2:17], v[178:181], v[182:185], v[2:17]
	s_waitcnt vmcnt(0)
	ds_write_b128 v135, v[126:129] offset:64512
	s_setprio 0
	s_waitcnt lgkmcnt(0)
	s_barrier
	s_setprio 1
	ds_read_b128 v[154:157], v0 offset:55296
	ds_read_b128 v[158:161], v132 offset:18432
	ds_read_b128 v[162:165], v0 offset:59904
	ds_read_b128 v[166:169], v132 offset:23040
	ds_read_b128 v[170:173], v0 offset:55328
	ds_read_b128 v[174:177], v132 offset:18464
	ds_read_b128 v[178:181], v0 offset:59936
	ds_read_b128 v[182:185], v132 offset:23072
	s_waitcnt lgkmcnt(6)
	v_mfma_f32_32x32x16_f16 v[50:65], v[154:157], v[158:161], v[50:65]
	s_waitcnt lgkmcnt(5)
	v_mfma_f32_32x32x16_f16 v[34:49], v[162:165], v[158:161], v[34:49]
	s_waitcnt lgkmcnt(4)
	v_mfma_f32_32x32x16_f16 v[18:33], v[154:157], v[166:169], v[18:33]
	v_mfma_f32_32x32x16_f16 v[2:17], v[162:165], v[166:169], v[2:17]
	ds_read_b128 v[154:157], v0 offset:55360
	ds_read_b128 v[158:161], v132 offset:18496
	ds_read_b128 v[162:165], v0 offset:59968
	ds_read_b128 v[166:169], v132 offset:23104
	s_waitcnt lgkmcnt(6)
	v_mfma_f32_32x32x16_f16 v[50:65], v[170:173], v[174:177], v[50:65]
	s_waitcnt lgkmcnt(5)
	v_mfma_f32_32x32x16_f16 v[34:49], v[178:181], v[174:177], v[34:49]
	s_waitcnt lgkmcnt(4)
	v_mfma_f32_32x32x16_f16 v[18:33], v[170:173], v[182:185], v[18:33]
	v_mfma_f32_32x32x16_f16 v[2:17], v[178:181], v[182:185], v[2:17]
	ds_read_b128 v[170:173], v0 offset:55392
	ds_read_b128 v[174:177], v132 offset:18528
	ds_read_b128 v[178:181], v0 offset:60000
	ds_read_b128 v[182:185], v132 offset:23136
	s_waitcnt lgkmcnt(6)
	v_mfma_f32_32x32x16_f16 v[50:65], v[154:157], v[158:161], v[50:65]
	s_waitcnt lgkmcnt(5)
	v_mfma_f32_32x32x16_f16 v[34:49], v[162:165], v[158:161], v[34:49]
	s_waitcnt lgkmcnt(4)
	v_mfma_f32_32x32x16_f16 v[18:33], v[154:157], v[166:169], v[18:33]
	v_mfma_f32_32x32x16_f16 v[2:17], v[162:165], v[166:169], v[2:17]
	s_waitcnt lgkmcnt(2)
	v_mfma_f32_32x32x16_f16 v[50:65], v[170:173], v[174:177], v[50:65]
	s_waitcnt lgkmcnt(1)
	v_mfma_f32_32x32x16_f16 v[34:49], v[178:181], v[174:177], v[34:49]
	s_waitcnt lgkmcnt(0)
	v_mfma_f32_32x32x16_f16 v[18:33], v[170:173], v[182:185], v[18:33]
	v_mfma_f32_32x32x16_f16 v[2:17], v[178:181], v[182:185], v[2:17]
	s_setprio 0
	s_barrier
; DI void phase5(const Params& p, int l, const float* xin, float* xout, char* lds) {
;     ...
; #pragma unroll
;     for (int mi = 0; mi < 2; ++mi) {
;       const size_t row = (size_t)mt * 128 + wm * 64 + mi * 32 + r;
; #pragma unroll
;       for (int ni = 0; ni < 2; ++ni)
; #pragma unroll
;         for (int a = 0; a < 4; ++a) {
;           const int col = nt * 128 + wn * 64 + ni * 32 + 8 * a + 4 * h;
;           float4 xv = *(const float4*)(xin + row * 1024 + col);
;           xv.x += acc[mi][ni][4 * a];
;           xv.y += acc[mi][ni][4 * a + 1];
;           xv.z += acc[mi][ni][4 * a + 2];
;           xv.w += acc[mi][ni][4 * a + 3];
;           *(float4*)(xout + row * 1024 + col) = xv;
;         }
;     }
	v_and_b32_e32 v66, 63, v209
	v_lshrrev_b32_e32 v67, 4, v66
	v_and_b32_e32 v68, 15, v66
	v_lshrrev_b32_e32 v69, 7, v209
	v_lshl_add_u32 v69, v69, 6, v67
	s_lshl_b32 s6, s0, 7
	v_add_u32_e32 v69, s6, v69
	v_lshlrev_b32_e32 v70, 12, v69
	s_lshl_b32 s6, s5, 9
	v_and_b32_e32 v71, 64, v209
	v_lshl_add_u32 v70, v71, 2, v70
	v_lshl_add_u32 v70, v68, 4, v70
	v_add_u32_e32 v72, s6, v70
	v_mov_b32_e32 v73, v72
	v_lshrrev_b32_e32 v74, 6, v209
	v_mul_u32_u24_e32 v76, 0x2400, v74
	v_lshrrev_b32_e32 v74, 1, v74
	v_mul_u32_u24_e32 v74, 0x4800, v74
	v_add_u32_e32 v76, v76, v74
	v_add_u32_e32 v76, 0x4800, v76
	v_and_b32_e32 v75, 31, v66
	v_lshrrev_b32_e32 v74, 5, v66
	v_mul_u32_u24_e32 v75, 0x110, v75
	v_lshl_add_u32 v75, v74, 4, v75
	v_add_u32_e32 v75, v75, v76
	v_mul_u32_u24_e32 v77, 0x110, v67
	v_lshl_add_u32 v77, v68, 4, v77
	v_add_u32_e32 v77, v77, v76
	global_load_dwordx4 v[84:87], v72, s[12:13]
	v_add_u32_e32 v72, 0x4000, v72
	global_load_dwordx4 v[88:91], v72, s[12:13]
	v_add_u32_e32 v72, 0x4000, v72
	global_load_dwordx4 v[92:95], v72, s[12:13]
	v_add_u32_e32 v72, 0x4000, v72
	global_load_dwordx4 v[96:99], v72, s[12:13]
	v_add_u32_e32 v72, 0x4000, v72
	global_load_dwordx4 v[100:103], v72, s[12:13]
	v_add_u32_e32 v72, 0x4000, v72
	global_load_dwordx4 v[104:107], v72, s[12:13]
	v_add_u32_e32 v72, 0x4000, v72
	global_load_dwordx4 v[108:111], v72, s[12:13]
	v_add_u32_e32 v72, 0x4000, v72
	global_load_dwordx4 v[112:115], v72, s[12:13]
	v_add_u32_e32 v72, 0x4000, v72
	ds_write_b128 v75, v[50:53]
	ds_write_b128 v75, v[54:57] offset:32
	ds_write_b128 v75, v[58:61] offset:64
	ds_write_b128 v75, v[62:65] offset:96
	ds_write_b128 v75, v[34:37] offset:128
	ds_write_b128 v75, v[38:41] offset:160
	ds_write_b128 v75, v[42:45] offset:192
	ds_write_b128 v75, v[46:49] offset:224
	s_waitcnt lgkmcnt(0)
	ds_read_b128 v[34:37], v77
	ds_read_b128 v[38:41], v77 offset:1088
	ds_read_b128 v[42:45], v77 offset:2176
	ds_read_b128 v[46:49], v77 offset:3264
	ds_read_b128 v[50:53], v77 offset:4352
	ds_read_b128 v[54:57], v77 offset:5440
	ds_read_b128 v[58:61], v77 offset:6528
	ds_read_b128 v[62:65], v77 offset:7616
	s_waitcnt vmcnt(7) lgkmcnt(7)
	v_pk_add_f32 v[34:35], v[34:35], v[84:85]
	v_pk_add_f32 v[36:37], v[36:37], v[86:87]
	global_store_dwordx4 v73, v[34:37], s[10:11]
	v_add_u32_e32 v73, 0x4000, v73
	s_waitcnt vmcnt(7) lgkmcnt(6)
	v_pk_add_f32 v[38:39], v[38:39], v[88:89]
	v_pk_add_f32 v[40:41], v[40:41], v[90:91]
	global_store_dwordx4 v73, v[38:41], s[10:11]
	v_add_u32_e32 v73, 0x4000, v73
	s_waitcnt vmcnt(7) lgkmcnt(5)
	v_pk_add_f32 v[42:43], v[42:43], v[92:93]
	v_pk_add_f32 v[44:45], v[44:45], v[94:95]
	global_store_dwordx4 v73, v[42:45], s[10:11]
	v_add_u32_e32 v73, 0x4000, v73
	s_waitcnt vmcnt(7) lgkmcnt(4)
	v_pk_add_f32 v[46:47], v[46:47], v[96:97]
	v_pk_add_f32 v[48:49], v[48:49], v[98:99]
	global_store_dwordx4 v73, v[46:49], s[10:11]
	v_add_u32_e32 v73, 0x4000, v73
	s_waitcnt vmcnt(7) lgkmcnt(3)
	v_pk_add_f32 v[50:51], v[50:51], v[100:101]
	v_pk_add_f32 v[52:53], v[52:53], v[102:103]
	global_store_dwordx4 v73, v[50:53], s[10:11]
	v_add_u32_e32 v73, 0x4000, v73
	s_waitcnt vmcnt(7) lgkmcnt(2)
	v_pk_add_f32 v[54:55], v[54:55], v[104:105]
	v_pk_add_f32 v[56:57], v[56:57], v[106:107]
	global_store_dwordx4 v73, v[54:57], s[10:11]
	v_add_u32_e32 v73, 0x4000, v73
	s_waitcnt vmcnt(7) lgkmcnt(1)
	v_pk_add_f32 v[58:59], v[58:59], v[108:109]
	v_pk_add_f32 v[60:61], v[60:61], v[110:111]
	global_store_dwordx4 v73, v[58:61], s[10:11]
	v_add_u32_e32 v73, 0x4000, v73
	s_waitcnt vmcnt(7) lgkmcnt(0)
	v_pk_add_f32 v[62:63], v[62:63], v[112:113]
	v_pk_add_f32 v[64:65], v[64:65], v[114:115]
	global_store_dwordx4 v73, v[62:65], s[10:11]
	v_add_u32_e32 v73, 0x4000, v73
	global_load_dwordx4 v[84:87], v72, s[12:13]
	v_add_u32_e32 v72, 0x4000, v72
	global_load_dwordx4 v[88:91], v72, s[12:13]
	v_add_u32_e32 v72, 0x4000, v72
	global_load_dwordx4 v[92:95], v72, s[12:13]
	v_add_u32_e32 v72, 0x4000, v72
	global_load_dwordx4 v[96:99], v72, s[12:13]
	v_add_u32_e32 v72, 0x4000, v72
	global_load_dwordx4 v[100:103], v72, s[12:13]
	v_add_u32_e32 v72, 0x4000, v72
	global_load_dwordx4 v[104:107], v72, s[12:13]
	v_add_u32_e32 v72, 0x4000, v72
	global_load_dwordx4 v[108:111], v72, s[12:13]
	v_add_u32_e32 v72, 0x4000, v72
	global_load_dwordx4 v[112:115], v72, s[12:13]
	v_add_u32_e32 v72, 0x4000, v72
	ds_write_b128 v75, v[18:21]
	ds_write_b128 v75, v[22:25] offset:32
	ds_write_b128 v75, v[26:29] offset:64
	ds_write_b128 v75, v[30:33] offset:96
	ds_write_b128 v75, v[2:5] offset:128
	ds_write_b128 v75, v[6:9] offset:160
	ds_write_b128 v75, v[10:13] offset:192
	ds_write_b128 v75, v[14:17] offset:224
	s_waitcnt lgkmcnt(0)
	ds_read_b128 v[2:5], v77
	ds_read_b128 v[6:9], v77 offset:1088
	ds_read_b128 v[10:13], v77 offset:2176
	ds_read_b128 v[14:17], v77 offset:3264
	ds_read_b128 v[18:21], v77 offset:4352
	ds_read_b128 v[22:25], v77 offset:5440
	ds_read_b128 v[26:29], v77 offset:6528
	ds_read_b128 v[30:33], v77 offset:7616
	s_waitcnt vmcnt(7) lgkmcnt(7)
	v_pk_add_f32 v[2:3], v[2:3], v[84:85]
	v_pk_add_f32 v[4:5], v[4:5], v[86:87]
	global_store_dwordx4 v73, v[2:5], s[10:11]
	v_add_u32_e32 v73, 0x4000, v73
	s_waitcnt vmcnt(7) lgkmcnt(6)
	v_pk_add_f32 v[6:7], v[6:7], v[88:89]
	v_pk_add_f32 v[8:9], v[8:9], v[90:91]
	global_store_dwordx4 v73, v[6:9], s[10:11]
	v_add_u32_e32 v73, 0x4000, v73
	s_waitcnt vmcnt(7) lgkmcnt(5)
	v_pk_add_f32 v[10:11], v[10:11], v[92:93]
	v_pk_add_f32 v[12:13], v[12:13], v[94:95]
	global_store_dwordx4 v73, v[10:13], s[10:11]
	v_add_u32_e32 v73, 0x4000, v73
	s_waitcnt vmcnt(7) lgkmcnt(4)
	v_pk_add_f32 v[14:15], v[14:15], v[96:97]
	v_pk_add_f32 v[16:17], v[16:17], v[98:99]
	global_store_dwordx4 v73, v[14:17], s[10:11]
	v_add_u32_e32 v73, 0x4000, v73
	s_waitcnt vmcnt(7) lgkmcnt(3)
	v_pk_add_f32 v[18:19], v[18:19], v[100:101]
	v_pk_add_f32 v[20:21], v[20:21], v[102:103]
	global_store_dwordx4 v73, v[18:21], s[10:11]
	v_add_u32_e32 v73, 0x4000, v73
	s_waitcnt vmcnt(7) lgkmcnt(2)
	v_pk_add_f32 v[22:23], v[22:23], v[104:105]
	v_pk_add_f32 v[24:25], v[24:25], v[106:107]
	global_store_dwordx4 v73, v[22:25], s[10:11]
	v_add_u32_e32 v73, 0x4000, v73
	s_waitcnt vmcnt(7) lgkmcnt(1)
	v_pk_add_f32 v[26:27], v[26:27], v[108:109]
	v_pk_add_f32 v[28:29], v[28:29], v[110:111]
	global_store_dwordx4 v73, v[26:29], s[10:11]
	v_add_u32_e32 v73, 0x4000, v73
	s_waitcnt vmcnt(7) lgkmcnt(0)
	v_pk_add_f32 v[30:31], v[30:31], v[112:113]
	v_pk_add_f32 v[32:33], v[32:33], v[114:115]
	global_store_dwordx4 v73, v[30:33], s[10:11]
	v_add_u32_e32 v73, 0x4000, v73
	s_add_i32 s4, s4, s30
	s_cmpk_lt_i32 s4, 0x400
	s_cbranch_scc1 .LBB0_1116
; DI void phase5(const Params& p, int l, const float* xin, float* xout, char* lds) {
;     ...
;   for (int tile = blockIdx.x; tile < 128 * 8; tile += gridDim.x) {
;     const int nt = tile & 7, mt = tile >> 3;
;     f32x16 acc[2][2];
;     zero_acc(acc);
;     gemm_mainloop(p.z + (size_t)mt * 128 * ZS, ZS, WOT(l) + (size_t)nt * 128 * 1024, 1024, 1024, lds, acc);
; #pragma unroll
;     for (int mi = 0; mi < 2; ++mi) {
;       const size_t row = (size_t)mt * 128 + wm * 64 + mi * 32 + r;
; #pragma unroll
;       for (int ni = 0; ni < 2; ++ni)
; #pragma unroll
;         for (int a = 0; a < 4; ++a) {
;           const int col = nt * 128 + wn * 64 + ni * 32 + 8 * a + 4 * h;
;           float4 xv = *(const float4*)(xin + row * 1024 + col);
;           xv.x += acc[mi][ni][4 * a];
;           xv.y += acc[mi][ni][4 * a + 1];
;           xv.z += acc[mi][ni][4 * a + 2];
;           xv.w += acc[mi][ni][4 * a + 3];
;           *(float4*)(xout + row * 1024 + col) = xv;
;         }
;     }
;   }
	v_readlane_b32 s0, v253, 1
	v_readlane_b32 s1, v253, 2
	v_lshlrev_b32_e32 v66, 4, v209
	s_nop 4
	global_load_dwordx4 v[166:169], v66, s[0:1]
	v_add_u32_e32 v66, 0x1000, v66
	global_load_dwordx4 v[170:173], v66, s[0:1]
	v_add_u32_e32 v66, 0x1000, v66
	global_load_dwordx4 v[174:177], v66, s[0:1]
	v_add_u32_e32 v66, 0x1000, v66
	global_load_dwordx4 v[178:181], v66, s[0:1]
	v_add_u32_e32 v66, 0x1000, v66
	global_load_dwordx4 v[182:185], v66, s[0:1]
	v_add_u32_e32 v66, 0x1000, v66
	s_waitcnt vmcnt(0)
	s_mov_b32 s19, s25
